# GEMM K-loops: drop the back-to-back s_setprio 0 / s_setprio 1 pair in the middle of each 32-MFMA block (two issue slots inside an MFMA-paced run)
# speedup vs baseline: 1.0027x; 1.0018x over previous
; #define PG8_STAGE(bufoff, goff, voff) do { _Pragma("unroll") for (int _i = 0; _i < 2; ++_i) \
;         __builtin_amdgcn_raw_ptr_buffer_load_lds(R_##voff, (LAS void*)(lds + (bufoff) + ldsw + _i * 8192), 16, (int)(voff)[_i], (int)(goff), 0, 0); } while (0)
; #define PG8_WAIT_V(n) asm volatile("s_waitcnt vmcnt(" #n ")" ::: "memory")
; #define PG8_WAIT_L(n) asm volatile("s_waitcnt lgkmcnt(" #n ")" ::: "memory")
; #define PG8_BAR __builtin_amdgcn_s_barrier()
; #define PG8_SCHED __builtin_amdgcn_sched_barrier(0)
; template <class Epi, class Sched, bool ALIGN_EPI, bool SP2>
; __device__ __forceinline__ void gemm_phase(LAS unsigned char* lds, const Gemm g, const Sched& S, const Epi& E, int tid_in) {
;     ...
;             PG8_LDB(B0, 0, 0); PG8_LDB(B1, 0, 1); PG8_SCHED; PG8_LDA(At, 0, 0); PG8_STAGE(PG8_SA(1, 1), a1 + hstepA, voffA);
;             PG8_WAIT_V(8); PG8_WAIT_L(0); PG8_BAR; PG8_MMA(0, 0, At, B0); PG8_MMA(0, 1, At, B1); PG8_BAR; PG8_SCHED;
;             PG8_LDA(At, 0, 1); PG8_STAGE(PG8_SB(0, 0), b2, voffB); PG8_STAGE(PG8_SB(0, 1), b2 + hstepB, voffB); PG8_STAGE(PG8_SA(0, 0), a2, voffA);
;             PG8_WAIT_V(8); PG8_WAIT_L(0); PG8_BAR; PG8_MMA(1, 0, At, B0); PG8_MMA(1, 1, At, B1); PG8_BAR; PG8_SCHED;
.LBB0_52:
	v_add_u32_e32 v0, 0x10000, v238
	ds_read_b128 v[128:131], v0
	ds_read_b128 v[140:143], v0 offset:1024
	ds_read_b128 v[144:147], v0 offset:2048
	ds_read_b128 v[148:151], v0 offset:3072
	v_add_u32_e32 v0, 0x14000, v238
	ds_read_b128 v[152:155], v0
	ds_read_b128 v[156:159], v0 offset:1024
	ds_read_b128 v[160:163], v0 offset:2048
	ds_read_b128 v[164:167], v0 offset:3072
	s_add_i32 s14, s30, s66
	s_add_i32 s15, s14, 0x100
	s_add_i32 s42, s31, s66
	s_cmpk_eq_i32 s66, 0x1f00
	s_cselect_b32 s15, s4, s15
	s_cselect_b32 s68, s5, s42
	s_or_b32 s67, s15, 0x80
	s_or_b32 s69, s68, 0x80
	s_add_i32 s14, s14, 0x100080
	s_mov_b32 m0, s54
	ds_read_b128 v[168:171], v239
	ds_read_b128 v[172:175], v239 offset:1024
	ds_read_b128 v[176:179], v239 offset:2048
	ds_read_b128 v[180:183], v239 offset:3072
	ds_read_b128 v[184:187], v239 offset:4096
	ds_read_b128 v[188:191], v239 offset:5120
	ds_read_b128 v[192:195], v239 offset:6144
	ds_read_b128 v[196:199], v239 offset:7168
	buffer_load_dwordx4 v115, s[84:87], s14 offen lds
	s_mov_b32 m0, s56
	s_nop 0
	buffer_load_dwordx4 v229, s[84:87], s14 offen lds
	s_waitcnt vmcnt(8)
	s_waitcnt lgkmcnt(0)
	s_barrier
	s_setprio 1
	s_waitcnt lgkmcnt(7)
	v_mfma_f32_16x16x32_bf16 v[136:139], v[128:131], v[168:171], v[136:139]
	v_mfma_f32_16x16x32_bf16 v[132:135], v[144:147], v[168:171], v[132:135]
	s_waitcnt lgkmcnt(5)
	v_mfma_f32_16x16x32_bf16 v[116:119], v[128:131], v[176:179], v[116:119]
	v_mfma_f32_16x16x32_bf16 v[108:111], v[144:147], v[176:179], v[108:111]
	s_waitcnt lgkmcnt(3)
	v_mfma_f32_16x16x32_bf16 v[96:99], v[128:131], v[184:187], v[96:99]
	v_mfma_f32_16x16x32_bf16 v[92:95], v[144:147], v[184:187], v[92:95]
	s_waitcnt lgkmcnt(1)
	v_mfma_f32_16x16x32_bf16 v[80:83], v[128:131], v[192:195], v[80:83]
	v_mfma_f32_16x16x32_bf16 v[76:79], v[144:147], v[192:195], v[76:79]
	v_mfma_f32_16x16x32_bf16 v[136:139], v[140:143], v[172:175], v[136:139]
	v_mfma_f32_16x16x32_bf16 v[132:135], v[148:151], v[172:175], v[132:135]
	v_mfma_f32_16x16x32_bf16 v[116:119], v[140:143], v[180:183], v[116:119]
	v_mfma_f32_16x16x32_bf16 v[108:111], v[148:151], v[180:183], v[108:111]
	v_mfma_f32_16x16x32_bf16 v[96:99], v[140:143], v[188:191], v[96:99]
	v_mfma_f32_16x16x32_bf16 v[92:95], v[148:151], v[188:191], v[92:95]
	s_waitcnt lgkmcnt(0)
	v_mfma_f32_16x16x32_bf16 v[80:83], v[140:143], v[196:199], v[80:83]
	v_mfma_f32_16x16x32_bf16 v[76:79], v[148:151], v[196:199], v[76:79]
	v_mfma_f32_16x16x32_bf16 v[124:127], v[152:155], v[168:171], v[124:127]
	v_mfma_f32_16x16x32_bf16 v[120:123], v[160:163], v[168:171], v[120:123]
	v_mfma_f32_16x16x32_bf16 v[104:107], v[152:155], v[176:179], v[104:107]
	v_mfma_f32_16x16x32_bf16 v[100:103], v[160:163], v[176:179], v[100:103]
	v_mfma_f32_16x16x32_bf16 v[88:91], v[152:155], v[184:187], v[88:91]
	v_mfma_f32_16x16x32_bf16 v[84:87], v[160:163], v[184:187], v[84:87]
	v_mfma_f32_16x16x32_bf16 v[72:75], v[152:155], v[192:195], v[72:75]
	v_mfma_f32_16x16x32_bf16 v[68:71], v[160:163], v[192:195], v[68:71]
	v_mfma_f32_16x16x32_bf16 v[124:127], v[156:159], v[172:175], v[124:127]
	v_mfma_f32_16x16x32_bf16 v[120:123], v[164:167], v[172:175], v[120:123]
	v_mfma_f32_16x16x32_bf16 v[104:107], v[156:159], v[180:183], v[104:107]
	v_mfma_f32_16x16x32_bf16 v[100:103], v[164:167], v[180:183], v[100:103]
	v_mfma_f32_16x16x32_bf16 v[88:91], v[156:159], v[188:191], v[88:91]
	v_mfma_f32_16x16x32_bf16 v[84:87], v[164:167], v[188:191], v[84:87]
	v_mfma_f32_16x16x32_bf16 v[72:75], v[156:159], v[196:199], v[72:75]
	v_mfma_f32_16x16x32_bf16 v[68:71], v[164:167], v[196:199], v[68:71]
	s_setprio 0
	s_barrier
	s_mov_b32 m0, s7
	s_mov_b32 s42, s86
	s_mov_b32 s43, s87
	ds_read_b128 v[168:171], v239 offset:16384
	ds_read_b128 v[172:175], v239 offset:17408
	ds_read_b128 v[176:179], v239 offset:18432
	ds_read_b128 v[180:183], v239 offset:19456
	ds_read_b128 v[184:187], v239 offset:20480
	ds_read_b128 v[188:191], v239 offset:21504
	ds_read_b128 v[192:195], v239 offset:22528
	ds_read_b128 v[196:199], v239 offset:23552
	buffer_load_dwordx4 v228, s[40:43], s68 offen lds
	s_mov_b32 m0, s9
	s_add_i32 s14, s68, 0x40000
	buffer_load_dwordx4 v230, s[40:43], s68 offen lds
	s_mov_b32 m0, s10
	s_nop 0
	buffer_load_dwordx4 v228, s[40:43], s14 offen lds
	s_mov_b32 m0, s12
	s_nop 0
	buffer_load_dwordx4 v230, s[40:43], s14 offen lds
	s_mov_b32 m0, s6
	s_nop 0
	buffer_load_dwordx4 v115, s[84:87], s15 offen lds
	s_mov_b32 m0, s13
	s_nop 0
	buffer_load_dwordx4 v229, s[84:87], s15 offen lds
	s_waitcnt vmcnt(8)
	s_waitcnt lgkmcnt(0)
	s_barrier
; #define PG8_STAGE(bufoff, goff, voff) do { _Pragma("unroll") for (int _i = 0; _i < 2; ++_i) \
;         __builtin_amdgcn_raw_ptr_buffer_load_lds(R_##voff, (LAS void*)(lds + (bufoff) + ldsw + _i * 8192), 16, (int)(voff)[_i], (int)(goff), 0, 0); } while (0)
; #define PG8_WAIT_V(n) asm volatile("s_waitcnt vmcnt(" #n ")" ::: "memory")
; #define PG8_WAIT_L(n) asm volatile("s_waitcnt lgkmcnt(" #n ")" ::: "memory")
; #define PG8_BAR __builtin_amdgcn_s_barrier()
; #define PG8_SCHED __builtin_amdgcn_sched_barrier(0)
; template <class Epi, class Sched, bool ALIGN_EPI, bool SP2>
; __device__ __forceinline__ void gemm_phase(LAS unsigned char* lds, const Gemm g, const Sched& S, const Epi& E, int tid_in) {
;     ...
;             PG8_WAIT_V(8); PG8_WAIT_L(0); PG8_BAR; PG8_MMA(1, 0, At, B0); PG8_MMA(1, 1, At, B1); PG8_BAR; PG8_SCHED;
;             PG8_LDB(B0, 1, 0); PG8_LDB(B1, 1, 1); PG8_SCHED; PG8_LDA(At, 1, 0); PG8_STAGE(PG8_SA(0, 1), a2 + hstepA, voffA);
;             PG8_WAIT_V(8); PG8_WAIT_L(0); PG8_BAR; PG8_MMA(0, 0, At, B0); PG8_MMA(0, 1, At, B1); PG8_BAR; PG8_SCHED;
	s_setprio 1
	s_waitcnt lgkmcnt(7)
	v_mfma_f32_16x16x32_bf16 v[64:67], v[128:131], v[168:171], v[64:67]
	v_mfma_f32_16x16x32_bf16 v[60:63], v[144:147], v[168:171], v[60:63]
	s_waitcnt lgkmcnt(5)
	v_mfma_f32_16x16x32_bf16 v[48:51], v[128:131], v[176:179], v[48:51]
	v_mfma_f32_16x16x32_bf16 v[44:47], v[144:147], v[176:179], v[44:47]
	s_waitcnt lgkmcnt(3)
	v_mfma_f32_16x16x32_bf16 v[32:35], v[128:131], v[184:187], v[32:35]
	v_mfma_f32_16x16x32_bf16 v[28:31], v[144:147], v[184:187], v[28:31]
	s_waitcnt lgkmcnt(1)
	v_mfma_f32_16x16x32_bf16 v[16:19], v[128:131], v[192:195], v[16:19]
	v_mfma_f32_16x16x32_bf16 v[12:15], v[144:147], v[192:195], v[12:15]
	v_mfma_f32_16x16x32_bf16 v[64:67], v[140:143], v[172:175], v[64:67]
	v_mfma_f32_16x16x32_bf16 v[60:63], v[148:151], v[172:175], v[60:63]
	v_mfma_f32_16x16x32_bf16 v[48:51], v[140:143], v[180:183], v[48:51]
	v_mfma_f32_16x16x32_bf16 v[44:47], v[148:151], v[180:183], v[44:47]
	v_mfma_f32_16x16x32_bf16 v[32:35], v[140:143], v[188:191], v[32:35]
	v_mfma_f32_16x16x32_bf16 v[28:31], v[148:151], v[188:191], v[28:31]
	s_waitcnt lgkmcnt(0)
	v_mfma_f32_16x16x32_bf16 v[16:19], v[140:143], v[196:199], v[16:19]
	v_mfma_f32_16x16x32_bf16 v[12:15], v[148:151], v[196:199], v[12:15]
	v_mfma_f32_16x16x32_bf16 v[56:59], v[152:155], v[168:171], v[56:59]
	v_mfma_f32_16x16x32_bf16 v[52:55], v[160:163], v[168:171], v[52:55]
	v_mfma_f32_16x16x32_bf16 v[40:43], v[152:155], v[176:179], v[40:43]
	v_mfma_f32_16x16x32_bf16 v[36:39], v[160:163], v[176:179], v[36:39]
	v_mfma_f32_16x16x32_bf16 v[24:27], v[152:155], v[184:187], v[24:27]
	v_mfma_f32_16x16x32_bf16 v[20:23], v[160:163], v[184:187], v[20:23]
	v_mfma_f32_16x16x32_bf16 v[8:11], v[152:155], v[192:195], v[8:11]
	v_mfma_f32_16x16x32_bf16 v[2:5], v[160:163], v[192:195], v[4:7]
	v_mfma_f32_16x16x32_bf16 v[56:59], v[156:159], v[172:175], v[56:59]
	v_mfma_f32_16x16x32_bf16 v[52:55], v[164:167], v[172:175], v[52:55]
	v_mfma_f32_16x16x32_bf16 v[40:43], v[156:159], v[180:183], v[40:43]
	v_mfma_f32_16x16x32_bf16 v[36:39], v[164:167], v[180:183], v[36:39]
	v_mfma_f32_16x16x32_bf16 v[24:27], v[156:159], v[188:191], v[24:27]
	v_mfma_f32_16x16x32_bf16 v[20:23], v[164:167], v[188:191], v[20:23]
	v_mfma_f32_16x16x32_bf16 v[8:11], v[156:159], v[196:199], v[8:11]
	v_mfma_f32_16x16x32_bf16 v[2:5], v[164:167], v[196:199], v[2:5]
	s_setprio 0
	s_barrier
	v_add_u32_e32 v0, 0x18000, v238
	ds_read_b128 v[128:131], v0
	ds_read_b128 v[140:143], v0 offset:1024
	ds_read_b128 v[144:147], v0 offset:2048
	ds_read_b128 v[148:151], v0 offset:3072
	v_add_u32_e32 v0, 0x1c000, v238
	ds_read_b128 v[152:155], v0
	ds_read_b128 v[156:159], v0 offset:1024
	ds_read_b128 v[160:163], v0 offset:2048
	ds_read_b128 v[164:167], v0 offset:3072
	s_add_i32 s15, s15, 0x100000
	s_mov_b32 m0, s16
	ds_read_b128 v[168:171], v239 offset:32768
	ds_read_b128 v[172:175], v239 offset:33792
	ds_read_b128 v[176:179], v239 offset:34816
	ds_read_b128 v[180:183], v239 offset:35840
	ds_read_b128 v[184:187], v239 offset:36864
	ds_read_b128 v[188:191], v239 offset:37888
	ds_read_b128 v[192:195], v239 offset:38912
	ds_read_b128 v[196:199], v239 offset:39936
	buffer_load_dwordx4 v115, s[84:87], s15 offen lds
	s_mov_b32 m0, s17
	s_nop 0
	buffer_load_dwordx4 v229, s[84:87], s15 offen lds
	s_waitcnt vmcnt(8)
	s_waitcnt lgkmcnt(0)
	s_barrier
	s_setprio 1
	s_waitcnt lgkmcnt(7)
	v_mfma_f32_16x16x32_bf16 v[136:139], v[128:131], v[168:171], v[136:139]
	v_mfma_f32_16x16x32_bf16 v[132:135], v[144:147], v[168:171], v[132:135]
	s_waitcnt lgkmcnt(5)
	v_mfma_f32_16x16x32_bf16 v[116:119], v[128:131], v[176:179], v[116:119]
	v_mfma_f32_16x16x32_bf16 v[108:111], v[144:147], v[176:179], v[108:111]
	s_waitcnt lgkmcnt(3)
	v_mfma_f32_16x16x32_bf16 v[96:99], v[128:131], v[184:187], v[96:99]
	v_mfma_f32_16x16x32_bf16 v[92:95], v[144:147], v[184:187], v[92:95]
	s_waitcnt lgkmcnt(1)
	v_mfma_f32_16x16x32_bf16 v[80:83], v[128:131], v[192:195], v[80:83]
	v_mfma_f32_16x16x32_bf16 v[76:79], v[144:147], v[192:195], v[76:79]
	v_mfma_f32_16x16x32_bf16 v[136:139], v[140:143], v[172:175], v[136:139]
	v_mfma_f32_16x16x32_bf16 v[132:135], v[148:151], v[172:175], v[132:135]
	v_mfma_f32_16x16x32_bf16 v[116:119], v[140:143], v[180:183], v[116:119]
	v_mfma_f32_16x16x32_bf16 v[108:111], v[148:151], v[180:183], v[108:111]
	v_mfma_f32_16x16x32_bf16 v[96:99], v[140:143], v[188:191], v[96:99]
	v_mfma_f32_16x16x32_bf16 v[92:95], v[148:151], v[188:191], v[92:95]
	s_waitcnt lgkmcnt(0)
	v_mfma_f32_16x16x32_bf16 v[80:83], v[140:143], v[196:199], v[80:83]
	v_mfma_f32_16x16x32_bf16 v[76:79], v[148:151], v[196:199], v[76:79]
	v_mfma_f32_16x16x32_bf16 v[124:127], v[152:155], v[168:171], v[124:127]
	v_mfma_f32_16x16x32_bf16 v[120:123], v[160:163], v[168:171], v[120:123]
	v_mfma_f32_16x16x32_bf16 v[104:107], v[152:155], v[176:179], v[104:107]
	v_mfma_f32_16x16x32_bf16 v[100:103], v[160:163], v[176:179], v[100:103]
	v_mfma_f32_16x16x32_bf16 v[88:91], v[152:155], v[184:187], v[88:91]
	v_mfma_f32_16x16x32_bf16 v[84:87], v[160:163], v[184:187], v[84:87]
	v_mfma_f32_16x16x32_bf16 v[72:75], v[152:155], v[192:195], v[72:75]
	v_mfma_f32_16x16x32_bf16 v[68:71], v[160:163], v[192:195], v[68:71]
	v_mfma_f32_16x16x32_bf16 v[124:127], v[156:159], v[172:175], v[124:127]
	v_mfma_f32_16x16x32_bf16 v[120:123], v[164:167], v[172:175], v[120:123]
	v_mfma_f32_16x16x32_bf16 v[104:107], v[156:159], v[180:183], v[104:107]
	v_mfma_f32_16x16x32_bf16 v[100:103], v[164:167], v[180:183], v[100:103]
	v_mfma_f32_16x16x32_bf16 v[88:91], v[156:159], v[188:191], v[88:91]
	v_mfma_f32_16x16x32_bf16 v[84:87], v[164:167], v[188:191], v[84:87]
	v_mfma_f32_16x16x32_bf16 v[72:75], v[156:159], v[196:199], v[72:75]
	v_mfma_f32_16x16x32_bf16 v[68:71], v[164:167], v[196:199], v[68:71]
	s_setprio 0
	s_barrier
; #define PG8_STAGE(bufoff, goff, voff) do { _Pragma("unroll") for (int _i = 0; _i < 2; ++_i) \
;         __builtin_amdgcn_raw_ptr_buffer_load_lds(R_##voff, (LAS void*)(lds + (bufoff) + ldsw + _i * 8192), 16, (int)(voff)[_i], (int)(goff), 0, 0); } while (0)
; #define PG8_WAIT_V(n) asm volatile("s_waitcnt vmcnt(" #n ")" ::: "memory")
; #define PG8_WAIT_L(n) asm volatile("s_waitcnt lgkmcnt(" #n ")" ::: "memory")
; #define PG8_BAR __builtin_amdgcn_s_barrier()
; #define PG8_SCHED __builtin_amdgcn_sched_barrier(0)
; template <class Epi, class Sched, bool ALIGN_EPI, bool SP2>
; __device__ __forceinline__ void gemm_phase(LAS unsigned char* lds, const Gemm g, const Sched& S, const Epi& E, int tid_in) {
;     ...
;             PG8_LDA(At, 1, 1); PG8_STAGE(PG8_SB(1, 0), b3, voffB); PG8_STAGE(PG8_SB(1, 1), b3 + hstepB, voffB); PG8_STAGE(PG8_SA(1, 0), a3, voffA);
;             PG8_WAIT_V(8); PG8_WAIT_L(0); PG8_BAR; PG8_MMA(1, 0, At, B0); PG8_MMA(1, 1, At, B1); PG8_BAR; PG8_SCHED;
	s_mov_b32 m0, s19
	ds_read_b128 v[168:171], v239 offset:49152
	ds_read_b128 v[172:175], v239 offset:50176
	ds_read_b128 v[176:179], v239 offset:51200
	ds_read_b128 v[180:183], v239 offset:52224
	ds_read_b128 v[184:187], v239 offset:53248
	ds_read_b128 v[188:191], v239 offset:54272
	ds_read_b128 v[192:195], v239 offset:55296
	ds_read_b128 v[196:199], v239 offset:56320
	buffer_load_dwordx4 v228, s[40:43], s69 offen lds
	s_mov_b32 m0, s25
	s_add_i32 s68, s68, 0x40080
	buffer_load_dwordx4 v230, s[40:43], s69 offen lds
	s_mov_b32 m0, s34
	s_nop 0
	buffer_load_dwordx4 v228, s[40:43], s68 offen lds
	s_mov_b32 m0, s49
	s_nop 0
	buffer_load_dwordx4 v230, s[40:43], s68 offen lds
	s_mov_b32 m0, s27
	s_nop 0
	buffer_load_dwordx4 v115, s[84:87], s67 offen lds
	s_mov_b32 m0, s29
	s_nop 0
	buffer_load_dwordx4 v229, s[84:87], s67 offen lds
	s_waitcnt vmcnt(8)
	s_waitcnt lgkmcnt(0)
	s_barrier
	s_setprio 1
	s_waitcnt lgkmcnt(7)
	v_mfma_f32_16x16x32_bf16 v[64:67], v[128:131], v[168:171], v[64:67]
	v_mfma_f32_16x16x32_bf16 v[60:63], v[144:147], v[168:171], v[60:63]
	s_waitcnt lgkmcnt(5)
	v_mfma_f32_16x16x32_bf16 v[48:51], v[128:131], v[176:179], v[48:51]
	v_mfma_f32_16x16x32_bf16 v[44:47], v[144:147], v[176:179], v[44:47]
	s_waitcnt lgkmcnt(3)
	v_mfma_f32_16x16x32_bf16 v[32:35], v[128:131], v[184:187], v[32:35]
	v_mfma_f32_16x16x32_bf16 v[28:31], v[144:147], v[184:187], v[28:31]
	s_waitcnt lgkmcnt(1)
	v_mfma_f32_16x16x32_bf16 v[16:19], v[128:131], v[192:195], v[16:19]
	v_mfma_f32_16x16x32_bf16 v[12:15], v[144:147], v[192:195], v[12:15]
	v_mfma_f32_16x16x32_bf16 v[64:67], v[140:143], v[172:175], v[64:67]
	v_mfma_f32_16x16x32_bf16 v[60:63], v[148:151], v[172:175], v[60:63]
	v_mfma_f32_16x16x32_bf16 v[48:51], v[140:143], v[180:183], v[48:51]
	v_mfma_f32_16x16x32_bf16 v[44:47], v[148:151], v[180:183], v[44:47]
	v_mfma_f32_16x16x32_bf16 v[32:35], v[140:143], v[188:191], v[32:35]
	v_mfma_f32_16x16x32_bf16 v[28:31], v[148:151], v[188:191], v[28:31]
	s_waitcnt lgkmcnt(0)
	v_mfma_f32_16x16x32_bf16 v[16:19], v[140:143], v[196:199], v[16:19]
	v_mfma_f32_16x16x32_bf16 v[12:15], v[148:151], v[196:199], v[12:15]
	v_mfma_f32_16x16x32_bf16 v[56:59], v[152:155], v[168:171], v[56:59]
	v_mfma_f32_16x16x32_bf16 v[52:55], v[160:163], v[168:171], v[52:55]
	v_mfma_f32_16x16x32_bf16 v[40:43], v[152:155], v[176:179], v[40:43]
	v_mfma_f32_16x16x32_bf16 v[36:39], v[160:163], v[176:179], v[36:39]
	v_mfma_f32_16x16x32_bf16 v[24:27], v[152:155], v[184:187], v[24:27]
	v_mfma_f32_16x16x32_bf16 v[20:23], v[160:163], v[184:187], v[20:23]
	v_mfma_f32_16x16x32_bf16 v[6:9], v[152:155], v[192:195], v[8:11]
	v_mfma_f32_16x16x32_bf16 v[2:5], v[160:163], v[192:195], v[2:5]
	v_mfma_f32_16x16x32_bf16 v[56:59], v[156:159], v[172:175], v[56:59]
	v_mfma_f32_16x16x32_bf16 v[52:55], v[164:167], v[172:175], v[52:55]
	v_mfma_f32_16x16x32_bf16 v[40:43], v[156:159], v[180:183], v[40:43]
	v_mfma_f32_16x16x32_bf16 v[36:39], v[164:167], v[180:183], v[36:39]
	v_mfma_f32_16x16x32_bf16 v[24:27], v[156:159], v[188:191], v[24:27]
	v_mfma_f32_16x16x32_bf16 v[20:23], v[164:167], v[188:191], v[20:23]
	v_mfma_f32_16x16x32_bf16 v[8:11], v[156:159], v[196:199], v[6:9]
	v_mfma_f32_16x16x32_bf16 v[4:7], v[164:167], v[196:199], v[2:5]
	s_setprio 0
	s_barrier
	s_add_i32 s65, s65, 2
	s_addk_i32 s66, 0x100
	s_cmp_gt_u32 s65, 61
	s_cbranch_scc1 .LBB0_55

; #define PG8_STAGE(bufoff, goff, voff) do { _Pragma("unroll") for (int _i = 0; _i < 2; ++_i) \
;         __builtin_amdgcn_raw_ptr_buffer_load_lds(R_##voff, (LAS void*)(lds + (bufoff) + ldsw + _i * 8192), 16, (int)(voff)[_i], (int)(goff), 0, 0); } while (0)
; #define PG8_WAIT_V(n) asm volatile("s_waitcnt vmcnt(" #n ")" ::: "memory")
; #define PG8_WAIT_L(n) asm volatile("s_waitcnt lgkmcnt(" #n ")" ::: "memory")
; #define PG8_BAR __builtin_amdgcn_s_barrier()
; #define PG8_SCHED __builtin_amdgcn_sched_barrier(0)
; template <class Epi, class Sched, bool ALIGN_EPI, bool SP2>
; __device__ __forceinline__ void gemm_phase(LAS unsigned char* lds, const Gemm g, const Sched& S, const Epi& E, int tid_in) {
;     ...
;             PG8_LDB(B0, 0, 0); PG8_LDB(B1, 0, 1); PG8_SCHED; PG8_LDA(At, 0, 0); PG8_STAGE(PG8_SA(1, 1), a1 + hstepA, voffA);
;             PG8_WAIT_V(8); PG8_WAIT_L(0); PG8_BAR; PG8_MMA(0, 0, At, B0); PG8_MMA(0, 1, At, B1); PG8_BAR; PG8_SCHED;
;             PG8_LDA(At, 0, 1); PG8_STAGE(PG8_SB(0, 0), b2, voffB); PG8_STAGE(PG8_SB(0, 1), b2 + hstepB, voffB); PG8_STAGE(PG8_SA(0, 0), a2, voffA);
;             PG8_WAIT_V(8); PG8_WAIT_L(0); PG8_BAR; PG8_MMA(1, 0, At, B0); PG8_MMA(1, 1, At, B1); PG8_BAR; PG8_SCHED;
.LBB0_98:
	v_add_u32_e32 v70, 0x10000, v241
	v_add_u32_e32 v152, 0x14000, v241
	ds_read_b128 v[50:53], v70
	ds_read_b128 v[54:57], v70 offset:1024
	ds_read_b128 v[66:69], v70 offset:2048
	ds_read_b128 v[70:73], v70 offset:3072
	ds_read_b128 v[132:135], v152
	ds_read_b128 v[136:139], v152 offset:1024
	ds_read_b128 v[148:151], v152 offset:2048
	ds_read_b128 v[152:155], v152 offset:3072
	s_add_i32 s14, s16, 0xfffc0080
	s_cmp_eq_u32 s19, 12
	s_cselect_b32 s27, s2, s14
	s_cselect_b32 s25, s3, s17
	s_or_b32 s20, s27, 0x80
	s_mov_b32 m0, s71
	ds_read_b128 v[156:159], v242
	ds_read_b128 v[160:163], v242 offset:1024
	ds_read_b128 v[164:167], v242 offset:2048
	ds_read_b128 v[168:171], v242 offset:3072
	ds_read_b128 v[180:183], v242 offset:4096
	ds_read_b128 v[184:187], v242 offset:5120
	ds_read_b128 v[188:191], v242 offset:6144
	ds_read_b128 v[192:195], v242 offset:7168
	buffer_load_dwordx4 v0, s[84:87], s16 offen lds
	s_mov_b32 m0, s73
	s_nop 0
	buffer_load_dwordx4 v237, s[84:87], s16 offen lds
	s_waitcnt vmcnt(8)
	s_waitcnt lgkmcnt(0)
	s_barrier
	s_setprio 1
	s_waitcnt lgkmcnt(6)
	v_mfma_f32_16x16x128_f8f6f4 v[176:179], v[50:57], v[156:163], v[176:179]
	v_mfma_f32_16x16x128_f8f6f4 v[172:175], v[66:73], v[156:163], v[172:175]
	s_waitcnt lgkmcnt(4)
	v_mfma_f32_16x16x128_f8f6f4 v[128:131], v[50:57], v[164:171], v[128:131]
	v_mfma_f32_16x16x128_f8f6f4 v[124:127], v[66:73], v[164:171], v[124:127]
	s_waitcnt lgkmcnt(2)
	v_mfma_f32_16x16x128_f8f6f4 v[196:199], v[50:57], v[180:187], v[110:113]
	v_mfma_f32_16x16x128_f8f6f4 v[200:203], v[66:73], v[180:187], v[106:109]
	s_waitcnt lgkmcnt(0)
	v_mfma_f32_16x16x128_f8f6f4 v[204:207], v[50:57], v[188:195], v[94:97]
	v_mfma_f32_16x16x128_f8f6f4 v[208:211], v[66:73], v[188:195], v[90:93]
	v_mfma_f32_16x16x128_f8f6f4 v[144:147], v[132:139], v[156:163], v[144:147]
	v_mfma_f32_16x16x128_f8f6f4 v[140:143], v[148:155], v[156:163], v[140:143]
	v_mfma_f32_16x16x128_f8f6f4 v[120:123], v[132:139], v[164:171], v[120:123]
	v_mfma_f32_16x16x128_f8f6f4 v[116:119], v[148:155], v[164:171], v[116:119]
	v_mfma_f32_16x16x128_f8f6f4 v[156:159], v[132:139], v[180:187], v[102:105]
	v_mfma_f32_16x16x128_f8f6f4 v[160:163], v[148:155], v[180:187], v[98:101]
	v_mfma_f32_16x16x128_f8f6f4 v[164:167], v[132:139], v[188:195], v[86:89]
	v_mfma_f32_16x16x128_f8f6f4 v[168:171], v[148:155], v[188:195], v[82:85]
	s_setprio 0
	s_barrier
	s_mov_b32 m0, s12
	s_mov_b32 s42, s86
	s_mov_b32 s43, s87
	s_nop 1
	ds_read_b128 v[82:85], v242 offset:16384
	ds_read_b128 v[86:89], v242 offset:17408
	ds_read_b128 v[90:93], v242 offset:18432
	ds_read_b128 v[94:97], v242 offset:19456
	ds_read_b128 v[98:101], v242 offset:20480
	ds_read_b128 v[102:105], v242 offset:21504
	ds_read_b128 v[106:109], v242 offset:22528
	ds_read_b128 v[110:113], v242 offset:23552
	buffer_load_dwordx4 v115, s[40:43], s25 offen lds
	s_mov_b32 m0, s13
	s_add_i32 s14, s25, 0x10000
	buffer_load_dwordx4 v238, s[40:43], s25 offen lds
	s_mov_b32 m0, s53
	s_nop 0
	buffer_load_dwordx4 v115, s[40:43], s14 offen lds
	s_mov_b32 m0, s58
	s_nop 0
	buffer_load_dwordx4 v238, s[40:43], s14 offen lds
	s_mov_b32 m0, s9
	s_nop 0
	buffer_load_dwordx4 v0, s[84:87], s27 offen lds
	s_mov_b32 m0, s59
	s_nop 0
	buffer_load_dwordx4 v237, s[84:87], s27 offen lds
	s_waitcnt vmcnt(8)
	s_waitcnt lgkmcnt(0)
	s_barrier
	s_setprio 1
	s_waitcnt lgkmcnt(6)
	v_mfma_f32_16x16x128_f8f6f4 v[78:81], v[50:57], v[82:89], v[78:81]
	v_mfma_f32_16x16x128_f8f6f4 v[74:77], v[66:73], v[82:89], v[74:77]
	s_waitcnt lgkmcnt(4)
	v_mfma_f32_16x16x128_f8f6f4 v[180:183], v[50:57], v[90:97], v[46:49]
	v_mfma_f32_16x16x128_f8f6f4 v[184:187], v[66:73], v[90:97], v[42:45]
	s_waitcnt lgkmcnt(2)
	v_mfma_f32_16x16x128_f8f6f4 v[188:191], v[50:57], v[98:105], v[30:33]
	v_mfma_f32_16x16x128_f8f6f4 v[192:195], v[66:73], v[98:105], v[26:29]
	s_waitcnt lgkmcnt(0)
	v_mfma_f32_16x16x128_f8f6f4 v[212:215], v[50:57], v[106:113], v[14:17]
	v_mfma_f32_16x16x128_f8f6f4 v[216:219], v[66:73], v[106:113], v[10:13]
	v_mfma_f32_16x16x128_f8f6f4 v[62:65], v[132:139], v[82:89], v[62:65]
	v_mfma_f32_16x16x128_f8f6f4 v[58:61], v[148:155], v[82:89], v[58:61]
	v_mfma_f32_16x16x128_f8f6f4 v[220:223], v[132:139], v[90:97], v[38:41]
	v_mfma_f32_16x16x128_f8f6f4 v[224:227], v[148:155], v[90:97], v[34:37]
	v_mfma_f32_16x16x128_f8f6f4 v[228:231], v[132:139], v[98:105], v[22:25]
	v_mfma_f32_16x16x128_f8f6f4 v[244:247], v[148:155], v[98:105], v[18:21]
	v_mfma_f32_16x16x128_f8f6f4 v[248:251], v[132:139], v[106:113], v[6:9]
	v_mfma_f32_16x16x128_f8f6f4 v[232:235], v[148:155], v[106:113], v[2:5]
	s_setprio 0
	s_barrier
; #define PG8_STAGE(bufoff, goff, voff) do { _Pragma("unroll") for (int _i = 0; _i < 2; ++_i) \
;         __builtin_amdgcn_raw_ptr_buffer_load_lds(R_##voff, (LAS void*)(lds + (bufoff) + ldsw + _i * 8192), 16, (int)(voff)[_i], (int)(goff), 0, 0); } while (0)
; #define PG8_WAIT_V(n) asm volatile("s_waitcnt vmcnt(" #n ")" ::: "memory")
; #define PG8_WAIT_L(n) asm volatile("s_waitcnt lgkmcnt(" #n ")" ::: "memory")
; #define PG8_BAR __builtin_amdgcn_s_barrier()
; #define PG8_SCHED __builtin_amdgcn_sched_barrier(0)
; template <class Epi, class Sched, bool ALIGN_EPI, bool SP2>
; __device__ __forceinline__ void gemm_phase(LAS unsigned char* lds, const Gemm g, const Sched& S, const Epi& E, int tid_in) {
;     ...
;             PG8_LDB(B0, 1, 0); PG8_LDB(B1, 1, 1); PG8_SCHED; PG8_LDA(At, 1, 0); PG8_STAGE(PG8_SA(0, 1), a2 + hstepA, voffA);
;             PG8_WAIT_V(8); PG8_WAIT_L(0); PG8_BAR; PG8_MMA(0, 0, At, B0); PG8_MMA(0, 1, At, B1); PG8_BAR; PG8_SCHED;
;             PG8_LDA(At, 1, 1); PG8_STAGE(PG8_SB(1, 0), b3, voffB); PG8_STAGE(PG8_SB(1, 1), b3 + hstepB, voffB); PG8_STAGE(PG8_SA(1, 0), a3, voffA);
;             PG8_WAIT_V(8); PG8_WAIT_L(0); PG8_BAR; PG8_MMA(1, 0, At, B0); PG8_MMA(1, 1, At, B1); PG8_BAR; PG8_SCHED;
	v_add_u32_e32 v10, 0x18000, v241
	s_nop 3
	ds_read_b128 v[2:5], v10
	ds_read_b128 v[6:9], v10 offset:1024
	ds_read_b128 v[18:21], v10 offset:2048
	ds_read_b128 v[22:25], v10 offset:3072
	v_add_u32_e32 v10, 0x1c000, v241
	ds_read_b128 v[50:53], v10
	ds_read_b128 v[54:57], v10 offset:1024
	ds_read_b128 v[66:69], v10 offset:2048
	ds_read_b128 v[70:73], v10 offset:3072
	s_add_i32 s27, s27, 0x40000
	s_mov_b32 m0, s60
	ds_read_b128 v[10:13], v242 offset:32768
	ds_read_b128 v[14:17], v242 offset:33792
	ds_read_b128 v[26:29], v242 offset:34816
	ds_read_b128 v[30:33], v242 offset:35840
	ds_read_b128 v[34:37], v242 offset:36864
	ds_read_b128 v[38:41], v242 offset:37888
	ds_read_b128 v[42:45], v242 offset:38912
	ds_read_b128 v[46:49], v242 offset:39936
	buffer_load_dwordx4 v0, s[84:87], s27 offen lds
	s_mov_b32 m0, s61
	s_nop 0
	buffer_load_dwordx4 v237, s[84:87], s27 offen lds
	s_waitcnt vmcnt(8)
	s_waitcnt lgkmcnt(0)
	s_barrier
	s_setprio 1
	s_waitcnt lgkmcnt(6)
	v_mfma_f32_16x16x128_f8f6f4 v[176:179], v[2:9], v[10:17], v[176:179]
	v_mfma_f32_16x16x128_f8f6f4 v[172:175], v[18:25], v[10:17], v[172:175]
	s_waitcnt lgkmcnt(4)
	v_mfma_f32_16x16x128_f8f6f4 v[128:131], v[2:9], v[26:33], v[128:131]
	v_mfma_f32_16x16x128_f8f6f4 v[124:127], v[18:25], v[26:33], v[124:127]
	s_waitcnt lgkmcnt(2)
	v_mfma_f32_16x16x128_f8f6f4 v[110:113], v[2:9], v[34:41], v[196:199]
	v_mfma_f32_16x16x128_f8f6f4 v[106:109], v[18:25], v[34:41], v[200:203]
	s_waitcnt lgkmcnt(0)
	v_mfma_f32_16x16x128_f8f6f4 v[94:97], v[2:9], v[42:49], v[204:207]
	v_mfma_f32_16x16x128_f8f6f4 v[90:93], v[18:25], v[42:49], v[208:211]
	v_mfma_f32_16x16x128_f8f6f4 v[144:147], v[50:57], v[10:17], v[144:147]
	v_mfma_f32_16x16x128_f8f6f4 v[140:143], v[66:73], v[10:17], v[140:143]
	v_mfma_f32_16x16x128_f8f6f4 v[120:123], v[50:57], v[26:33], v[120:123]
	v_mfma_f32_16x16x128_f8f6f4 v[116:119], v[66:73], v[26:33], v[116:119]
	v_mfma_f32_16x16x128_f8f6f4 v[102:105], v[50:57], v[34:41], v[156:159]
	v_mfma_f32_16x16x128_f8f6f4 v[98:101], v[66:73], v[34:41], v[160:163]
	v_mfma_f32_16x16x128_f8f6f4 v[86:89], v[50:57], v[42:49], v[164:167]
	v_mfma_f32_16x16x128_f8f6f4 v[82:85], v[66:73], v[42:49], v[168:171]
	s_setprio 0
	s_barrier
	s_mov_b32 m0, s49
	s_or_b32 s14, s25, 0x80
	ds_read_b128 v[34:37], v242 offset:49152
	ds_read_b128 v[38:41], v242 offset:50176
	ds_read_b128 v[132:135], v242 offset:51200
	ds_read_b128 v[136:139], v242 offset:52224
	ds_read_b128 v[148:151], v242 offset:53248
	ds_read_b128 v[152:155], v242 offset:54272
	ds_read_b128 v[156:159], v242 offset:55296
	ds_read_b128 v[160:163], v242 offset:56320
	buffer_load_dwordx4 v115, s[40:43], s14 offen lds
	s_mov_b32 m0, s31
	s_add_i32 s25, s25, 0x10080
	buffer_load_dwordx4 v238, s[40:43], s14 offen lds
	s_mov_b32 m0, s67
	s_nop 0
	buffer_load_dwordx4 v115, s[40:43], s25 offen lds
	s_mov_b32 m0, s68
	s_nop 0
	buffer_load_dwordx4 v238, s[40:43], s25 offen lds
	s_mov_b32 m0, s30
	s_nop 0
	buffer_load_dwordx4 v0, s[84:87], s20 offen lds
	s_mov_b32 m0, s66
	s_nop 0
	buffer_load_dwordx4 v237, s[84:87], s20 offen lds
	s_waitcnt vmcnt(8)
	s_waitcnt lgkmcnt(0)
	s_barrier
	s_setprio 1
	s_waitcnt lgkmcnt(6)
	v_mfma_f32_16x16x128_f8f6f4 v[78:81], v[2:9], v[34:41], v[78:81]
	v_mfma_f32_16x16x128_f8f6f4 v[74:77], v[18:25], v[34:41], v[74:77]
	s_waitcnt lgkmcnt(4)
	v_mfma_f32_16x16x128_f8f6f4 v[46:49], v[2:9], v[132:139], v[180:183]
	v_mfma_f32_16x16x128_f8f6f4 v[42:45], v[18:25], v[132:139], v[184:187]
	s_waitcnt lgkmcnt(2)
	v_mfma_f32_16x16x128_f8f6f4 v[30:33], v[2:9], v[148:155], v[188:191]
	v_mfma_f32_16x16x128_f8f6f4 v[26:29], v[18:25], v[148:155], v[192:195]
	s_waitcnt lgkmcnt(0)
	v_mfma_f32_16x16x128_f8f6f4 v[14:17], v[2:9], v[156:163], v[212:215]
	v_mfma_f32_16x16x128_f8f6f4 v[10:13], v[18:25], v[156:163], v[216:219]
	v_mfma_f32_16x16x128_f8f6f4 v[62:65], v[50:57], v[34:41], v[62:65]
	v_mfma_f32_16x16x128_f8f6f4 v[58:61], v[66:73], v[34:41], v[58:61]
	v_mfma_f32_16x16x128_f8f6f4 v[38:41], v[50:57], v[132:139], v[220:223]
	v_mfma_f32_16x16x128_f8f6f4 v[34:37], v[66:73], v[132:139], v[224:227]
	v_mfma_f32_16x16x128_f8f6f4 v[22:25], v[50:57], v[148:155], v[228:231]
	v_mfma_f32_16x16x128_f8f6f4 v[18:21], v[66:73], v[148:155], v[244:247]
	v_mfma_f32_16x16x128_f8f6f4 v[6:9], v[50:57], v[156:163], v[248:251]
	v_mfma_f32_16x16x128_f8f6f4 v[2:5], v[66:73], v[156:163], v[232:235]
	s_setprio 0
	s_barrier
	s_add_i32 s19, s19, 2
	s_addk_i32 s16, 0x100
	s_addk_i32 s17, 0x100
	s_cmp_gt_u32 s19, 13
	s_cbranch_scc0 .LBB0_98
	s_and_b64 vcc, exec, s[56:57]
	s_cbranch_vccz .LBB0_101
	s_barrier

; #define PG8_STAGE(bufoff, goff, voff) do { _Pragma("unroll") for (int _i = 0; _i < 2; ++_i) \
;         __builtin_amdgcn_raw_ptr_buffer_load_lds(R_##voff, (LAS void*)(lds + (bufoff) + ldsw + _i * 8192), 16, (int)(voff)[_i], (int)(goff), 0, 0); } while (0)
; #define PG8_WAIT_V(n) asm volatile("s_waitcnt vmcnt(" #n ")" ::: "memory")
; #define PG8_WAIT_L(n) asm volatile("s_waitcnt lgkmcnt(" #n ")" ::: "memory")
; #define PG8_BAR __builtin_amdgcn_s_barrier()
; #define PG8_SCHED __builtin_amdgcn_sched_barrier(0)
; template <class Epi, class Sched, bool ALIGN_EPI, bool SP2>
; __device__ __forceinline__ void gemm_phase(LAS unsigned char* lds, const Gemm g, const Sched& S, const Epi& E, int tid_in) {
;     ...
;             PG8_LDB(B0, 0, 0); PG8_LDB(B1, 0, 1); PG8_SCHED; PG8_LDA(At, 0, 0); PG8_STAGE(PG8_SA(1, 1), a1 + hstepA, voffA);
;             PG8_WAIT_V(8); PG8_WAIT_L(0); PG8_BAR; PG8_MMA(0, 0, At, B0); PG8_MMA(0, 1, At, B1); PG8_BAR; PG8_SCHED;
;             PG8_LDA(At, 0, 1); PG8_STAGE(PG8_SB(0, 0), b2, voffB); PG8_STAGE(PG8_SB(0, 1), b2 + hstepB, voffB); PG8_STAGE(PG8_SA(0, 0), a2, voffA);
;             PG8_WAIT_V(8); PG8_WAIT_L(0); PG8_BAR; PG8_MMA(1, 0, At, B0); PG8_MMA(1, 1, At, B1); PG8_BAR; PG8_SCHED;
.LBB0_137:
	v_add_u32_e32 v0, 0x10000, v193
	ds_read_b128 v[2:5], v0
	ds_read_b128 v[6:9], v0 offset:1024
	ds_read_b128 v[10:13], v0 offset:2048
	ds_read_b128 v[14:17], v0 offset:3072
	v_add_u32_e32 v0, 0x14000, v193
	ds_read_b128 v[18:21], v0
	ds_read_b128 v[22:25], v0 offset:1024
	ds_read_b128 v[26:29], v0 offset:2048
	ds_read_b128 v[30:33], v0 offset:3072
	s_add_i32 s11, s4, 0xfff00080
	s_cmp_eq_u32 s10, 60
	s_cselect_b32 s13, s3, s11
	s_cselect_b32 s12, s2, s5
	s_or_b32 s11, s13, 0x80
	s_mov_b32 m0, s8
	ds_read_b128 v[164:167], v194
	ds_read_b128 v[168:171], v194 offset:1024
	ds_read_b128 v[172:175], v194 offset:2048
	ds_read_b128 v[176:179], v194 offset:3072
	ds_read_b128 v[180:183], v194 offset:4096
	ds_read_b128 v[184:187], v194 offset:5120
	ds_read_b128 v[196:199], v194 offset:6144
	ds_read_b128 v[200:203], v194 offset:7168
	buffer_load_dwordx4 v115, s[40:43], s4 offen lds
	s_mov_b32 m0, s16
	s_nop 0
	buffer_load_dwordx4 v189, s[40:43], s4 offen lds
	s_waitcnt vmcnt(8)
	s_waitcnt lgkmcnt(0)
	s_barrier
	s_setprio 1
	s_waitcnt lgkmcnt(7)
	v_mfma_f32_16x16x32_bf16 v[46:49], v[2:5], v[164:167], v[46:49]
	v_mfma_f32_16x16x32_bf16 v[42:45], v[10:13], v[164:167], v[42:45]
	s_waitcnt lgkmcnt(5)
	v_mfma_f32_16x16x32_bf16 v[160:163], v[2:5], v[172:175], v[160:163]
	v_mfma_f32_16x16x32_bf16 v[156:159], v[10:13], v[172:175], v[156:159]
	s_waitcnt lgkmcnt(3)
	v_mfma_f32_16x16x32_bf16 v[144:147], v[2:5], v[180:183], v[144:147]
	v_mfma_f32_16x16x32_bf16 v[140:143], v[10:13], v[180:183], v[140:143]
	s_waitcnt lgkmcnt(1)
	v_mfma_f32_16x16x32_bf16 v[62:65], v[2:5], v[196:199], v[62:65]
	v_mfma_f32_16x16x32_bf16 v[58:61], v[10:13], v[196:199], v[58:61]
	v_mfma_f32_16x16x32_bf16 v[46:49], v[6:9], v[168:171], v[46:49]
	v_mfma_f32_16x16x32_bf16 v[42:45], v[14:17], v[168:171], v[42:45]
	v_mfma_f32_16x16x32_bf16 v[160:163], v[6:9], v[176:179], v[160:163]
	v_mfma_f32_16x16x32_bf16 v[156:159], v[14:17], v[176:179], v[156:159]
	v_mfma_f32_16x16x32_bf16 v[144:147], v[6:9], v[184:187], v[144:147]
	v_mfma_f32_16x16x32_bf16 v[140:143], v[14:17], v[184:187], v[140:143]
	s_waitcnt lgkmcnt(0)
	v_mfma_f32_16x16x32_bf16 v[62:65], v[6:9], v[200:203], v[62:65]
	v_mfma_f32_16x16x32_bf16 v[58:61], v[14:17], v[200:203], v[58:61]
	v_mfma_f32_16x16x32_bf16 v[38:41], v[18:21], v[164:167], v[38:41]
	v_mfma_f32_16x16x32_bf16 v[34:37], v[26:29], v[164:167], v[34:37]
	v_mfma_f32_16x16x32_bf16 v[152:155], v[18:21], v[172:175], v[152:155]
	v_mfma_f32_16x16x32_bf16 v[148:151], v[26:29], v[172:175], v[148:151]
	v_mfma_f32_16x16x32_bf16 v[136:139], v[18:21], v[180:183], v[136:139]
	v_mfma_f32_16x16x32_bf16 v[132:135], v[26:29], v[180:183], v[132:135]
	v_mfma_f32_16x16x32_bf16 v[54:57], v[18:21], v[196:199], v[54:57]
	v_mfma_f32_16x16x32_bf16 v[50:53], v[26:29], v[196:199], v[50:53]
	v_mfma_f32_16x16x32_bf16 v[38:41], v[22:25], v[168:171], v[38:41]
	v_mfma_f32_16x16x32_bf16 v[34:37], v[30:33], v[168:171], v[34:37]
	v_mfma_f32_16x16x32_bf16 v[152:155], v[22:25], v[176:179], v[152:155]
	v_mfma_f32_16x16x32_bf16 v[148:151], v[30:33], v[176:179], v[148:151]
	v_mfma_f32_16x16x32_bf16 v[136:139], v[22:25], v[184:187], v[136:139]
	v_mfma_f32_16x16x32_bf16 v[132:135], v[30:33], v[184:187], v[132:135]
	v_mfma_f32_16x16x32_bf16 v[54:57], v[22:25], v[200:203], v[54:57]
	v_mfma_f32_16x16x32_bf16 v[50:53], v[30:33], v[200:203], v[50:53]
	s_setprio 0
	s_barrier
	s_mov_b32 m0, s68
	s_mov_b32 s46, s42
	s_mov_b32 s47, s43
	ds_read_b128 v[164:167], v194 offset:16384
	ds_read_b128 v[168:171], v194 offset:17408
	ds_read_b128 v[172:175], v194 offset:18432
	ds_read_b128 v[176:179], v194 offset:19456
	ds_read_b128 v[180:183], v194 offset:20480
	ds_read_b128 v[184:187], v194 offset:21504
	ds_read_b128 v[196:199], v194 offset:22528
	ds_read_b128 v[200:203], v194 offset:23552
	buffer_load_dwordx4 v188, s[44:47], s12 offen lds
	s_mov_b32 m0, s69
	s_add_i32 s14, s12, 0x40000
	buffer_load_dwordx4 v190, s[44:47], s12 offen lds
	s_mov_b32 m0, s70
	s_nop 0
	buffer_load_dwordx4 v188, s[44:47], s14 offen lds
	s_mov_b32 m0, s72
	s_nop 0
	buffer_load_dwordx4 v190, s[44:47], s14 offen lds
	s_mov_b32 m0, s15
	s_nop 0
	buffer_load_dwordx4 v115, s[40:43], s13 offen lds
	s_mov_b32 m0, s73
	s_nop 0
	buffer_load_dwordx4 v189, s[40:43], s13 offen lds
	s_waitcnt vmcnt(8)
	s_waitcnt lgkmcnt(0)
	s_barrier
	s_setprio 1
	s_waitcnt lgkmcnt(7)
	v_mfma_f32_16x16x32_bf16 v[128:131], v[2:5], v[164:167], v[128:131]
	v_mfma_f32_16x16x32_bf16 v[124:127], v[10:13], v[164:167], v[124:127]
	s_waitcnt lgkmcnt(5)
	v_mfma_f32_16x16x32_bf16 v[110:113], v[2:5], v[172:175], v[110:113]
	v_mfma_f32_16x16x32_bf16 v[106:109], v[10:13], v[172:175], v[106:109]
	s_waitcnt lgkmcnt(3)
	v_mfma_f32_16x16x32_bf16 v[94:97], v[2:5], v[180:183], v[94:97]
	v_mfma_f32_16x16x32_bf16 v[90:93], v[10:13], v[180:183], v[90:93]
	s_waitcnt lgkmcnt(1)
	v_mfma_f32_16x16x32_bf16 v[2:5], v[2:5], v[196:199], v[78:81]
	v_mfma_f32_16x16x32_bf16 v[128:131], v[6:9], v[168:171], v[128:131]
	v_mfma_f32_16x16x32_bf16 v[124:127], v[14:17], v[168:171], v[124:127]
	v_mfma_f32_16x16x32_bf16 v[110:113], v[6:9], v[176:179], v[110:113]
	v_mfma_f32_16x16x32_bf16 v[106:109], v[14:17], v[176:179], v[106:109]
	v_mfma_f32_16x16x32_bf16 v[94:97], v[6:9], v[184:187], v[94:97]
	v_mfma_f32_16x16x32_bf16 v[90:93], v[14:17], v[184:187], v[90:93]
	s_waitcnt lgkmcnt(0)
	v_mfma_f32_16x16x32_bf16 v[2:5], v[6:9], v[200:203], v[2:5]
	v_mfma_f32_16x16x32_bf16 v[6:9], v[10:13], v[196:199], v[74:77]
	v_mfma_f32_16x16x32_bf16 v[6:9], v[14:17], v[200:203], v[6:9]
	v_mfma_f32_16x16x32_bf16 v[74:77], v[18:21], v[172:175], v[102:105]
	v_mfma_f32_16x16x32_bf16 v[102:105], v[22:25], v[176:179], v[74:77]
	v_mfma_f32_16x16x32_bf16 v[74:77], v[26:29], v[172:175], v[98:101]
	v_mfma_f32_16x16x32_bf16 v[98:101], v[30:33], v[176:179], v[74:77]
	v_mfma_f32_16x16x32_bf16 v[74:77], v[18:21], v[180:183], v[86:89]
	v_mfma_f32_16x16x32_bf16 v[10:13], v[18:21], v[164:167], v[120:123]
	v_mfma_f32_16x16x32_bf16 v[86:89], v[22:25], v[184:187], v[74:77]
	v_mfma_f32_16x16x32_bf16 v[74:77], v[26:29], v[180:183], v[82:85]
	v_mfma_f32_16x16x32_bf16 v[18:21], v[18:21], v[196:199], v[70:73]
	v_mfma_f32_16x16x32_bf16 v[10:13], v[22:25], v[168:171], v[10:13]
	v_mfma_f32_16x16x32_bf16 v[14:17], v[26:29], v[164:167], v[116:119]
	v_mfma_f32_16x16x32_bf16 v[82:85], v[30:33], v[184:187], v[74:77]
	v_mfma_f32_16x16x32_bf16 v[18:21], v[22:25], v[200:203], v[18:21]
	v_mfma_f32_16x16x32_bf16 v[22:25], v[26:29], v[196:199], v[66:69]
	v_mfma_f32_16x16x32_bf16 v[14:17], v[30:33], v[168:171], v[14:17]
	v_mfma_f32_16x16x32_bf16 v[22:25], v[30:33], v[200:203], v[22:25]
	s_setprio 0
	s_barrier
; #define PG8_STAGE(bufoff, goff, voff) do { _Pragma("unroll") for (int _i = 0; _i < 2; ++_i) \
;         __builtin_amdgcn_raw_ptr_buffer_load_lds(R_##voff, (LAS void*)(lds + (bufoff) + ldsw + _i * 8192), 16, (int)(voff)[_i], (int)(goff), 0, 0); } while (0)
; #define PG8_WAIT_V(n) asm volatile("s_waitcnt vmcnt(" #n ")" ::: "memory")
; #define PG8_WAIT_L(n) asm volatile("s_waitcnt lgkmcnt(" #n ")" ::: "memory")
; #define PG8_BAR __builtin_amdgcn_s_barrier()
; #define PG8_SCHED __builtin_amdgcn_sched_barrier(0)
; template <class Epi, class Sched, bool ALIGN_EPI, bool SP2>
; __device__ __forceinline__ void gemm_phase(LAS unsigned char* lds, const Gemm g, const Sched& S, const Epi& E, int tid_in) {
;     ...
;             PG8_LDB(B0, 1, 0); PG8_LDB(B1, 1, 1); PG8_SCHED; PG8_LDA(At, 1, 0); PG8_STAGE(PG8_SA(0, 1), a2 + hstepA, voffA);
;             PG8_WAIT_V(8); PG8_WAIT_L(0); PG8_BAR; PG8_MMA(0, 0, At, B0); PG8_MMA(0, 1, At, B1); PG8_BAR; PG8_SCHED;
;             PG8_LDA(At, 1, 1); PG8_STAGE(PG8_SB(1, 0), b3, voffB); PG8_STAGE(PG8_SB(1, 1), b3 + hstepB, voffB); PG8_STAGE(PG8_SA(1, 0), a3, voffA);
;             PG8_WAIT_V(8); PG8_WAIT_L(0); PG8_BAR; PG8_MMA(1, 0, At, B0); PG8_MMA(1, 1, At, B1); PG8_BAR; PG8_SCHED;
	v_add_u32_e32 v0, 0x18000, v193
	ds_read_b128 v[26:29], v0
	ds_read_b128 v[30:33], v0 offset:1024
	ds_read_b128 v[66:69], v0 offset:2048
	ds_read_b128 v[70:73], v0 offset:3072
	v_add_u32_e32 v0, 0x1c000, v193
	ds_read_b128 v[164:167], v0
	ds_read_b128 v[168:171], v0 offset:1024
	ds_read_b128 v[172:175], v0 offset:2048
	ds_read_b128 v[176:179], v0 offset:3072
	s_add_i32 s13, s13, 0x100000
	s_mov_b32 m0, s74
	ds_read_b128 v[74:77], v194 offset:32768
	ds_read_b128 v[78:81], v194 offset:33792
	ds_read_b128 v[116:119], v194 offset:34816
	ds_read_b128 v[120:123], v194 offset:35840
	ds_read_b128 v[180:183], v194 offset:36864
	ds_read_b128 v[184:187], v194 offset:37888
	ds_read_b128 v[196:199], v194 offset:38912
	ds_read_b128 v[200:203], v194 offset:39936
	buffer_load_dwordx4 v115, s[40:43], s13 offen lds
	s_mov_b32 m0, s75
	s_nop 0
	buffer_load_dwordx4 v189, s[40:43], s13 offen lds
	s_waitcnt vmcnt(8)
	s_waitcnt lgkmcnt(0)
	s_barrier
	s_setprio 1
	s_waitcnt lgkmcnt(7)
	v_mfma_f32_16x16x32_bf16 v[46:49], v[26:29], v[74:77], v[46:49]
	v_mfma_f32_16x16x32_bf16 v[42:45], v[66:69], v[74:77], v[42:45]
	s_waitcnt lgkmcnt(5)
	v_mfma_f32_16x16x32_bf16 v[160:163], v[26:29], v[116:119], v[160:163]
	v_mfma_f32_16x16x32_bf16 v[156:159], v[66:69], v[116:119], v[156:159]
	s_waitcnt lgkmcnt(3)
	v_mfma_f32_16x16x32_bf16 v[144:147], v[26:29], v[180:183], v[144:147]
	v_mfma_f32_16x16x32_bf16 v[140:143], v[66:69], v[180:183], v[140:143]
	s_waitcnt lgkmcnt(1)
	v_mfma_f32_16x16x32_bf16 v[62:65], v[26:29], v[196:199], v[62:65]
	v_mfma_f32_16x16x32_bf16 v[58:61], v[66:69], v[196:199], v[58:61]
	v_mfma_f32_16x16x32_bf16 v[46:49], v[30:33], v[78:81], v[46:49]
	v_mfma_f32_16x16x32_bf16 v[42:45], v[70:73], v[78:81], v[42:45]
	v_mfma_f32_16x16x32_bf16 v[160:163], v[30:33], v[120:123], v[160:163]
	v_mfma_f32_16x16x32_bf16 v[156:159], v[70:73], v[120:123], v[156:159]
	v_mfma_f32_16x16x32_bf16 v[144:147], v[30:33], v[184:187], v[144:147]
	v_mfma_f32_16x16x32_bf16 v[140:143], v[70:73], v[184:187], v[140:143]
	s_waitcnt lgkmcnt(0)
	v_mfma_f32_16x16x32_bf16 v[62:65], v[30:33], v[200:203], v[62:65]
	v_mfma_f32_16x16x32_bf16 v[58:61], v[70:73], v[200:203], v[58:61]
	v_mfma_f32_16x16x32_bf16 v[38:41], v[164:167], v[74:77], v[38:41]
	v_mfma_f32_16x16x32_bf16 v[34:37], v[172:175], v[74:77], v[34:37]
	v_mfma_f32_16x16x32_bf16 v[74:77], v[164:167], v[116:119], v[152:155]
	v_mfma_f32_16x16x32_bf16 v[152:155], v[168:171], v[120:123], v[74:77]
	v_mfma_f32_16x16x32_bf16 v[74:77], v[172:175], v[116:119], v[148:151]
	v_mfma_f32_16x16x32_bf16 v[148:151], v[176:179], v[120:123], v[74:77]
	v_mfma_f32_16x16x32_bf16 v[74:77], v[164:167], v[180:183], v[136:139]
	v_mfma_f32_16x16x32_bf16 v[136:139], v[168:171], v[184:187], v[74:77]
	v_mfma_f32_16x16x32_bf16 v[74:77], v[172:175], v[180:183], v[132:135]
	v_mfma_f32_16x16x32_bf16 v[54:57], v[164:167], v[196:199], v[54:57]
	v_mfma_f32_16x16x32_bf16 v[50:53], v[172:175], v[196:199], v[50:53]
	v_mfma_f32_16x16x32_bf16 v[38:41], v[168:171], v[78:81], v[38:41]
	v_mfma_f32_16x16x32_bf16 v[34:37], v[176:179], v[78:81], v[34:37]
	v_mfma_f32_16x16x32_bf16 v[132:135], v[176:179], v[184:187], v[74:77]
	v_mfma_f32_16x16x32_bf16 v[54:57], v[168:171], v[200:203], v[54:57]
	v_mfma_f32_16x16x32_bf16 v[50:53], v[176:179], v[200:203], v[50:53]
	s_setprio 0
	s_barrier
	s_mov_b32 m0, s85
	s_or_b32 s13, s12, 0x80
	ds_read_b128 v[116:119], v194 offset:49152
	ds_read_b128 v[180:183], v194 offset:50176
	ds_read_b128 v[184:187], v194 offset:51200
	ds_read_b128 v[196:199], v194 offset:52224
	ds_read_b128 v[200:203], v194 offset:53248
	ds_read_b128 v[204:207], v194 offset:54272
	ds_read_b128 v[208:211], v194 offset:55296
	ds_read_b128 v[220:223], v194 offset:56320
	buffer_load_dwordx4 v188, s[44:47], s13 offen lds
	s_mov_b32 m0, s93
	s_add_i32 s12, s12, 0x40080
	buffer_load_dwordx4 v190, s[44:47], s13 offen lds
	s_mov_b32 m0, s67
	s_nop 0
	buffer_load_dwordx4 v188, s[44:47], s12 offen lds
	s_mov_b32 m0, s49
	s_nop 0
	buffer_load_dwordx4 v190, s[44:47], s12 offen lds
	s_mov_b32 m0, s94
	s_nop 0
	buffer_load_dwordx4 v115, s[40:43], s11 offen lds
	s_mov_b32 m0, s95
	s_nop 0
	buffer_load_dwordx4 v189, s[40:43], s11 offen lds
	s_waitcnt vmcnt(8)
	s_waitcnt lgkmcnt(0)
	s_barrier
	s_setprio 1
	s_waitcnt lgkmcnt(7)
	v_mfma_f32_16x16x32_bf16 v[74:77], v[26:29], v[116:119], v[128:131]
	s_waitcnt lgkmcnt(6)
	v_mfma_f32_16x16x32_bf16 v[128:131], v[30:33], v[180:183], v[74:77]
	v_mfma_f32_16x16x32_bf16 v[74:77], v[66:69], v[116:119], v[124:127]
	v_mfma_f32_16x16x32_bf16 v[124:127], v[70:73], v[180:183], v[74:77]
	s_waitcnt lgkmcnt(5)
	v_mfma_f32_16x16x32_bf16 v[74:77], v[26:29], v[184:187], v[110:113]
	s_waitcnt lgkmcnt(4)
	v_mfma_f32_16x16x32_bf16 v[110:113], v[30:33], v[196:199], v[74:77]
	v_mfma_f32_16x16x32_bf16 v[74:77], v[66:69], v[184:187], v[106:109]
	v_mfma_f32_16x16x32_bf16 v[106:109], v[70:73], v[196:199], v[74:77]
	s_waitcnt lgkmcnt(3)
	v_mfma_f32_16x16x32_bf16 v[74:77], v[26:29], v[200:203], v[94:97]
	s_waitcnt lgkmcnt(1)
	v_mfma_f32_16x16x32_bf16 v[2:5], v[26:29], v[208:211], v[2:5]
	v_mfma_f32_16x16x32_bf16 v[94:97], v[30:33], v[204:207], v[74:77]
	v_mfma_f32_16x16x32_bf16 v[74:77], v[66:69], v[200:203], v[90:93]
	s_waitcnt lgkmcnt(0)
	v_mfma_f32_16x16x32_bf16 v[78:81], v[30:33], v[220:223], v[2:5]
	v_mfma_f32_16x16x32_bf16 v[2:5], v[66:69], v[208:211], v[6:9]
	v_mfma_f32_16x16x32_bf16 v[90:93], v[70:73], v[204:207], v[74:77]
	v_mfma_f32_16x16x32_bf16 v[74:77], v[70:73], v[220:223], v[2:5]
	v_mfma_f32_16x16x32_bf16 v[2:5], v[164:167], v[116:119], v[10:13]
	v_mfma_f32_16x16x32_bf16 v[120:123], v[168:171], v[180:183], v[2:5]
	v_mfma_f32_16x16x32_bf16 v[2:5], v[172:175], v[116:119], v[14:17]
	v_mfma_f32_16x16x32_bf16 v[116:119], v[176:179], v[180:183], v[2:5]
	v_mfma_f32_16x16x32_bf16 v[2:5], v[164:167], v[184:187], v[102:105]
	v_mfma_f32_16x16x32_bf16 v[102:105], v[168:171], v[196:199], v[2:5]
	v_mfma_f32_16x16x32_bf16 v[2:5], v[172:175], v[184:187], v[98:101]
	v_mfma_f32_16x16x32_bf16 v[98:101], v[176:179], v[196:199], v[2:5]
	v_mfma_f32_16x16x32_bf16 v[2:5], v[164:167], v[200:203], v[86:89]
	v_mfma_f32_16x16x32_bf16 v[86:89], v[168:171], v[204:207], v[2:5]
	v_mfma_f32_16x16x32_bf16 v[2:5], v[172:175], v[200:203], v[82:85]
	v_mfma_f32_16x16x32_bf16 v[82:85], v[176:179], v[204:207], v[2:5]
	v_mfma_f32_16x16x32_bf16 v[2:5], v[164:167], v[208:211], v[18:21]
	v_mfma_f32_16x16x32_bf16 v[70:73], v[168:171], v[220:223], v[2:5]
	v_mfma_f32_16x16x32_bf16 v[2:5], v[172:175], v[208:211], v[22:25]
	v_mfma_f32_16x16x32_bf16 v[66:69], v[176:179], v[220:223], v[2:5]
	s_setprio 0
	s_barrier
	s_add_i32 s10, s10, 2
	s_addk_i32 s4, 0x100
	s_addk_i32 s5, 0x100
	s_cmp_gt_u32 s10, 61
	s_cbranch_scc0 .LBB0_137
	v_readlane_b32 s2, v255, 30
	v_readlane_b32 s3, v255, 31
	s_and_b64 vcc, exec, s[2:3]
	s_cbranch_vccz .LBB0_140
	s_barrier

; #define PG8_STAGE(bufoff, goff, voff) do { _Pragma("unroll") for (int _i = 0; _i < 2; ++_i) \
;         __builtin_amdgcn_raw_ptr_buffer_load_lds(R_##voff, (LAS void*)(lds + (bufoff) + ldsw + _i * 8192), 16, (int)(voff)[_i], (int)(goff), 0, 0); } while (0)
; #define PG8_WAIT_V(n) asm volatile("s_waitcnt vmcnt(" #n ")" ::: "memory")
; #define PG8_WAIT_L(n) asm volatile("s_waitcnt lgkmcnt(" #n ")" ::: "memory")
; #define PG8_BAR __builtin_amdgcn_s_barrier()
; #define PG8_SCHED __builtin_amdgcn_sched_barrier(0)
; template <class Epi, class Sched, bool ALIGN_EPI, bool SP2>
; __device__ __forceinline__ void gemm_phase(LAS unsigned char* lds, const Gemm g, const Sched& S, const Epi& E, int tid_in) {
;     ...
;             PG8_LDB(B0, 0, 0); PG8_LDB(B1, 0, 1); PG8_SCHED; PG8_LDA(At, 0, 0); PG8_STAGE(PG8_SA(1, 1), a1 + hstepA, voffA);
;             PG8_WAIT_V(8); PG8_WAIT_L(0); PG8_BAR; PG8_MMA(0, 0, At, B0); PG8_MMA(0, 1, At, B1); PG8_BAR; PG8_SCHED;
;             PG8_LDA(At, 0, 1); PG8_STAGE(PG8_SB(0, 0), b2, voffB); PG8_STAGE(PG8_SB(0, 1), b2 + hstepB, voffB); PG8_STAGE(PG8_SA(0, 0), a2, voffA);
;             PG8_WAIT_V(8); PG8_WAIT_L(0); PG8_BAR; PG8_MMA(1, 0, At, B0); PG8_MMA(1, 1, At, B1); PG8_BAR; PG8_SCHED;
.LBB0_338:
	v_add_u32_e32 v144, 0x10000, v154
	v_add_u32_e32 v148, 0x14000, v154
	ds_read_b128 v[132:135], v144
	ds_read_b128 v[136:139], v144 offset:1024
	ds_read_b128 v[140:143], v144 offset:2048
	ds_read_b128 v[144:147], v144 offset:3072
	ds_read_b128 v[156:159], v148
	ds_read_b128 v[160:163], v148 offset:1024
	ds_read_b128 v[164:167], v148 offset:2048
	ds_read_b128 v[168:171], v148 offset:3072
	s_add_i32 s14, s57, 0xfff00080
	s_cmp_eq_u32 s59, 60
	s_cselect_b32 s14, s4, s14
	s_cselect_b32 s61, s5, s58
	s_or_b32 s60, s14, 0x80
	s_mov_b32 m0, s34
	ds_read_b128 v[172:175], v155
	ds_read_b128 v[176:179], v155 offset:1024
	ds_read_b128 v[180:183], v155 offset:2048
	ds_read_b128 v[184:187], v155 offset:3072
	ds_read_b128 v[188:191], v155 offset:4096
	ds_read_b128 v[192:195], v155 offset:5120
	ds_read_b128 v[196:199], v155 offset:6144
	ds_read_b128 v[200:203], v155 offset:7168
	buffer_load_dwordx4 v0, s[84:87], s57 offen lds
	s_mov_b32 m0, s47
	s_nop 0
	buffer_load_dwordx4 v150, s[84:87], s57 offen lds
	s_waitcnt vmcnt(8)
	s_waitcnt lgkmcnt(0)
	s_barrier
	s_setprio 1
	s_waitcnt lgkmcnt(7)
	v_mfma_f32_16x16x32_bf16 v[128:131], v[132:135], v[172:175], v[128:131]
	v_mfma_f32_16x16x32_bf16 v[124:127], v[140:143], v[172:175], v[124:127]
	s_waitcnt lgkmcnt(5)
	v_mfma_f32_16x16x32_bf16 v[116:119], v[132:135], v[180:183], v[116:119]
	v_mfma_f32_16x16x32_bf16 v[106:109], v[140:143], v[180:183], v[106:109]
	s_waitcnt lgkmcnt(3)
	v_mfma_f32_16x16x32_bf16 v[98:101], v[132:135], v[188:191], v[98:101]
	v_mfma_f32_16x16x32_bf16 v[90:93], v[140:143], v[188:191], v[90:93]
	s_waitcnt lgkmcnt(1)
	v_mfma_f32_16x16x32_bf16 v[82:85], v[132:135], v[196:199], v[82:85]
	v_mfma_f32_16x16x32_bf16 v[74:77], v[140:143], v[196:199], v[74:77]
	v_mfma_f32_16x16x32_bf16 v[128:131], v[136:139], v[176:179], v[128:131]
	v_mfma_f32_16x16x32_bf16 v[124:127], v[144:147], v[176:179], v[124:127]
	v_mfma_f32_16x16x32_bf16 v[116:119], v[136:139], v[184:187], v[116:119]
	v_mfma_f32_16x16x32_bf16 v[106:109], v[144:147], v[184:187], v[106:109]
	v_mfma_f32_16x16x32_bf16 v[98:101], v[136:139], v[192:195], v[98:101]
	v_mfma_f32_16x16x32_bf16 v[90:93], v[144:147], v[192:195], v[90:93]
	s_waitcnt lgkmcnt(0)
	v_mfma_f32_16x16x32_bf16 v[82:85], v[136:139], v[200:203], v[82:85]
	v_mfma_f32_16x16x32_bf16 v[74:77], v[144:147], v[200:203], v[74:77]
	v_mfma_f32_16x16x32_bf16 v[120:123], v[156:159], v[172:175], v[120:123]
	v_mfma_f32_16x16x32_bf16 v[110:113], v[164:167], v[172:175], v[110:113]
	v_mfma_f32_16x16x32_bf16 v[102:105], v[156:159], v[180:183], v[102:105]
	v_mfma_f32_16x16x32_bf16 v[94:97], v[164:167], v[180:183], v[94:97]
	v_mfma_f32_16x16x32_bf16 v[86:89], v[156:159], v[188:191], v[86:89]
	v_mfma_f32_16x16x32_bf16 v[78:81], v[164:167], v[188:191], v[78:81]
	v_mfma_f32_16x16x32_bf16 v[70:73], v[156:159], v[196:199], v[70:73]
	v_mfma_f32_16x16x32_bf16 v[66:69], v[164:167], v[196:199], v[66:69]
	v_mfma_f32_16x16x32_bf16 v[120:123], v[160:163], v[176:179], v[120:123]
	v_mfma_f32_16x16x32_bf16 v[110:113], v[168:171], v[176:179], v[110:113]
	v_mfma_f32_16x16x32_bf16 v[102:105], v[160:163], v[184:187], v[102:105]
	v_mfma_f32_16x16x32_bf16 v[94:97], v[168:171], v[184:187], v[94:97]
	v_mfma_f32_16x16x32_bf16 v[86:89], v[160:163], v[192:195], v[86:89]
	v_mfma_f32_16x16x32_bf16 v[78:81], v[168:171], v[192:195], v[78:81]
	v_mfma_f32_16x16x32_bf16 v[70:73], v[160:163], v[200:203], v[70:73]
	v_mfma_f32_16x16x32_bf16 v[66:69], v[168:171], v[200:203], v[66:69]
	s_setprio 0
	s_barrier
	s_mov_b32 m0, s8
	ds_read_b128 v[172:175], v155 offset:16384
	ds_read_b128 v[176:179], v155 offset:17408
	ds_read_b128 v[180:183], v155 offset:18432
	ds_read_b128 v[184:187], v155 offset:19456
	ds_read_b128 v[188:191], v155 offset:20480
	ds_read_b128 v[192:195], v155 offset:21504
	ds_read_b128 v[196:199], v155 offset:22528
	ds_read_b128 v[200:203], v155 offset:23552
	buffer_load_dwordx4 v115, s[40:43], s61 offen lds
	s_mov_b32 m0, s9
	s_add_i32 s15, s61, 0x40000
	buffer_load_dwordx4 v151, s[40:43], s61 offen lds
	s_mov_b32 m0, s10
	s_nop 0
	buffer_load_dwordx4 v115, s[40:43], s15 offen lds
	s_mov_b32 m0, s11
	s_nop 0
	buffer_load_dwordx4 v151, s[40:43], s15 offen lds
	s_mov_b32 m0, s7
	s_nop 0
	buffer_load_dwordx4 v0, s[84:87], s14 offen lds
	s_mov_b32 m0, s12
	s_nop 0
	buffer_load_dwordx4 v150, s[84:87], s14 offen lds
	s_waitcnt vmcnt(8)
	s_waitcnt lgkmcnt(0)
	s_barrier
	s_setprio 1
	s_waitcnt lgkmcnt(7)
	v_mfma_f32_16x16x32_bf16 v[62:65], v[132:135], v[172:175], v[62:65]
	v_mfma_f32_16x16x32_bf16 v[58:61], v[140:143], v[172:175], v[58:61]
	s_waitcnt lgkmcnt(5)
	v_mfma_f32_16x16x32_bf16 v[50:53], v[132:135], v[180:183], v[50:53]
	v_mfma_f32_16x16x32_bf16 v[42:45], v[140:143], v[180:183], v[42:45]
	s_waitcnt lgkmcnt(3)
	v_mfma_f32_16x16x32_bf16 v[34:37], v[132:135], v[188:191], v[34:37]
	v_mfma_f32_16x16x32_bf16 v[26:29], v[140:143], v[188:191], v[26:29]
	s_waitcnt lgkmcnt(1)
	v_mfma_f32_16x16x32_bf16 v[18:21], v[132:135], v[196:199], v[18:21]
	v_mfma_f32_16x16x32_bf16 v[10:13], v[140:143], v[196:199], v[10:13]
	v_mfma_f32_16x16x32_bf16 v[62:65], v[136:139], v[176:179], v[62:65]
	v_mfma_f32_16x16x32_bf16 v[58:61], v[144:147], v[176:179], v[58:61]
	v_mfma_f32_16x16x32_bf16 v[50:53], v[136:139], v[184:187], v[50:53]
	v_mfma_f32_16x16x32_bf16 v[42:45], v[144:147], v[184:187], v[42:45]
	v_mfma_f32_16x16x32_bf16 v[34:37], v[136:139], v[192:195], v[34:37]
	v_mfma_f32_16x16x32_bf16 v[26:29], v[144:147], v[192:195], v[26:29]
	s_waitcnt lgkmcnt(0)
	v_mfma_f32_16x16x32_bf16 v[18:21], v[136:139], v[200:203], v[18:21]
	v_mfma_f32_16x16x32_bf16 v[10:13], v[144:147], v[200:203], v[10:13]
	v_mfma_f32_16x16x32_bf16 v[54:57], v[156:159], v[172:175], v[54:57]
	v_mfma_f32_16x16x32_bf16 v[46:49], v[164:167], v[172:175], v[46:49]
	v_mfma_f32_16x16x32_bf16 v[38:41], v[156:159], v[180:183], v[38:41]
	v_mfma_f32_16x16x32_bf16 v[30:33], v[164:167], v[180:183], v[30:33]
	v_mfma_f32_16x16x32_bf16 v[22:25], v[156:159], v[188:191], v[22:25]
	v_mfma_f32_16x16x32_bf16 v[14:17], v[164:167], v[188:191], v[14:17]
	v_mfma_f32_16x16x32_bf16 v[6:9], v[156:159], v[196:199], v[6:9]
	v_mfma_f32_16x16x32_bf16 v[2:5], v[164:167], v[196:199], v[2:5]
	v_mfma_f32_16x16x32_bf16 v[54:57], v[160:163], v[176:179], v[54:57]
	v_mfma_f32_16x16x32_bf16 v[46:49], v[168:171], v[176:179], v[46:49]
	v_mfma_f32_16x16x32_bf16 v[38:41], v[160:163], v[184:187], v[38:41]
	v_mfma_f32_16x16x32_bf16 v[30:33], v[168:171], v[184:187], v[30:33]
	v_mfma_f32_16x16x32_bf16 v[22:25], v[160:163], v[192:195], v[22:25]
	v_mfma_f32_16x16x32_bf16 v[14:17], v[168:171], v[192:195], v[14:17]
	v_mfma_f32_16x16x32_bf16 v[6:9], v[160:163], v[200:203], v[6:9]
	v_mfma_f32_16x16x32_bf16 v[2:5], v[168:171], v[200:203], v[2:5]
	s_setprio 0
	s_barrier
; #define PG8_STAGE(bufoff, goff, voff) do { _Pragma("unroll") for (int _i = 0; _i < 2; ++_i) \
;         __builtin_amdgcn_raw_ptr_buffer_load_lds(R_##voff, (LAS void*)(lds + (bufoff) + ldsw + _i * 8192), 16, (int)(voff)[_i], (int)(goff), 0, 0); } while (0)
; #define PG8_WAIT_V(n) asm volatile("s_waitcnt vmcnt(" #n ")" ::: "memory")
; #define PG8_WAIT_L(n) asm volatile("s_waitcnt lgkmcnt(" #n ")" ::: "memory")
; #define PG8_BAR __builtin_amdgcn_s_barrier()
; #define PG8_SCHED __builtin_amdgcn_sched_barrier(0)
; template <class Epi, class Sched, bool ALIGN_EPI, bool SP2>
; __device__ __forceinline__ void gemm_phase(LAS unsigned char* lds, const Gemm g, const Sched& S, const Epi& E, int tid_in) {
;     ...
;             PG8_LDB(B0, 1, 0); PG8_LDB(B1, 1, 1); PG8_SCHED; PG8_LDA(At, 1, 0); PG8_STAGE(PG8_SA(0, 1), a2 + hstepA, voffA);
;             PG8_WAIT_V(8); PG8_WAIT_L(0); PG8_BAR; PG8_MMA(0, 0, At, B0); PG8_MMA(0, 1, At, B1); PG8_BAR; PG8_SCHED;
;             PG8_LDA(At, 1, 1); PG8_STAGE(PG8_SB(1, 0), b3, voffB); PG8_STAGE(PG8_SB(1, 1), b3 + hstepB, voffB); PG8_STAGE(PG8_SA(1, 0), a3, voffA);
;             PG8_WAIT_V(8); PG8_WAIT_L(0); PG8_BAR; PG8_MMA(1, 0, At, B0); PG8_MMA(1, 1, At, B1); PG8_BAR; PG8_SCHED;
	v_add_u32_e32 v144, 0x18000, v154
	v_add_u32_e32 v148, 0x1c000, v154
	ds_read_b128 v[132:135], v144
	ds_read_b128 v[136:139], v144 offset:1024
	ds_read_b128 v[140:143], v144 offset:2048
	ds_read_b128 v[144:147], v144 offset:3072
	ds_read_b128 v[156:159], v148
	ds_read_b128 v[160:163], v148 offset:1024
	ds_read_b128 v[164:167], v148 offset:2048
	ds_read_b128 v[168:171], v148 offset:3072
	s_add_i32 s14, s14, 0x100000
	s_mov_b32 m0, s13
	ds_read_b128 v[172:175], v155 offset:32768
	ds_read_b128 v[176:179], v155 offset:33792
	ds_read_b128 v[180:183], v155 offset:34816
	ds_read_b128 v[184:187], v155 offset:35840
	ds_read_b128 v[188:191], v155 offset:36864
	ds_read_b128 v[192:195], v155 offset:37888
	ds_read_b128 v[196:199], v155 offset:38912
	ds_read_b128 v[200:203], v155 offset:39936
	buffer_load_dwordx4 v0, s[84:87], s14 offen lds
	s_mov_b32 m0, s16
	s_nop 0
	buffer_load_dwordx4 v150, s[84:87], s14 offen lds
	s_waitcnt vmcnt(8)
	s_waitcnt lgkmcnt(0)
	s_barrier
	s_setprio 1
	s_waitcnt lgkmcnt(7)
	v_mfma_f32_16x16x32_bf16 v[128:131], v[132:135], v[172:175], v[128:131]
	v_mfma_f32_16x16x32_bf16 v[124:127], v[140:143], v[172:175], v[124:127]
	s_waitcnt lgkmcnt(5)
	v_mfma_f32_16x16x32_bf16 v[116:119], v[132:135], v[180:183], v[116:119]
	v_mfma_f32_16x16x32_bf16 v[106:109], v[140:143], v[180:183], v[106:109]
	s_waitcnt lgkmcnt(3)
	v_mfma_f32_16x16x32_bf16 v[98:101], v[132:135], v[188:191], v[98:101]
	v_mfma_f32_16x16x32_bf16 v[90:93], v[140:143], v[188:191], v[90:93]
	s_waitcnt lgkmcnt(1)
	v_mfma_f32_16x16x32_bf16 v[82:85], v[132:135], v[196:199], v[82:85]
	v_mfma_f32_16x16x32_bf16 v[74:77], v[140:143], v[196:199], v[74:77]
	v_mfma_f32_16x16x32_bf16 v[128:131], v[136:139], v[176:179], v[128:131]
	v_mfma_f32_16x16x32_bf16 v[124:127], v[144:147], v[176:179], v[124:127]
	v_mfma_f32_16x16x32_bf16 v[116:119], v[136:139], v[184:187], v[116:119]
	v_mfma_f32_16x16x32_bf16 v[106:109], v[144:147], v[184:187], v[106:109]
	v_mfma_f32_16x16x32_bf16 v[98:101], v[136:139], v[192:195], v[98:101]
	v_mfma_f32_16x16x32_bf16 v[90:93], v[144:147], v[192:195], v[90:93]
	s_waitcnt lgkmcnt(0)
	v_mfma_f32_16x16x32_bf16 v[82:85], v[136:139], v[200:203], v[82:85]
	v_mfma_f32_16x16x32_bf16 v[74:77], v[144:147], v[200:203], v[74:77]
	v_mfma_f32_16x16x32_bf16 v[120:123], v[156:159], v[172:175], v[120:123]
	v_mfma_f32_16x16x32_bf16 v[110:113], v[164:167], v[172:175], v[110:113]
	v_mfma_f32_16x16x32_bf16 v[102:105], v[156:159], v[180:183], v[102:105]
	v_mfma_f32_16x16x32_bf16 v[94:97], v[164:167], v[180:183], v[94:97]
	v_mfma_f32_16x16x32_bf16 v[86:89], v[156:159], v[188:191], v[86:89]
	v_mfma_f32_16x16x32_bf16 v[78:81], v[164:167], v[188:191], v[78:81]
	v_mfma_f32_16x16x32_bf16 v[70:73], v[156:159], v[196:199], v[70:73]
	v_mfma_f32_16x16x32_bf16 v[66:69], v[164:167], v[196:199], v[66:69]
	v_mfma_f32_16x16x32_bf16 v[120:123], v[160:163], v[176:179], v[120:123]
	v_mfma_f32_16x16x32_bf16 v[110:113], v[168:171], v[176:179], v[110:113]
	v_mfma_f32_16x16x32_bf16 v[102:105], v[160:163], v[184:187], v[102:105]
	v_mfma_f32_16x16x32_bf16 v[94:97], v[168:171], v[184:187], v[94:97]
	v_mfma_f32_16x16x32_bf16 v[86:89], v[160:163], v[192:195], v[86:89]
	v_mfma_f32_16x16x32_bf16 v[78:81], v[168:171], v[192:195], v[78:81]
	v_mfma_f32_16x16x32_bf16 v[70:73], v[160:163], v[200:203], v[70:73]
	v_mfma_f32_16x16x32_bf16 v[66:69], v[168:171], v[200:203], v[66:69]
	s_setprio 0
	s_barrier
	s_mov_b32 m0, s17
	s_or_b32 s14, s61, 0x80
	ds_read_b128 v[172:175], v155 offset:49152
	ds_read_b128 v[176:179], v155 offset:50176
	ds_read_b128 v[180:183], v155 offset:51200
	ds_read_b128 v[184:187], v155 offset:52224
	ds_read_b128 v[188:191], v155 offset:53248
	ds_read_b128 v[192:195], v155 offset:54272
	ds_read_b128 v[196:199], v155 offset:55296
	ds_read_b128 v[200:203], v155 offset:56320
	buffer_load_dwordx4 v115, s[40:43], s14 offen lds
	s_mov_b32 m0, s19
	s_add_i32 s61, s61, 0x40080
	buffer_load_dwordx4 v151, s[40:43], s14 offen lds
	s_mov_b32 m0, s29
	s_nop 0
	buffer_load_dwordx4 v115, s[40:43], s61 offen lds
	s_mov_b32 m0, s30
	s_nop 0
	buffer_load_dwordx4 v151, s[40:43], s61 offen lds
	s_mov_b32 m0, s25
	s_nop 0
	buffer_load_dwordx4 v0, s[84:87], s60 offen lds
	s_mov_b32 m0, s27
	s_nop 0
	buffer_load_dwordx4 v150, s[84:87], s60 offen lds
	s_waitcnt vmcnt(8)
	s_waitcnt lgkmcnt(0)
	s_barrier
	s_setprio 1
	s_waitcnt lgkmcnt(7)
	v_mfma_f32_16x16x32_bf16 v[62:65], v[132:135], v[172:175], v[62:65]
	v_mfma_f32_16x16x32_bf16 v[58:61], v[140:143], v[172:175], v[58:61]
	s_waitcnt lgkmcnt(5)
	v_mfma_f32_16x16x32_bf16 v[50:53], v[132:135], v[180:183], v[50:53]
	v_mfma_f32_16x16x32_bf16 v[42:45], v[140:143], v[180:183], v[42:45]
	s_waitcnt lgkmcnt(3)
	v_mfma_f32_16x16x32_bf16 v[34:37], v[132:135], v[188:191], v[34:37]
	v_mfma_f32_16x16x32_bf16 v[26:29], v[140:143], v[188:191], v[26:29]
	s_waitcnt lgkmcnt(1)
	v_mfma_f32_16x16x32_bf16 v[18:21], v[132:135], v[196:199], v[18:21]
	v_mfma_f32_16x16x32_bf16 v[10:13], v[140:143], v[196:199], v[10:13]
	v_mfma_f32_16x16x32_bf16 v[62:65], v[136:139], v[176:179], v[62:65]
	v_mfma_f32_16x16x32_bf16 v[58:61], v[144:147], v[176:179], v[58:61]
	v_mfma_f32_16x16x32_bf16 v[50:53], v[136:139], v[184:187], v[50:53]
	v_mfma_f32_16x16x32_bf16 v[42:45], v[144:147], v[184:187], v[42:45]
	v_mfma_f32_16x16x32_bf16 v[34:37], v[136:139], v[192:195], v[34:37]
	v_mfma_f32_16x16x32_bf16 v[26:29], v[144:147], v[192:195], v[26:29]
	s_waitcnt lgkmcnt(0)
	v_mfma_f32_16x16x32_bf16 v[18:21], v[136:139], v[200:203], v[18:21]
	v_mfma_f32_16x16x32_bf16 v[10:13], v[144:147], v[200:203], v[10:13]
	v_mfma_f32_16x16x32_bf16 v[54:57], v[156:159], v[172:175], v[54:57]
	v_mfma_f32_16x16x32_bf16 v[46:49], v[164:167], v[172:175], v[46:49]
	v_mfma_f32_16x16x32_bf16 v[38:41], v[156:159], v[180:183], v[38:41]
	v_mfma_f32_16x16x32_bf16 v[30:33], v[164:167], v[180:183], v[30:33]
	v_mfma_f32_16x16x32_bf16 v[22:25], v[156:159], v[188:191], v[22:25]
	v_mfma_f32_16x16x32_bf16 v[14:17], v[164:167], v[188:191], v[14:17]
	v_mfma_f32_16x16x32_bf16 v[6:9], v[156:159], v[196:199], v[6:9]
	v_mfma_f32_16x16x32_bf16 v[2:5], v[164:167], v[196:199], v[2:5]
	v_mfma_f32_16x16x32_bf16 v[54:57], v[160:163], v[176:179], v[54:57]
	v_mfma_f32_16x16x32_bf16 v[46:49], v[168:171], v[176:179], v[46:49]
	v_mfma_f32_16x16x32_bf16 v[38:41], v[160:163], v[184:187], v[38:41]
	v_mfma_f32_16x16x32_bf16 v[30:33], v[168:171], v[184:187], v[30:33]
	v_mfma_f32_16x16x32_bf16 v[22:25], v[160:163], v[192:195], v[22:25]
	v_mfma_f32_16x16x32_bf16 v[14:17], v[168:171], v[192:195], v[14:17]
	v_mfma_f32_16x16x32_bf16 v[6:9], v[160:163], v[200:203], v[6:9]
	v_mfma_f32_16x16x32_bf16 v[2:5], v[168:171], v[200:203], v[2:5]
	s_setprio 0
	s_barrier
	s_add_i32 s59, s59, 2
	s_addk_i32 s57, 0x100
	s_addk_i32 s58, 0x100
	s_cmp_gt_u32 s59, 61
	s_cbranch_scc0 .LBB0_338
	s_and_b64 vcc, exec, s[44:45]
	s_cbranch_vccz .LBB0_341
	s_barrier

;     __device__ __forceinline__ bool next(int i, Unit& u) const { if (i) return false; u.pm = pm; u.pn = pn; return true; }
; #define PG8_BAR __builtin_amdgcn_s_barrier()
; template <class Epi, class Sched, bool ALIGN_EPI, bool SP2>
; __device__ __forceinline__ void gemm_phase(LAS unsigned char* lds, const Gemm g, const Sched& S, const Epi& E, int tid_in) {
;     ...
;         PG8_STAGE(PG8_SB(0, 0), cB, voffB); PG8_STAGE(PG8_SB(0, 1), cB + hstepB, voffB); PG8_STAGE(PG8_SA(0, 0), cA, voffA); PG8_STAGE(PG8_SA(0, 1), cA + hstepA, voffA);
;         if (wr == 1) PG8_BAR;
;         PG8_WAIT_V(2); PG8_BAR;
;         PG8_STAGE(PG8_SB(1, 0), cB + kstep, voffB); PG8_STAGE(PG8_SA(1, 0), cA + kstep, voffA); PG8_STAGE(PG8_SB(1, 1), cB + hstepB + kstep, voffB);
;         PG8_WAIT_V(6); PG8_BAR;
;     } else {
;         PG8_STAGE(PG8_SB(0, 0), cB, voffB); PG8_STAGE(PG8_SA(0, 0), cA, voffA); PG8_STAGE(PG8_SB(0, 1), cB + hstepB, voffB); PG8_STAGE(PG8_SA(0, 1), cA + hstepA, voffA);
;         if (wr == 1) PG8_BAR;
;         PG8_WAIT_V(4); PG8_BAR;
;         PG8_STAGE(PG8_SB(1, 0), cB + kstep, voffB); PG8_STAGE(PG8_SA(1, 0), cA + kstep, voffA); PG8_STAGE(PG8_SB(1, 1), cB + hstepB + kstep, voffB);
;         PG8_WAIT_V(6); PG8_BAR;
;     }
;     for (;;) {
;         const bool has_next = S.next(ui + 1, nxt);
;         const unsigned nA = has_next ? (unsigned)nxt.pm * tstepA : cA, nB = has_next ? (unsigned)nxt.pn * tstepB : cB;
;         for (int t = 0; t < nt; t += 2) {
;             const bool last = (t == nt - 2);
;             const unsigned a1 = cA + (unsigned)(t + 1) * kstep;
;             const unsigned a2 = last ? nA : cA + (unsigned)(t + 2) * kstep, b2 = last ? nB : cB + (unsigned)(t + 2) * kstep;
;             const unsigned a3 = a2 + kstep, b3 = b2 + kstep;
;             if constexpr (Epi::MIDK) { if (t == g.kmid) E.midk(acc, wr, fr); }
;             if constexpr (SP2) {
;             PG8_LDB(B0, 0, 0); PG8_LDB(B1, 0, 1); PG8_SCHED; PG8_LDA(At, 0, 0); PG8_STAGE(PG8_SA(1, 1), a1 + hstepA, voffA);
;             PG8_WAIT_V(8); PG8_WAIT_L(0); PG8_BAR; PG8_MMA(0, 0, At, B0); PG8_MMA(0, 1, At, B1); PG8_BAR; PG8_SCHED;
;             PG8_LDA(At, 0, 1); PG8_STAGE(PG8_SB(0, 0), b2, voffB); PG8_STAGE(PG8_SB(0, 1), b2 + hstepB, voffB); PG8_STAGE(PG8_SA(0, 0), a2, voffA);
;             PG8_WAIT_V(8); PG8_WAIT_L(0); PG8_BAR; PG8_MMA(1, 0, At, B0); PG8_MMA(1, 1, At, B1); PG8_BAR; PG8_SCHED;
.LBB0_503:
	s_add_i32 s25, 0, 0x18000
	s_add_i32 s57, s25, s12
	s_mov_b32 m0, s57
	s_movk_i32 s72, 0x80
	s_add_i32 s67, s57, 0x2000
	s_waitcnt vmcnt(2)
	s_barrier
	buffer_load_dwordx4 v34, s[84:87], s72 offen lds
	s_mov_b32 m0, s67
	s_add_i32 s66, s31, 0x8000
	buffer_load_dwordx4 v36, s[84:87], s72 offen lds
	s_or_b32 s12, s13, 0x80
	s_mov_b32 s36, s46
	s_mov_b32 s38, s86
	s_mov_b32 s39, s87
	s_mov_b32 m0, s66
	s_add_i32 s68, s31, 0xa000
	buffer_load_dwordx4 v0, s[36:39], s12 offen lds
	s_mov_b32 m0, s68
	s_add_i32 s69, s31, 0x1c000
	buffer_load_dwordx4 v35, s[36:39], s12 offen lds
	s_mov_b32 m0, s69
	s_mov_b32 s73, 0x10080
	s_add_i32 s70, s31, 0x1e000
	buffer_load_dwordx4 v34, s[84:87], s73 offen lds
	s_mov_b32 m0, s70
	v_bfe_u32 v66, v2, 4, 2
	buffer_load_dwordx4 v36, s[84:87], s73 offen lds
	s_and_b32 s4, s4, 3
	v_and_b32_e32 v67, 15, v2
	v_lshlrev_b32_e32 v3, 4, v66
	v_lshlrev_b32_e32 v2, 2, v2
	v_lshl_or_b32 v3, v67, 6, v3
	v_and_b32_e32 v2, 32, v2
	s_lshl_b32 s15, s4, 12
	s_lshl_b32 s14, s5, 13
	v_bitop3_b32 v4, v3, s15, v2 bitop3:0xde
	v_bitop3_b32 v2, v3, s14, v2 bitop3:0xde
	v_add_u32_e32 v3, 0, v4
	v_add_u32_e32 v37, 0x10000, v3
	s_waitcnt vmcnt(6)
	s_barrier
	v_add_u32_e32 v112, 0, v2
	v_add_u32_e32 v113, s25, v4
	ds_read_b128 v[2:5], v37
	ds_read_b128 v[6:9], v37 offset:1024
	ds_read_b128 v[10:13], v37 offset:2048
	ds_read_b128 v[14:17], v37 offset:3072
	s_add_i32 s27, s13, 0x18080
	s_or_b32 s19, s13, 0x100
	s_or_b32 s16, s13, 0x180
	s_add_i32 s71, s31, 0xc000
	s_mov_b32 m0, s71
	s_add_i32 s14, s31, 0xe000
	ds_read_b128 v[18:21], v112
	ds_read_b128 v[22:25], v112 offset:1024
	ds_read_b128 v[26:29], v112 offset:2048
	s_waitcnt vmcnt(14)
	ds_read_b128 v[30:33], v112 offset:3072
	ds_read_b128 v[38:41], v112 offset:4096
	ds_read_b128 v[42:45], v112 offset:5120
	ds_read_b128 v[46:49], v112 offset:6144
	ds_read_b128 v[50:53], v112 offset:7168
	buffer_load_dwordx4 v0, s[36:39], s27 offen lds
	s_mov_b32 m0, s14
	s_nop 0
	buffer_load_dwordx4 v35, s[36:39], s27 offen lds
	s_waitcnt vmcnt(8)
	s_waitcnt lgkmcnt(0)
	s_barrier
	s_setprio 1
	s_waitcnt lgkmcnt(7)
	v_mfma_f32_16x16x32_bf16 v[54:57], v[2:5], v[18:21], 0
	v_mfma_f32_16x16x32_bf16 v[18:21], v[10:13], v[18:21], 0
	s_waitcnt lgkmcnt(6)
	v_mfma_f32_16x16x32_bf16 v[54:57], v[6:9], v[22:25], v[54:57]
	v_mfma_f32_16x16x32_bf16 v[18:21], v[14:17], v[22:25], v[18:21]
	s_waitcnt lgkmcnt(5)
	v_mfma_f32_16x16x32_bf16 v[22:25], v[2:5], v[26:29], 0
	v_mfma_f32_16x16x32_bf16 v[26:29], v[10:13], v[26:29], 0
	s_waitcnt lgkmcnt(4)
	v_mfma_f32_16x16x32_bf16 v[22:25], v[6:9], v[30:33], v[22:25]
	v_mfma_f32_16x16x32_bf16 v[26:29], v[14:17], v[30:33], v[26:29]
	s_waitcnt lgkmcnt(3)
	v_mfma_f32_16x16x32_bf16 v[30:33], v[2:5], v[38:41], 0
	v_mfma_f32_16x16x32_bf16 v[38:41], v[10:13], v[38:41], 0
	s_waitcnt lgkmcnt(2)
	v_mfma_f32_16x16x32_bf16 v[30:33], v[6:9], v[42:45], v[30:33]
	v_mfma_f32_16x16x32_bf16 v[38:41], v[14:17], v[42:45], v[38:41]
	s_waitcnt lgkmcnt(1)
	v_mfma_f32_16x16x32_bf16 v[42:45], v[2:5], v[46:49], 0
	v_mfma_f32_16x16x32_bf16 v[46:49], v[10:13], v[46:49], 0
	s_waitcnt lgkmcnt(0)
	v_mfma_f32_16x16x32_bf16 v[42:45], v[6:9], v[50:53], v[42:45]
	v_mfma_f32_16x16x32_bf16 v[46:49], v[14:17], v[50:53], v[46:49]
	s_setprio 0
	s_barrier
	s_mov_b32 m0, s34
	s_movk_i32 s15, 0x100
	ds_read_b128 v[50:53], v112 offset:16384
	ds_read_b128 v[58:61], v112 offset:17408
	ds_read_b128 v[62:65], v112 offset:18432
	ds_read_b128 v[68:71], v112 offset:19456
	ds_read_b128 v[72:75], v112 offset:20480
	ds_read_b128 v[76:79], v112 offset:21504
	ds_read_b128 v[80:83], v112 offset:22528
	ds_read_b128 v[84:87], v112 offset:23552
	buffer_load_dwordx4 v34, s[84:87], s15 offen lds
	s_mov_b32 m0, s50
	s_nop 0
	buffer_load_dwordx4 v36, s[84:87], s15 offen lds
	s_mov_b32 m0, s52
	s_mov_b32 s15, 0x10100
	buffer_load_dwordx4 v34, s[84:87], s15 offen lds
	s_mov_b32 m0, s56
	s_nop 0
	buffer_load_dwordx4 v36, s[84:87], s15 offen lds
	s_mov_b32 m0, s31
	s_nop 0
	buffer_load_dwordx4 v0, s[36:39], s19 offen lds
	s_mov_b32 m0, s65
	s_nop 0
	buffer_load_dwordx4 v35, s[36:39], s19 offen lds
	s_waitcnt vmcnt(8)
	s_waitcnt lgkmcnt(0)
	s_barrier
	s_setprio 1
	s_waitcnt lgkmcnt(7)
	v_mfma_f32_16x16x32_bf16 v[88:91], v[2:5], v[50:53], 0
	v_mfma_f32_16x16x32_bf16 v[50:53], v[10:13], v[50:53], 0
	s_waitcnt lgkmcnt(6)
	v_mfma_f32_16x16x32_bf16 v[88:91], v[6:9], v[58:61], v[88:91]
	v_mfma_f32_16x16x32_bf16 v[50:53], v[14:17], v[58:61], v[50:53]
	s_waitcnt lgkmcnt(5)
	v_mfma_f32_16x16x32_bf16 v[58:61], v[2:5], v[62:65], 0
	v_mfma_f32_16x16x32_bf16 v[62:65], v[10:13], v[62:65], 0
	s_waitcnt lgkmcnt(4)
	v_mfma_f32_16x16x32_bf16 v[58:61], v[6:9], v[68:71], v[58:61]
	v_mfma_f32_16x16x32_bf16 v[62:65], v[14:17], v[68:71], v[62:65]
	s_waitcnt lgkmcnt(3)
	v_mfma_f32_16x16x32_bf16 v[68:71], v[2:5], v[72:75], 0
	s_waitcnt lgkmcnt(1)
	v_mfma_f32_16x16x32_bf16 v[2:5], v[2:5], v[80:83], 0
	v_mfma_f32_16x16x32_bf16 v[68:71], v[6:9], v[76:79], v[68:71]
	s_waitcnt lgkmcnt(0)
	v_mfma_f32_16x16x32_bf16 v[2:5], v[6:9], v[84:87], v[2:5]
	v_mfma_f32_16x16x32_bf16 v[6:9], v[10:13], v[80:83], 0
	v_mfma_f32_16x16x32_bf16 v[72:75], v[10:13], v[72:75], 0
	v_mfma_f32_16x16x32_bf16 v[6:9], v[14:17], v[84:87], v[6:9]
	v_mfma_f32_16x16x32_bf16 v[72:75], v[14:17], v[76:79], v[72:75]
	s_setprio 0
	s_barrier
	ds_read_b128 v[10:13], v113
	ds_read_b128 v[14:17], v113 offset:1024
	ds_read_b128 v[76:79], v113 offset:2048
	ds_read_b128 v[80:83], v113 offset:3072
	s_add_i32 s29, s13, 0x18100
	s_mov_b32 m0, s11
	ds_read_b128 v[84:87], v112 offset:32768
	ds_read_b128 v[92:95], v112 offset:33792
	ds_read_b128 v[96:99], v112 offset:34816
	ds_read_b128 v[100:103], v112 offset:35840
	ds_read_b128 v[104:107], v112 offset:36864
	ds_read_b128 v[108:111], v112 offset:37888
	ds_read_b128 v[116:119], v112 offset:38912
	ds_read_b128 v[120:123], v112 offset:39936
	buffer_load_dwordx4 v0, s[36:39], s29 offen lds
	s_mov_b32 m0, s30
	s_nop 0
	buffer_load_dwordx4 v35, s[36:39], s29 offen lds
	s_waitcnt vmcnt(8)
	s_waitcnt lgkmcnt(0)
	s_barrier
; #define PG8_STAGE(bufoff, goff, voff) do { _Pragma("unroll") for (int _i = 0; _i < 2; ++_i) \
;         __builtin_amdgcn_raw_ptr_buffer_load_lds(R_##voff, (LAS void*)(lds + (bufoff) + ldsw + _i * 8192), 16, (int)(voff)[_i], (int)(goff), 0, 0); } while (0)
; #define PG8_WAIT_V(n) asm volatile("s_waitcnt vmcnt(" #n ")" ::: "memory")
; #define PG8_WAIT_L(n) asm volatile("s_waitcnt lgkmcnt(" #n ")" ::: "memory")
; #define PG8_BAR __builtin_amdgcn_s_barrier()
; #define PG8_SCHED __builtin_amdgcn_sched_barrier(0)
; template <class Epi, class Sched, bool ALIGN_EPI, bool SP2>
; __device__ __forceinline__ void gemm_phase(LAS unsigned char* lds, const Gemm g, const Sched& S, const Epi& E, int tid_in) {
;     ...
;             PG8_WAIT_V(8); PG8_WAIT_L(0); PG8_BAR; PG8_MMA(1, 0, At, B0); PG8_MMA(1, 1, At, B1); PG8_BAR; PG8_SCHED;
;             PG8_LDB(B0, 1, 0); PG8_LDB(B1, 1, 1); PG8_SCHED; PG8_LDA(At, 1, 0); PG8_STAGE(PG8_SA(0, 1), a2 + hstepA, voffA);
;             PG8_WAIT_V(8); PG8_WAIT_L(0); PG8_BAR; PG8_MMA(0, 0, At, B0); PG8_MMA(0, 1, At, B1); PG8_BAR; PG8_SCHED;
;             PG8_LDA(At, 1, 1); PG8_STAGE(PG8_SB(1, 0), b3, voffB); PG8_STAGE(PG8_SB(1, 1), b3 + hstepB, voffB); PG8_STAGE(PG8_SA(1, 0), a3, voffA);
;             PG8_WAIT_V(8); PG8_WAIT_L(0); PG8_BAR; PG8_MMA(1, 0, At, B0); PG8_MMA(1, 1, At, B1); PG8_BAR; PG8_SCHED;
	s_setprio 1
	s_waitcnt lgkmcnt(7)
	v_mfma_f32_16x16x32_bf16 v[54:57], v[10:13], v[84:87], v[54:57]
	v_mfma_f32_16x16x32_bf16 v[18:21], v[76:79], v[84:87], v[18:21]
	s_waitcnt lgkmcnt(5)
	v_mfma_f32_16x16x32_bf16 v[22:25], v[10:13], v[96:99], v[22:25]
	v_mfma_f32_16x16x32_bf16 v[26:29], v[76:79], v[96:99], v[26:29]
	s_waitcnt lgkmcnt(3)
	v_mfma_f32_16x16x32_bf16 v[30:33], v[10:13], v[104:107], v[30:33]
	v_mfma_f32_16x16x32_bf16 v[38:41], v[76:79], v[104:107], v[38:41]
	s_waitcnt lgkmcnt(1)
	v_mfma_f32_16x16x32_bf16 v[42:45], v[10:13], v[116:119], v[42:45]
	v_mfma_f32_16x16x32_bf16 v[46:49], v[76:79], v[116:119], v[46:49]
	v_mfma_f32_16x16x32_bf16 v[54:57], v[14:17], v[92:95], v[54:57]
	v_mfma_f32_16x16x32_bf16 v[18:21], v[80:83], v[92:95], v[18:21]
	v_mfma_f32_16x16x32_bf16 v[22:25], v[14:17], v[100:103], v[22:25]
	v_mfma_f32_16x16x32_bf16 v[26:29], v[80:83], v[100:103], v[26:29]
	v_mfma_f32_16x16x32_bf16 v[30:33], v[14:17], v[108:111], v[30:33]
	v_mfma_f32_16x16x32_bf16 v[38:41], v[80:83], v[108:111], v[38:41]
	s_waitcnt lgkmcnt(0)
	v_mfma_f32_16x16x32_bf16 v[42:45], v[14:17], v[120:123], v[42:45]
	v_mfma_f32_16x16x32_bf16 v[46:49], v[80:83], v[120:123], v[46:49]
	s_setprio 0
	s_barrier
	s_mov_b32 m0, s57
	s_movk_i32 s15, 0x180
	ds_read_b128 v[84:87], v112 offset:49152
	ds_read_b128 v[92:95], v112 offset:50176
	ds_read_b128 v[96:99], v112 offset:51200
	ds_read_b128 v[100:103], v112 offset:52224
	ds_read_b128 v[104:107], v112 offset:53248
	ds_read_b128 v[108:111], v112 offset:54272
	ds_read_b128 v[116:119], v112 offset:55296
	ds_read_b128 v[120:123], v112 offset:56320
	buffer_load_dwordx4 v34, s[84:87], s15 offen lds
	s_mov_b32 m0, s67
	s_nop 0
	buffer_load_dwordx4 v36, s[84:87], s15 offen lds
	s_mov_b32 m0, s69
	s_mov_b32 s15, 0x10180
	buffer_load_dwordx4 v34, s[84:87], s15 offen lds
	s_mov_b32 m0, s70
	s_nop 0
	buffer_load_dwordx4 v36, s[84:87], s15 offen lds
	s_mov_b32 m0, s66
	s_nop 0
	buffer_load_dwordx4 v0, s[36:39], s16 offen lds
	s_mov_b32 m0, s68
	s_nop 0
	buffer_load_dwordx4 v35, s[36:39], s16 offen lds
	s_waitcnt vmcnt(8)
	s_waitcnt lgkmcnt(0)
	s_barrier
	s_setprio 1
	s_waitcnt lgkmcnt(7)
	v_mfma_f32_16x16x32_bf16 v[50:53], v[76:79], v[84:87], v[50:53]
	s_waitcnt lgkmcnt(5)
	v_mfma_f32_16x16x32_bf16 v[58:61], v[10:13], v[96:99], v[58:61]
	v_mfma_f32_16x16x32_bf16 v[62:65], v[76:79], v[96:99], v[62:65]
	s_waitcnt lgkmcnt(1)
	v_mfma_f32_16x16x32_bf16 v[2:5], v[10:13], v[116:119], v[2:5]
	v_mfma_f32_16x16x32_bf16 v[6:9], v[76:79], v[116:119], v[6:9]
	v_mfma_f32_16x16x32_bf16 v[88:91], v[10:13], v[84:87], v[88:91]
	v_mfma_f32_16x16x32_bf16 v[50:53], v[80:83], v[92:95], v[50:53]
	v_mfma_f32_16x16x32_bf16 v[58:61], v[14:17], v[100:103], v[58:61]
	v_mfma_f32_16x16x32_bf16 v[62:65], v[80:83], v[100:103], v[62:65]
	v_mfma_f32_16x16x32_bf16 v[68:71], v[10:13], v[104:107], v[68:71]
	v_mfma_f32_16x16x32_bf16 v[72:75], v[76:79], v[104:107], v[72:75]
	s_waitcnt lgkmcnt(0)
	v_mfma_f32_16x16x32_bf16 v[2:5], v[14:17], v[120:123], v[2:5]
	v_mfma_f32_16x16x32_bf16 v[6:9], v[80:83], v[120:123], v[6:9]
	v_mfma_f32_16x16x32_bf16 v[88:91], v[14:17], v[92:95], v[88:91]
	v_mfma_f32_16x16x32_bf16 v[68:71], v[14:17], v[108:111], v[68:71]
	v_mfma_f32_16x16x32_bf16 v[72:75], v[80:83], v[108:111], v[72:75]
	s_setprio 0
	s_barrier
	ds_read_b128 v[10:13], v37
	ds_read_b128 v[14:17], v37 offset:1024
	ds_read_b128 v[76:79], v37 offset:2048
	ds_read_b128 v[80:83], v37 offset:3072
	s_add_i32 s20, s13, 0x18180
	s_mov_b32 m0, s71
	ds_read_b128 v[84:87], v112
	ds_read_b128 v[92:95], v112 offset:1024
	ds_read_b128 v[96:99], v112 offset:2048
	ds_read_b128 v[100:103], v112 offset:3072
	ds_read_b128 v[104:107], v112 offset:4096
	ds_read_b128 v[108:111], v112 offset:5120
	ds_read_b128 v[116:119], v112 offset:6144
	ds_read_b128 v[120:123], v112 offset:7168
	buffer_load_dwordx4 v0, s[36:39], s20 offen lds
	s_mov_b32 m0, s14
	s_nop 0
	buffer_load_dwordx4 v35, s[36:39], s20 offen lds
	s_waitcnt vmcnt(8)
	s_waitcnt lgkmcnt(0)
	s_barrier
	s_setprio 1
	s_waitcnt lgkmcnt(7)
	v_mfma_f32_16x16x32_bf16 v[54:57], v[10:13], v[84:87], v[54:57]
	v_mfma_f32_16x16x32_bf16 v[18:21], v[76:79], v[84:87], v[18:21]
	s_waitcnt lgkmcnt(5)
	v_mfma_f32_16x16x32_bf16 v[22:25], v[10:13], v[96:99], v[22:25]
	v_mfma_f32_16x16x32_bf16 v[26:29], v[76:79], v[96:99], v[26:29]
	s_waitcnt lgkmcnt(3)
	v_mfma_f32_16x16x32_bf16 v[30:33], v[10:13], v[104:107], v[30:33]
	v_mfma_f32_16x16x32_bf16 v[38:41], v[76:79], v[104:107], v[38:41]
	s_waitcnt lgkmcnt(1)
	v_mfma_f32_16x16x32_bf16 v[42:45], v[10:13], v[116:119], v[42:45]
	v_mfma_f32_16x16x32_bf16 v[46:49], v[76:79], v[116:119], v[46:49]
	v_mfma_f32_16x16x32_bf16 v[54:57], v[14:17], v[92:95], v[54:57]
	v_mfma_f32_16x16x32_bf16 v[18:21], v[80:83], v[92:95], v[18:21]
	v_mfma_f32_16x16x32_bf16 v[22:25], v[14:17], v[100:103], v[22:25]
	v_mfma_f32_16x16x32_bf16 v[26:29], v[80:83], v[100:103], v[26:29]
	v_mfma_f32_16x16x32_bf16 v[30:33], v[14:17], v[108:111], v[30:33]
	v_mfma_f32_16x16x32_bf16 v[38:41], v[80:83], v[108:111], v[38:41]
	s_waitcnt lgkmcnt(0)
	v_mfma_f32_16x16x32_bf16 v[42:45], v[14:17], v[120:123], v[42:45]
	v_mfma_f32_16x16x32_bf16 v[46:49], v[80:83], v[120:123], v[46:49]
	s_setprio 0
	s_barrier
	s_mov_b32 m0, s34
	ds_read_b128 v[84:87], v112 offset:16384
	ds_read_b128 v[92:95], v112 offset:17408
	ds_read_b128 v[96:99], v112 offset:18432
	ds_read_b128 v[100:103], v112 offset:19456
	ds_read_b128 v[104:107], v112 offset:20480
	ds_read_b128 v[108:111], v112 offset:21504
	ds_read_b128 v[116:119], v112 offset:22528
	ds_read_b128 v[120:123], v112 offset:23552
	buffer_load_dwordx4 v34, s[84:87], 0 offen lds
	s_mov_b32 m0, s50
	s_mov_b32 s14, 0x10000
	buffer_load_dwordx4 v36, s[84:87], 0 offen lds
	s_mov_b32 m0, s52
	s_nop 0
	buffer_load_dwordx4 v34, s[84:87], s14 offen lds
	s_mov_b32 m0, s56
	s_nop 0
	buffer_load_dwordx4 v36, s[84:87], s14 offen lds
	s_mov_b32 m0, s31
	s_nop 0
	buffer_load_dwordx4 v0, s[36:39], s13 offen lds
	s_mov_b32 m0, s65
	s_nop 0
	buffer_load_dwordx4 v35, s[36:39], s13 offen lds
	s_waitcnt vmcnt(8)
	s_waitcnt lgkmcnt(0)
	s_barrier
; #define PG8_STAGE(bufoff, goff, voff) do { _Pragma("unroll") for (int _i = 0; _i < 2; ++_i) \
;         __builtin_amdgcn_raw_ptr_buffer_load_lds(R_##voff, (LAS void*)(lds + (bufoff) + ldsw + _i * 8192), 16, (int)(voff)[_i], (int)(goff), 0, 0); } while (0)
; #define PG8_WAIT_V(n) asm volatile("s_waitcnt vmcnt(" #n ")" ::: "memory")
; #define PG8_WAIT_L(n) asm volatile("s_waitcnt lgkmcnt(" #n ")" ::: "memory")
; #define PG8_BAR __builtin_amdgcn_s_barrier()
; #define PG8_SCHED __builtin_amdgcn_sched_barrier(0)
; template <class Epi, class Sched, bool ALIGN_EPI, bool SP2>
; __device__ __forceinline__ void gemm_phase(LAS unsigned char* lds, const Gemm g, const Sched& S, const Epi& E, int tid_in) {
;     ...
;             PG8_WAIT_V(8); PG8_WAIT_L(0); PG8_BAR; PG8_MMA(1, 0, At, B0); PG8_MMA(1, 1, At, B1); PG8_BAR; PG8_SCHED;
;             PG8_LDB(B0, 1, 0); PG8_LDB(B1, 1, 1); PG8_SCHED; PG8_LDA(At, 1, 0); PG8_STAGE(PG8_SA(0, 1), a2 + hstepA, voffA);
;             PG8_WAIT_V(8); PG8_WAIT_L(0); PG8_BAR; PG8_MMA(0, 0, At, B0); PG8_MMA(0, 1, At, B1); PG8_BAR; PG8_SCHED;
;             PG8_LDA(At, 1, 1); PG8_STAGE(PG8_SB(1, 0), b3, voffB); PG8_STAGE(PG8_SB(1, 1), b3 + hstepB, voffB); PG8_STAGE(PG8_SA(1, 0), a3, voffA);
;             PG8_WAIT_V(8); PG8_WAIT_L(0); PG8_BAR; PG8_MMA(1, 0, At, B0); PG8_MMA(1, 1, At, B1); PG8_BAR; PG8_SCHED;
;     ...
;     PG8_WAIT_V(0);
;     if constexpr (!ALIGN_EPI) { if (wr == 0) PG8_BAR; }
;     PG8_BAR;
	s_setprio 1
	s_waitcnt lgkmcnt(7)
	v_mfma_f32_16x16x32_bf16 v[50:53], v[76:79], v[84:87], v[50:53]
	s_waitcnt lgkmcnt(5)
	v_mfma_f32_16x16x32_bf16 v[58:61], v[10:13], v[96:99], v[58:61]
	v_mfma_f32_16x16x32_bf16 v[62:65], v[76:79], v[96:99], v[62:65]
	s_waitcnt lgkmcnt(1)
	v_mfma_f32_16x16x32_bf16 v[2:5], v[10:13], v[116:119], v[2:5]
	v_mfma_f32_16x16x32_bf16 v[88:91], v[10:13], v[84:87], v[88:91]
	v_mfma_f32_16x16x32_bf16 v[50:53], v[80:83], v[92:95], v[50:53]
	v_mfma_f32_16x16x32_bf16 v[58:61], v[14:17], v[100:103], v[58:61]
	v_mfma_f32_16x16x32_bf16 v[62:65], v[80:83], v[100:103], v[62:65]
	v_mfma_f32_16x16x32_bf16 v[68:71], v[10:13], v[104:107], v[68:71]
	v_mfma_f32_16x16x32_bf16 v[72:75], v[76:79], v[104:107], v[72:75]
	s_waitcnt lgkmcnt(0)
	v_mfma_f32_16x16x32_bf16 v[84:87], v[14:17], v[120:123], v[2:5]
	v_mfma_f32_16x16x32_bf16 v[2:5], v[76:79], v[116:119], v[6:9]
	v_mfma_f32_16x16x32_bf16 v[88:91], v[14:17], v[92:95], v[88:91]
	v_mfma_f32_16x16x32_bf16 v[68:71], v[14:17], v[108:111], v[68:71]
	v_mfma_f32_16x16x32_bf16 v[72:75], v[80:83], v[108:111], v[72:75]
	v_mfma_f32_16x16x32_bf16 v[76:79], v[80:83], v[120:123], v[2:5]
	s_setprio 0
	s_barrier
	ds_read_b128 v[80:83], v113
	ds_read_b128 v[92:95], v113 offset:1024
	ds_read_b128 v[96:99], v113 offset:2048
	ds_read_b128 v[100:103], v113 offset:3072
	s_mov_b32 m0, s11
	ds_read_b128 v[6:9], v112 offset:32768
	ds_read_b128 v[10:13], v112 offset:33792
	ds_read_b128 v[14:17], v112 offset:34816
	ds_read_b128 v[104:107], v112 offset:35840
	ds_read_b128 v[108:111], v112 offset:36864
	ds_read_b128 v[116:119], v112 offset:37888
	ds_read_b128 v[120:123], v112 offset:38912
	ds_read_b128 v[124:127], v112 offset:39936
	buffer_load_dwordx4 v0, s[36:39], s10 offen lds
	s_mov_b32 m0, s30
	s_nop 0
	buffer_load_dwordx4 v35, s[36:39], s10 offen lds
	s_waitcnt vmcnt(8)
	s_waitcnt lgkmcnt(0)
	s_barrier
	s_setprio 1
	s_waitcnt lgkmcnt(7)
	v_mfma_f32_16x16x32_bf16 v[2:5], v[80:83], v[6:9], v[54:57]
	v_mfma_f32_16x16x32_bf16 v[6:9], v[96:99], v[6:9], v[18:21]
	s_waitcnt lgkmcnt(6)
	v_mfma_f32_16x16x32_bf16 v[2:5], v[92:95], v[10:13], v[2:5]
	v_mfma_f32_16x16x32_bf16 v[6:9], v[100:103], v[10:13], v[6:9]
	s_waitcnt lgkmcnt(5)
	v_mfma_f32_16x16x32_bf16 v[10:13], v[80:83], v[14:17], v[22:25]
	v_mfma_f32_16x16x32_bf16 v[14:17], v[96:99], v[14:17], v[26:29]
	s_waitcnt lgkmcnt(3)
	v_mfma_f32_16x16x32_bf16 v[18:21], v[80:83], v[108:111], v[30:33]
	v_mfma_f32_16x16x32_bf16 v[22:25], v[96:99], v[108:111], v[38:41]
	s_waitcnt lgkmcnt(1)
	v_mfma_f32_16x16x32_bf16 v[26:29], v[80:83], v[120:123], v[42:45]
	v_mfma_f32_16x16x32_bf16 v[30:33], v[96:99], v[120:123], v[46:49]
	v_mfma_f32_16x16x32_bf16 v[10:13], v[92:95], v[104:107], v[10:13]
	v_mfma_f32_16x16x32_bf16 v[14:17], v[100:103], v[104:107], v[14:17]
	v_mfma_f32_16x16x32_bf16 v[18:21], v[92:95], v[116:119], v[18:21]
	v_mfma_f32_16x16x32_bf16 v[22:25], v[100:103], v[116:119], v[22:25]
	s_waitcnt lgkmcnt(0)
	v_mfma_f32_16x16x32_bf16 v[26:29], v[92:95], v[124:127], v[26:29]
	v_mfma_f32_16x16x32_bf16 v[30:33], v[100:103], v[124:127], v[30:33]
	s_setprio 0
	s_barrier
	s_mov_b32 m0, s57
	ds_read_b128 v[38:41], v112 offset:49152
	ds_read_b128 v[42:45], v112 offset:50176
	ds_read_b128 v[46:49], v112 offset:51200
	ds_read_b128 v[54:57], v112 offset:52224
	ds_read_b128 v[104:107], v112 offset:53248
	ds_read_b128 v[108:111], v112 offset:54272
	ds_read_b128 v[116:119], v112 offset:55296
	ds_read_b128 v[120:123], v112 offset:56320
	buffer_load_dwordx4 v34, s[84:87], s72 offen lds
	s_mov_b32 m0, s67
	s_movk_i32 s11, 0x80
	buffer_load_dwordx4 v36, s[84:87], s72 offen lds
	s_mov_b32 m0, s69
	s_nop 0
	buffer_load_dwordx4 v34, s[84:87], s73 offen lds
	s_mov_b32 m0, s70
	s_nop 0
	buffer_load_dwordx4 v36, s[84:87], s73 offen lds
	s_mov_b32 m0, s66
	s_nop 0
	buffer_load_dwordx4 v0, s[36:39], s12 offen lds
	s_mov_b32 m0, s68
	s_nop 0
	buffer_load_dwordx4 v35, s[36:39], s12 offen lds
	s_waitcnt vmcnt(8)
	s_waitcnt lgkmcnt(0)
	s_barrier
	s_setprio 1
	s_waitcnt lgkmcnt(7)
	v_mfma_f32_16x16x32_bf16 v[34:37], v[80:83], v[38:41], v[88:91]
	v_mfma_f32_16x16x32_bf16 v[38:41], v[96:99], v[38:41], v[50:53]
	s_waitcnt lgkmcnt(6)
	v_mfma_f32_16x16x32_bf16 v[34:37], v[92:95], v[42:45], v[34:37]
	v_mfma_f32_16x16x32_bf16 v[38:41], v[100:103], v[42:45], v[38:41]
	s_waitcnt lgkmcnt(5)
	v_mfma_f32_16x16x32_bf16 v[42:45], v[80:83], v[46:49], v[58:61]
	v_mfma_f32_16x16x32_bf16 v[46:49], v[96:99], v[46:49], v[62:65]
	s_waitcnt lgkmcnt(4)
	v_mfma_f32_16x16x32_bf16 v[42:45], v[92:95], v[54:57], v[42:45]
	v_mfma_f32_16x16x32_bf16 v[46:49], v[100:103], v[54:57], v[46:49]
	s_waitcnt lgkmcnt(3)
	v_mfma_f32_16x16x32_bf16 v[50:53], v[80:83], v[104:107], v[68:71]
	v_mfma_f32_16x16x32_bf16 v[54:57], v[96:99], v[104:107], v[72:75]
	s_waitcnt lgkmcnt(1)
	v_mfma_f32_16x16x32_bf16 v[58:61], v[80:83], v[116:119], v[84:87]
	v_mfma_f32_16x16x32_bf16 v[62:65], v[96:99], v[116:119], v[76:79]
	v_mfma_f32_16x16x32_bf16 v[50:53], v[92:95], v[108:111], v[50:53]
	v_mfma_f32_16x16x32_bf16 v[54:57], v[100:103], v[108:111], v[54:57]
	s_waitcnt lgkmcnt(0)
	v_mfma_f32_16x16x32_bf16 v[58:61], v[92:95], v[120:123], v[58:61]
	v_mfma_f32_16x16x32_bf16 v[62:65], v[100:103], v[120:123], v[62:65]
	s_setprio 0
	s_barrier
	s_waitcnt vmcnt(0)
	s_cmpk_gt_u32 s3, 0xff
	s_cbranch_scc1 .LBB0_505
	s_barrier

;     __device__ __forceinline__ bool next(int i, Unit& u) const { if (i) return false; u.pm = pm; u.pn = pn; return true; }
; #define PG8_BAR __builtin_amdgcn_s_barrier()
; template <class Epi, class Sched, bool ALIGN_EPI, bool SP2>
; __device__ __forceinline__ void gemm_phase(LAS unsigned char* lds, const Gemm g, const Sched& S, const Epi& E, int tid_in) {
;     ...
;         PG8_STAGE(PG8_SB(0, 0), cB, voffB); PG8_STAGE(PG8_SB(0, 1), cB + hstepB, voffB); PG8_STAGE(PG8_SA(0, 0), cA, voffA); PG8_STAGE(PG8_SA(0, 1), cA + hstepA, voffA);
;         if (wr == 1) PG8_BAR;
;         PG8_WAIT_V(2); PG8_BAR;
;         PG8_STAGE(PG8_SB(1, 0), cB + kstep, voffB); PG8_STAGE(PG8_SA(1, 0), cA + kstep, voffA); PG8_STAGE(PG8_SB(1, 1), cB + hstepB + kstep, voffB);
;         PG8_WAIT_V(6); PG8_BAR;
;     } else {
;         PG8_STAGE(PG8_SB(0, 0), cB, voffB); PG8_STAGE(PG8_SA(0, 0), cA, voffA); PG8_STAGE(PG8_SB(0, 1), cB + hstepB, voffB); PG8_STAGE(PG8_SA(0, 1), cA + hstepA, voffA);
;         if (wr == 1) PG8_BAR;
;         PG8_WAIT_V(4); PG8_BAR;
;         PG8_STAGE(PG8_SB(1, 0), cB + kstep, voffB); PG8_STAGE(PG8_SA(1, 0), cA + kstep, voffA); PG8_STAGE(PG8_SB(1, 1), cB + hstepB + kstep, voffB);
;         PG8_WAIT_V(6); PG8_BAR;
;     }
;     for (;;) {
;         const bool has_next = S.next(ui + 1, nxt);
;         const unsigned nA = has_next ? (unsigned)nxt.pm * tstepA : cA, nB = has_next ? (unsigned)nxt.pn * tstepB : cB;
;         for (int t = 0; t < nt; t += 2) {
;             const bool last = (t == nt - 2);
;             const unsigned a1 = cA + (unsigned)(t + 1) * kstep;
;             const unsigned a2 = last ? nA : cA + (unsigned)(t + 2) * kstep, b2 = last ? nB : cB + (unsigned)(t + 2) * kstep;
;             const unsigned a3 = a2 + kstep, b3 = b2 + kstep;
;             if constexpr (Epi::MIDK) { if (t == g.kmid) E.midk(acc, wr, fr); }
;             if constexpr (SP2) {
;             PG8_LDB(B0, 0, 0); PG8_LDB(B1, 0, 1); PG8_SCHED; PG8_LDA(At, 0, 0); PG8_STAGE(PG8_SA(1, 1), a1 + hstepA, voffA);
;             PG8_WAIT_V(8); PG8_WAIT_L(0); PG8_BAR; PG8_MMA(0, 0, At, B0); PG8_MMA(0, 1, At, B1); PG8_BAR; PG8_SCHED;
;             PG8_LDA(At, 0, 1); PG8_STAGE(PG8_SB(0, 0), b2, voffB); PG8_STAGE(PG8_SB(0, 1), b2 + hstepB, voffB); PG8_STAGE(PG8_SA(0, 0), a2, voffA);
;             PG8_WAIT_V(8); PG8_WAIT_L(0); PG8_BAR; PG8_MMA(1, 0, At, B0); PG8_MMA(1, 1, At, B1); PG8_BAR; PG8_SCHED;
.LBB0_512:
	v_readlane_b32 s66, v255, 42
	v_readlane_b32 s67, v255, 43
	s_waitcnt lgkmcnt(0)
	s_add_u32 s11, s2, s66
	s_addc_u32 s34, s3, s67
	s_lshl_b32 s2, s17, 4
	s_ashr_i32 s3, s2, 31
	s_lshl_b64 s[66:67], s[2:3], 2
	s_add_u32 s66, s11, s66
	v_bfe_u32 v11, v5, 4, 2
	s_addc_u32 s67, s34, s67
	s_and_b32 s5, s5, 3
	v_and_b32_e32 v10, 15, v5
	v_lshlrev_b32_e32 v6, 4, v11
	v_lshlrev_b32_e32 v5, 2, v5
	s_add_i32 s50, s25, s14
	v_lshl_or_b32 v6, v10, 6, v6
	v_and_b32_e32 v5, 32, v5
	s_lshl_b32 s17, s5, 12
	s_mov_b32 m0, s50
	s_movk_i32 s74, 0x80
	s_add_i32 s52, s50, 0x2000
	s_lshl_b32 s11, s15, 6
	s_lshl_b32 s15, s15, 13
	v_bitop3_b32 v12, v6, s17, v5 bitop3:0xde
	s_waitcnt vmcnt(2)
	s_barrier
	buffer_load_dwordx4 v2, s[84:87], s74 offen lds
	s_mov_b32 m0, s52
	s_add_i32 s17, s56, 0x8000
	v_bitop3_b32 v5, v6, s15, v5 bitop3:0xde
	buffer_load_dwordx4 v4, s[84:87], s74 offen lds
	s_mov_b32 m0, s17
	s_add_i32 s34, s56, 0xa000
	s_add_i32 s15, 0, 0x1c000
	buffer_load_dwordx4 v0, s[36:39], s12 offen lds
	s_mov_b32 m0, s34
	s_add_i32 s57, s15, s14
	buffer_load_dwordx4 v3, s[36:39], s12 offen lds
	s_mov_b32 m0, s57
	s_movk_i32 s75, 0x6080
	s_add_i32 s65, s57, 0x2000
	buffer_load_dwordx4 v2, s[84:87], s75 offen lds
	s_mov_b32 m0, s65
	v_add_u32_e32 v6, 0, v12
	buffer_load_dwordx4 v4, s[84:87], s75 offen lds
	v_add_u32_e32 v9, 0x10000, v6
	s_waitcnt vmcnt(6)
	s_barrier
	v_add_u32_e32 v8, 0x14000, v6
	v_add_u32_e32 v7, s25, v12
	v_add_u32_e32 v6, s15, v12
	ds_read_b128 v[12:15], v9
	ds_read_b128 v[16:19], v9 offset:1024
	ds_read_b128 v[20:23], v9 offset:2048
	ds_read_b128 v[24:27], v9 offset:3072
	ds_read_b128 v[28:31], v8
	ds_read_b128 v[32:35], v8 offset:1024
	ds_read_b128 v[36:39], v8 offset:2048
	ds_read_b128 v[40:43], v8 offset:3072
	v_add_u32_e32 v5, 0, v5
	s_add_i32 s73, s56, 0xc000
	s_mov_b32 m0, s73
	s_add_i32 s25, s56, 0xe000
	ds_read_b128 v[44:47], v5
	ds_read_b128 v[48:51], v5 offset:1024
	ds_read_b128 v[52:55], v5 offset:2048
	ds_read_b128 v[56:59], v5 offset:3072
	ds_read_b128 v[60:63], v5 offset:4096
	ds_read_b128 v[64:67], v5 offset:5120
	ds_read_b128 v[68:71], v5 offset:6144
	ds_read_b128 v[72:75], v5 offset:7168
	buffer_load_dwordx4 v0, s[36:39], s27 offen lds
	s_mov_b32 m0, s25
	s_nop 0
	buffer_load_dwordx4 v3, s[36:39], s27 offen lds
	s_waitcnt vmcnt(8)
	s_waitcnt lgkmcnt(0)
	s_barrier
	s_setprio 1
	s_waitcnt lgkmcnt(7)
	v_mfma_f32_16x16x32_bf16 v[76:79], v[12:15], v[44:47], 0
	v_mfma_f32_16x16x32_bf16 v[80:83], v[20:23], v[44:47], 0
	s_waitcnt lgkmcnt(5)
	v_mfma_f32_16x16x32_bf16 v[84:87], v[12:15], v[52:55], 0
	v_mfma_f32_16x16x32_bf16 v[88:91], v[20:23], v[52:55], 0
	s_waitcnt lgkmcnt(3)
	v_mfma_f32_16x16x32_bf16 v[92:95], v[12:15], v[60:63], 0
	v_mfma_f32_16x16x32_bf16 v[96:99], v[20:23], v[60:63], 0
	s_waitcnt lgkmcnt(1)
	v_mfma_f32_16x16x32_bf16 v[100:103], v[12:15], v[68:71], 0
	v_mfma_f32_16x16x32_bf16 v[104:107], v[20:23], v[68:71], 0
	v_mfma_f32_16x16x32_bf16 v[76:79], v[16:19], v[48:51], v[76:79]
	v_mfma_f32_16x16x32_bf16 v[80:83], v[24:27], v[48:51], v[80:83]
	v_mfma_f32_16x16x32_bf16 v[84:87], v[16:19], v[56:59], v[84:87]
	v_mfma_f32_16x16x32_bf16 v[88:91], v[24:27], v[56:59], v[88:91]
	v_mfma_f32_16x16x32_bf16 v[92:95], v[16:19], v[64:67], v[92:95]
	v_mfma_f32_16x16x32_bf16 v[96:99], v[24:27], v[64:67], v[96:99]
	s_waitcnt lgkmcnt(0)
	v_mfma_f32_16x16x32_bf16 v[100:103], v[16:19], v[72:75], v[100:103]
	v_mfma_f32_16x16x32_bf16 v[104:107], v[24:27], v[72:75], v[104:107]
	v_mfma_f32_16x16x32_bf16 v[108:111], v[28:31], v[44:47], 0
	v_mfma_f32_16x16x32_bf16 v[44:47], v[36:39], v[44:47], 0
	v_mfma_f32_16x16x32_bf16 v[108:111], v[32:35], v[48:51], v[108:111]
	v_mfma_f32_16x16x32_bf16 v[44:47], v[40:43], v[48:51], v[44:47]
	v_mfma_f32_16x16x32_bf16 v[48:51], v[28:31], v[52:55], 0
	v_mfma_f32_16x16x32_bf16 v[52:55], v[36:39], v[52:55], 0
	v_mfma_f32_16x16x32_bf16 v[48:51], v[32:35], v[56:59], v[48:51]
	v_mfma_f32_16x16x32_bf16 v[52:55], v[40:43], v[56:59], v[52:55]
	v_mfma_f32_16x16x32_bf16 v[56:59], v[28:31], v[60:63], 0
	v_mfma_f32_16x16x32_bf16 v[60:63], v[36:39], v[60:63], 0
	v_mfma_f32_16x16x32_bf16 v[56:59], v[32:35], v[64:67], v[56:59]
	v_mfma_f32_16x16x32_bf16 v[60:63], v[40:43], v[64:67], v[60:63]
	v_mfma_f32_16x16x32_bf16 v[64:67], v[28:31], v[68:71], 0
	v_mfma_f32_16x16x32_bf16 v[68:71], v[36:39], v[68:71], 0
	v_mfma_f32_16x16x32_bf16 v[64:67], v[32:35], v[72:75], v[64:67]
	v_mfma_f32_16x16x32_bf16 v[68:71], v[40:43], v[72:75], v[68:71]
	s_setprio 0
	s_barrier
	s_mov_b32 m0, s68
	s_movk_i32 s14, 0x100
	ds_read_b128 v[72:75], v5 offset:16384
	ds_read_b128 v[116:119], v5 offset:17408
	ds_read_b128 v[120:123], v5 offset:18432
	ds_read_b128 v[124:127], v5 offset:19456
	ds_read_b128 v[128:131], v5 offset:20480
	ds_read_b128 v[132:135], v5 offset:21504
	ds_read_b128 v[136:139], v5 offset:22528
	ds_read_b128 v[140:143], v5 offset:23552
	buffer_load_dwordx4 v2, s[84:87], s14 offen lds
	s_mov_b32 m0, s69
	s_nop 0
	buffer_load_dwordx4 v4, s[84:87], s14 offen lds
	s_mov_b32 m0, s70
	s_movk_i32 s14, 0x6100
	buffer_load_dwordx4 v2, s[84:87], s14 offen lds
	s_mov_b32 m0, s71
	s_nop 0
	buffer_load_dwordx4 v4, s[84:87], s14 offen lds
	s_mov_b32 m0, s56
	s_nop 0
	buffer_load_dwordx4 v0, s[36:39], s19 offen lds
	s_mov_b32 m0, s72
	s_nop 0
	buffer_load_dwordx4 v3, s[36:39], s19 offen lds
	s_waitcnt vmcnt(8)
	s_waitcnt lgkmcnt(0)
	s_barrier
; #define PG8_STAGE(bufoff, goff, voff) do { _Pragma("unroll") for (int _i = 0; _i < 2; ++_i) \
;         __builtin_amdgcn_raw_ptr_buffer_load_lds(R_##voff, (LAS void*)(lds + (bufoff) + ldsw + _i * 8192), 16, (int)(voff)[_i], (int)(goff), 0, 0); } while (0)
; #define PG8_WAIT_V(n) asm volatile("s_waitcnt vmcnt(" #n ")" ::: "memory")
; #define PG8_WAIT_L(n) asm volatile("s_waitcnt lgkmcnt(" #n ")" ::: "memory")
; #define PG8_BAR __builtin_amdgcn_s_barrier()
; #define PG8_SCHED __builtin_amdgcn_sched_barrier(0)
; template <class Epi, class Sched, bool ALIGN_EPI, bool SP2>
; __device__ __forceinline__ void gemm_phase(LAS unsigned char* lds, const Gemm g, const Sched& S, const Epi& E, int tid_in) {
;     ...
;             PG8_WAIT_V(8); PG8_WAIT_L(0); PG8_BAR; PG8_MMA(1, 0, At, B0); PG8_MMA(1, 1, At, B1); PG8_BAR; PG8_SCHED;
;             PG8_LDB(B0, 1, 0); PG8_LDB(B1, 1, 1); PG8_SCHED; PG8_LDA(At, 1, 0); PG8_STAGE(PG8_SA(0, 1), a2 + hstepA, voffA);
;             PG8_WAIT_V(8); PG8_WAIT_L(0); PG8_BAR; PG8_MMA(0, 0, At, B0); PG8_MMA(0, 1, At, B1); PG8_BAR; PG8_SCHED;
	s_setprio 1
	s_waitcnt lgkmcnt(7)
	v_mfma_f32_16x16x32_bf16 v[144:147], v[12:15], v[72:75], 0
	s_waitcnt lgkmcnt(5)
	v_mfma_f32_16x16x32_bf16 v[152:155], v[12:15], v[120:123], 0
	s_waitcnt lgkmcnt(3)
	v_mfma_f32_16x16x32_bf16 v[160:163], v[12:15], v[128:131], 0
	s_waitcnt lgkmcnt(1)
	v_mfma_f32_16x16x32_bf16 v[12:15], v[12:15], v[136:139], 0
	v_mfma_f32_16x16x32_bf16 v[144:147], v[16:19], v[116:119], v[144:147]
	v_mfma_f32_16x16x32_bf16 v[148:151], v[20:23], v[72:75], 0
	v_mfma_f32_16x16x32_bf16 v[152:155], v[16:19], v[124:127], v[152:155]
	v_mfma_f32_16x16x32_bf16 v[156:159], v[20:23], v[120:123], 0
	v_mfma_f32_16x16x32_bf16 v[160:163], v[16:19], v[132:135], v[160:163]
	v_mfma_f32_16x16x32_bf16 v[164:167], v[20:23], v[128:131], 0
	s_waitcnt lgkmcnt(0)
	v_mfma_f32_16x16x32_bf16 v[12:15], v[16:19], v[140:143], v[12:15]
	v_mfma_f32_16x16x32_bf16 v[16:19], v[20:23], v[136:139], 0
	v_mfma_f32_16x16x32_bf16 v[148:151], v[24:27], v[116:119], v[148:151]
	v_mfma_f32_16x16x32_bf16 v[156:159], v[24:27], v[124:127], v[156:159]
	v_mfma_f32_16x16x32_bf16 v[164:167], v[24:27], v[132:135], v[164:167]
	v_mfma_f32_16x16x32_bf16 v[16:19], v[24:27], v[140:143], v[16:19]
	v_mfma_f32_16x16x32_bf16 v[20:23], v[28:31], v[72:75], 0
	v_mfma_f32_16x16x32_bf16 v[24:27], v[36:39], v[72:75], 0
	v_mfma_f32_16x16x32_bf16 v[20:23], v[32:35], v[116:119], v[20:23]
	v_mfma_f32_16x16x32_bf16 v[24:27], v[40:43], v[116:119], v[24:27]
	v_mfma_f32_16x16x32_bf16 v[72:75], v[28:31], v[120:123], 0
	v_mfma_f32_16x16x32_bf16 v[116:119], v[36:39], v[120:123], 0
	v_mfma_f32_16x16x32_bf16 v[120:123], v[28:31], v[128:131], 0
	v_mfma_f32_16x16x32_bf16 v[28:31], v[28:31], v[136:139], 0
	v_mfma_f32_16x16x32_bf16 v[72:75], v[32:35], v[124:127], v[72:75]
	v_mfma_f32_16x16x32_bf16 v[116:119], v[40:43], v[124:127], v[116:119]
	v_mfma_f32_16x16x32_bf16 v[120:123], v[32:35], v[132:135], v[120:123]
	v_mfma_f32_16x16x32_bf16 v[124:127], v[36:39], v[128:131], 0
	v_mfma_f32_16x16x32_bf16 v[28:31], v[32:35], v[140:143], v[28:31]
	v_mfma_f32_16x16x32_bf16 v[32:35], v[36:39], v[136:139], 0
	v_mfma_f32_16x16x32_bf16 v[124:127], v[40:43], v[132:135], v[124:127]
	v_mfma_f32_16x16x32_bf16 v[32:35], v[40:43], v[140:143], v[32:35]
	s_setprio 0
	s_barrier
	ds_read_b128 v[36:39], v7
	ds_read_b128 v[40:43], v7 offset:1024
	ds_read_b128 v[128:131], v7 offset:2048
	ds_read_b128 v[132:135], v7 offset:3072
	ds_read_b128 v[136:139], v6
	ds_read_b128 v[140:143], v6 offset:1024
	ds_read_b128 v[168:171], v6 offset:2048
	ds_read_b128 v[172:175], v6 offset:3072
	s_mov_b32 m0, s30
	ds_read_b128 v[176:179], v5 offset:32768
	ds_read_b128 v[180:183], v5 offset:33792
	ds_read_b128 v[184:187], v5 offset:34816
	ds_read_b128 v[188:191], v5 offset:35840
	ds_read_b128 v[192:195], v5 offset:36864
	ds_read_b128 v[196:199], v5 offset:37888
	ds_read_b128 v[200:203], v5 offset:38912
	ds_read_b128 v[204:207], v5 offset:39936
	buffer_load_dwordx4 v0, s[36:39], s29 offen lds
	s_mov_b32 m0, s31
	s_nop 0
	buffer_load_dwordx4 v3, s[36:39], s29 offen lds
	s_waitcnt vmcnt(8)
	s_waitcnt lgkmcnt(0)
	s_barrier
	s_setprio 1
	s_waitcnt lgkmcnt(7)
	v_mfma_f32_16x16x32_bf16 v[76:79], v[36:39], v[176:179], v[76:79]
	v_mfma_f32_16x16x32_bf16 v[80:83], v[128:131], v[176:179], v[80:83]
	s_waitcnt lgkmcnt(5)
	v_mfma_f32_16x16x32_bf16 v[84:87], v[36:39], v[184:187], v[84:87]
	v_mfma_f32_16x16x32_bf16 v[88:91], v[128:131], v[184:187], v[88:91]
	s_waitcnt lgkmcnt(3)
	v_mfma_f32_16x16x32_bf16 v[92:95], v[36:39], v[192:195], v[92:95]
	v_mfma_f32_16x16x32_bf16 v[96:99], v[128:131], v[192:195], v[96:99]
	s_waitcnt lgkmcnt(1)
	v_mfma_f32_16x16x32_bf16 v[100:103], v[36:39], v[200:203], v[100:103]
	v_mfma_f32_16x16x32_bf16 v[104:107], v[128:131], v[200:203], v[104:107]
	v_mfma_f32_16x16x32_bf16 v[76:79], v[40:43], v[180:183], v[76:79]
	v_mfma_f32_16x16x32_bf16 v[80:83], v[132:135], v[180:183], v[80:83]
	v_mfma_f32_16x16x32_bf16 v[84:87], v[40:43], v[188:191], v[84:87]
	v_mfma_f32_16x16x32_bf16 v[88:91], v[132:135], v[188:191], v[88:91]
	v_mfma_f32_16x16x32_bf16 v[92:95], v[40:43], v[196:199], v[92:95]
	v_mfma_f32_16x16x32_bf16 v[96:99], v[132:135], v[196:199], v[96:99]
	s_waitcnt lgkmcnt(0)
	v_mfma_f32_16x16x32_bf16 v[100:103], v[40:43], v[204:207], v[100:103]
	v_mfma_f32_16x16x32_bf16 v[104:107], v[132:135], v[204:207], v[104:107]
	v_mfma_f32_16x16x32_bf16 v[108:111], v[136:139], v[176:179], v[108:111]
	v_mfma_f32_16x16x32_bf16 v[44:47], v[168:171], v[176:179], v[44:47]
	v_mfma_f32_16x16x32_bf16 v[48:51], v[136:139], v[184:187], v[48:51]
	v_mfma_f32_16x16x32_bf16 v[52:55], v[168:171], v[184:187], v[52:55]
	v_mfma_f32_16x16x32_bf16 v[56:59], v[136:139], v[192:195], v[56:59]
	v_mfma_f32_16x16x32_bf16 v[60:63], v[168:171], v[192:195], v[60:63]
	v_mfma_f32_16x16x32_bf16 v[64:67], v[136:139], v[200:203], v[64:67]
	v_mfma_f32_16x16x32_bf16 v[68:71], v[168:171], v[200:203], v[68:71]
	v_mfma_f32_16x16x32_bf16 v[108:111], v[140:143], v[180:183], v[108:111]
	v_mfma_f32_16x16x32_bf16 v[44:47], v[172:175], v[180:183], v[44:47]
	v_mfma_f32_16x16x32_bf16 v[48:51], v[140:143], v[188:191], v[48:51]
	v_mfma_f32_16x16x32_bf16 v[52:55], v[172:175], v[188:191], v[52:55]
	v_mfma_f32_16x16x32_bf16 v[56:59], v[140:143], v[196:199], v[56:59]
	v_mfma_f32_16x16x32_bf16 v[60:63], v[172:175], v[196:199], v[60:63]
	v_mfma_f32_16x16x32_bf16 v[64:67], v[140:143], v[204:207], v[64:67]
	v_mfma_f32_16x16x32_bf16 v[68:71], v[172:175], v[204:207], v[68:71]
	s_setprio 0
	s_barrier
; #define PG8_STAGE(bufoff, goff, voff) do { _Pragma("unroll") for (int _i = 0; _i < 2; ++_i) \
;         __builtin_amdgcn_raw_ptr_buffer_load_lds(R_##voff, (LAS void*)(lds + (bufoff) + ldsw + _i * 8192), 16, (int)(voff)[_i], (int)(goff), 0, 0); } while (0)
; #define PG8_WAIT_V(n) asm volatile("s_waitcnt vmcnt(" #n ")" ::: "memory")
; #define PG8_WAIT_L(n) asm volatile("s_waitcnt lgkmcnt(" #n ")" ::: "memory")
; #define PG8_BAR __builtin_amdgcn_s_barrier()
; #define PG8_SCHED __builtin_amdgcn_sched_barrier(0)
; template <class Epi, class Sched, bool ALIGN_EPI, bool SP2>
; __device__ __forceinline__ void gemm_phase(LAS unsigned char* lds, const Gemm g, const Sched& S, const Epi& E, int tid_in) {
;     ...
;             PG8_WAIT_V(8); PG8_WAIT_L(0); PG8_BAR; PG8_MMA(0, 0, At, B0); PG8_MMA(0, 1, At, B1); PG8_BAR; PG8_SCHED;
;             PG8_LDA(At, 1, 1); PG8_STAGE(PG8_SB(1, 0), b3, voffB); PG8_STAGE(PG8_SB(1, 1), b3 + hstepB, voffB); PG8_STAGE(PG8_SA(1, 0), a3, voffA);
;             PG8_WAIT_V(8); PG8_WAIT_L(0); PG8_BAR; PG8_MMA(1, 0, At, B0); PG8_MMA(1, 1, At, B1); PG8_BAR; PG8_SCHED;
	s_mov_b32 m0, s50
	s_movk_i32 s14, 0x180
	ds_read_b128 v[176:179], v5 offset:49152
	ds_read_b128 v[180:183], v5 offset:50176
	ds_read_b128 v[184:187], v5 offset:51200
	ds_read_b128 v[188:191], v5 offset:52224
	ds_read_b128 v[192:195], v5 offset:53248
	ds_read_b128 v[196:199], v5 offset:54272
	ds_read_b128 v[200:203], v5 offset:55296
	ds_read_b128 v[204:207], v5 offset:56320
	buffer_load_dwordx4 v2, s[84:87], s14 offen lds
	s_mov_b32 m0, s52
	s_nop 0
	buffer_load_dwordx4 v4, s[84:87], s14 offen lds
	s_mov_b32 m0, s57
	s_movk_i32 s14, 0x6180
	buffer_load_dwordx4 v2, s[84:87], s14 offen lds
	s_mov_b32 m0, s65
	s_nop 0
	buffer_load_dwordx4 v4, s[84:87], s14 offen lds
	s_mov_b32 m0, s17
	s_nop 0
	buffer_load_dwordx4 v0, s[36:39], s16 offen lds
	s_mov_b32 m0, s34
	s_nop 0
	buffer_load_dwordx4 v3, s[36:39], s16 offen lds
	s_waitcnt vmcnt(8)
	s_waitcnt lgkmcnt(0)
	s_barrier
	s_setprio 1
	s_waitcnt lgkmcnt(7)
	v_mfma_f32_16x16x32_bf16 v[144:147], v[36:39], v[176:179], v[144:147]
	v_mfma_f32_16x16x32_bf16 v[148:151], v[128:131], v[176:179], v[148:151]
	s_waitcnt lgkmcnt(5)
	v_mfma_f32_16x16x32_bf16 v[152:155], v[36:39], v[184:187], v[152:155]
	v_mfma_f32_16x16x32_bf16 v[156:159], v[128:131], v[184:187], v[156:159]
	s_waitcnt lgkmcnt(3)
	v_mfma_f32_16x16x32_bf16 v[160:163], v[36:39], v[192:195], v[160:163]
	v_mfma_f32_16x16x32_bf16 v[164:167], v[128:131], v[192:195], v[164:167]
	s_waitcnt lgkmcnt(1)
	v_mfma_f32_16x16x32_bf16 v[12:15], v[36:39], v[200:203], v[12:15]
	v_mfma_f32_16x16x32_bf16 v[16:19], v[128:131], v[200:203], v[16:19]
	v_mfma_f32_16x16x32_bf16 v[144:147], v[40:43], v[180:183], v[144:147]
	v_mfma_f32_16x16x32_bf16 v[148:151], v[132:135], v[180:183], v[148:151]
	v_mfma_f32_16x16x32_bf16 v[152:155], v[40:43], v[188:191], v[152:155]
	v_mfma_f32_16x16x32_bf16 v[156:159], v[132:135], v[188:191], v[156:159]
	v_mfma_f32_16x16x32_bf16 v[160:163], v[40:43], v[196:199], v[160:163]
	v_mfma_f32_16x16x32_bf16 v[164:167], v[132:135], v[196:199], v[164:167]
	s_waitcnt lgkmcnt(0)
	v_mfma_f32_16x16x32_bf16 v[12:15], v[40:43], v[204:207], v[12:15]
	v_mfma_f32_16x16x32_bf16 v[16:19], v[132:135], v[204:207], v[16:19]
	v_mfma_f32_16x16x32_bf16 v[20:23], v[136:139], v[176:179], v[20:23]
	v_mfma_f32_16x16x32_bf16 v[24:27], v[168:171], v[176:179], v[24:27]
	v_mfma_f32_16x16x32_bf16 v[36:39], v[136:139], v[184:187], v[72:75]
	v_mfma_f32_16x16x32_bf16 v[40:43], v[168:171], v[184:187], v[116:119]
	v_mfma_f32_16x16x32_bf16 v[72:75], v[136:139], v[192:195], v[120:123]
	v_mfma_f32_16x16x32_bf16 v[116:119], v[168:171], v[192:195], v[124:127]
	v_mfma_f32_16x16x32_bf16 v[28:31], v[136:139], v[200:203], v[28:31]
	v_mfma_f32_16x16x32_bf16 v[32:35], v[168:171], v[200:203], v[32:35]
	v_mfma_f32_16x16x32_bf16 v[20:23], v[140:143], v[180:183], v[20:23]
	v_mfma_f32_16x16x32_bf16 v[24:27], v[172:175], v[180:183], v[24:27]
	v_mfma_f32_16x16x32_bf16 v[36:39], v[140:143], v[188:191], v[36:39]
	v_mfma_f32_16x16x32_bf16 v[40:43], v[172:175], v[188:191], v[40:43]
	v_mfma_f32_16x16x32_bf16 v[72:75], v[140:143], v[196:199], v[72:75]
	v_mfma_f32_16x16x32_bf16 v[116:119], v[172:175], v[196:199], v[116:119]
	v_mfma_f32_16x16x32_bf16 v[28:31], v[140:143], v[204:207], v[28:31]
	v_mfma_f32_16x16x32_bf16 v[32:35], v[172:175], v[204:207], v[32:35]
	s_setprio 0
	s_barrier
	ds_read_b128 v[120:123], v9
	ds_read_b128 v[124:127], v9 offset:1024
	ds_read_b128 v[128:131], v9 offset:2048
	ds_read_b128 v[132:135], v9 offset:3072
	ds_read_b128 v[136:139], v8
	ds_read_b128 v[140:143], v8 offset:1024
	ds_read_b128 v[168:171], v8 offset:2048
	ds_read_b128 v[172:175], v8 offset:3072
	s_or_b32 s14, s13, 0x200
	s_or_b32 s15, s13, 0x280
	s_mov_b32 m0, s73
	ds_read_b128 v[176:179], v5
	ds_read_b128 v[180:183], v5 offset:1024
	ds_read_b128 v[184:187], v5 offset:2048
	ds_read_b128 v[188:191], v5 offset:3072
	ds_read_b128 v[192:195], v5 offset:4096
	ds_read_b128 v[196:199], v5 offset:5120
	ds_read_b128 v[200:203], v5 offset:6144
	ds_read_b128 v[204:207], v5 offset:7168
	buffer_load_dwordx4 v0, s[36:39], s20 offen lds
	s_mov_b32 m0, s25
	s_nop 0
	buffer_load_dwordx4 v3, s[36:39], s20 offen lds
	s_waitcnt vmcnt(8)
	s_waitcnt lgkmcnt(0)
	s_barrier
	s_setprio 1
	s_waitcnt lgkmcnt(7)
	v_mfma_f32_16x16x32_bf16 v[76:79], v[120:123], v[176:179], v[76:79]
	v_mfma_f32_16x16x32_bf16 v[80:83], v[128:131], v[176:179], v[80:83]
	s_waitcnt lgkmcnt(5)
	v_mfma_f32_16x16x32_bf16 v[84:87], v[120:123], v[184:187], v[84:87]
	v_mfma_f32_16x16x32_bf16 v[88:91], v[128:131], v[184:187], v[88:91]
	s_waitcnt lgkmcnt(3)
	v_mfma_f32_16x16x32_bf16 v[92:95], v[120:123], v[192:195], v[92:95]
	v_mfma_f32_16x16x32_bf16 v[96:99], v[128:131], v[192:195], v[96:99]
	s_waitcnt lgkmcnt(1)
	v_mfma_f32_16x16x32_bf16 v[100:103], v[120:123], v[200:203], v[100:103]
	v_mfma_f32_16x16x32_bf16 v[104:107], v[128:131], v[200:203], v[104:107]
	v_mfma_f32_16x16x32_bf16 v[76:79], v[124:127], v[180:183], v[76:79]
	v_mfma_f32_16x16x32_bf16 v[80:83], v[132:135], v[180:183], v[80:83]
	v_mfma_f32_16x16x32_bf16 v[84:87], v[124:127], v[188:191], v[84:87]
	v_mfma_f32_16x16x32_bf16 v[88:91], v[132:135], v[188:191], v[88:91]
	v_mfma_f32_16x16x32_bf16 v[92:95], v[124:127], v[196:199], v[92:95]
	v_mfma_f32_16x16x32_bf16 v[96:99], v[132:135], v[196:199], v[96:99]
	s_waitcnt lgkmcnt(0)
	v_mfma_f32_16x16x32_bf16 v[100:103], v[124:127], v[204:207], v[100:103]
	v_mfma_f32_16x16x32_bf16 v[104:107], v[132:135], v[204:207], v[104:107]
	v_mfma_f32_16x16x32_bf16 v[108:111], v[136:139], v[176:179], v[108:111]
	v_mfma_f32_16x16x32_bf16 v[44:47], v[168:171], v[176:179], v[44:47]
	v_mfma_f32_16x16x32_bf16 v[48:51], v[136:139], v[184:187], v[48:51]
	v_mfma_f32_16x16x32_bf16 v[52:55], v[168:171], v[184:187], v[52:55]
	v_mfma_f32_16x16x32_bf16 v[56:59], v[136:139], v[192:195], v[56:59]
	v_mfma_f32_16x16x32_bf16 v[60:63], v[168:171], v[192:195], v[60:63]
	v_mfma_f32_16x16x32_bf16 v[64:67], v[136:139], v[200:203], v[64:67]
	v_mfma_f32_16x16x32_bf16 v[68:71], v[168:171], v[200:203], v[68:71]
	v_mfma_f32_16x16x32_bf16 v[108:111], v[140:143], v[180:183], v[108:111]
	v_mfma_f32_16x16x32_bf16 v[44:47], v[172:175], v[180:183], v[44:47]
	v_mfma_f32_16x16x32_bf16 v[48:51], v[140:143], v[188:191], v[48:51]
	v_mfma_f32_16x16x32_bf16 v[52:55], v[172:175], v[188:191], v[52:55]
	v_mfma_f32_16x16x32_bf16 v[56:59], v[140:143], v[196:199], v[56:59]
	v_mfma_f32_16x16x32_bf16 v[60:63], v[172:175], v[196:199], v[60:63]
	v_mfma_f32_16x16x32_bf16 v[64:67], v[140:143], v[204:207], v[64:67]
	v_mfma_f32_16x16x32_bf16 v[68:71], v[172:175], v[204:207], v[68:71]
	s_setprio 0
	s_barrier
; #define PG8_STAGE(bufoff, goff, voff) do { _Pragma("unroll") for (int _i = 0; _i < 2; ++_i) \
;         __builtin_amdgcn_raw_ptr_buffer_load_lds(R_##voff, (LAS void*)(lds + (bufoff) + ldsw + _i * 8192), 16, (int)(voff)[_i], (int)(goff), 0, 0); } while (0)
; #define PG8_WAIT_V(n) asm volatile("s_waitcnt vmcnt(" #n ")" ::: "memory")
; #define PG8_WAIT_L(n) asm volatile("s_waitcnt lgkmcnt(" #n ")" ::: "memory")
; #define PG8_BAR __builtin_amdgcn_s_barrier()
; #define PG8_SCHED __builtin_amdgcn_sched_barrier(0)
; template <class Epi, class Sched, bool ALIGN_EPI, bool SP2>
; __device__ __forceinline__ void gemm_phase(LAS unsigned char* lds, const Gemm g, const Sched& S, const Epi& E, int tid_in) {
;     ...
;             PG8_LDA(At, 0, 1); PG8_STAGE(PG8_SB(0, 0), b2, voffB); PG8_STAGE(PG8_SB(0, 1), b2 + hstepB, voffB); PG8_STAGE(PG8_SA(0, 0), a2, voffA);
;             PG8_WAIT_V(8); PG8_WAIT_L(0); PG8_BAR; PG8_MMA(1, 0, At, B0); PG8_MMA(1, 1, At, B1); PG8_BAR; PG8_SCHED;
;             PG8_LDB(B0, 1, 0); PG8_LDB(B1, 1, 1); PG8_SCHED; PG8_LDA(At, 1, 0); PG8_STAGE(PG8_SA(0, 1), a2 + hstepA, voffA);
;             PG8_WAIT_V(8); PG8_WAIT_L(0); PG8_BAR; PG8_MMA(0, 0, At, B0); PG8_MMA(0, 1, At, B1); PG8_BAR; PG8_SCHED;
	s_mov_b32 m0, s68
	s_movk_i32 s16, 0x200
	ds_read_b128 v[176:179], v5 offset:16384
	ds_read_b128 v[180:183], v5 offset:17408
	ds_read_b128 v[184:187], v5 offset:18432
	ds_read_b128 v[188:191], v5 offset:19456
	ds_read_b128 v[192:195], v5 offset:20480
	ds_read_b128 v[196:199], v5 offset:21504
	ds_read_b128 v[200:203], v5 offset:22528
	ds_read_b128 v[204:207], v5 offset:23552
	buffer_load_dwordx4 v2, s[84:87], s16 offen lds
	s_mov_b32 m0, s69
	s_nop 0
	buffer_load_dwordx4 v4, s[84:87], s16 offen lds
	s_mov_b32 m0, s70
	s_movk_i32 s16, 0x6200
	buffer_load_dwordx4 v2, s[84:87], s16 offen lds
	s_mov_b32 m0, s71
	s_nop 0
	buffer_load_dwordx4 v4, s[84:87], s16 offen lds
	s_mov_b32 m0, s56
	s_nop 0
	buffer_load_dwordx4 v0, s[36:39], s14 offen lds
	s_mov_b32 m0, s72
	s_nop 0
	buffer_load_dwordx4 v3, s[36:39], s14 offen lds
	s_waitcnt vmcnt(8)
	s_waitcnt lgkmcnt(0)
	s_barrier
	s_setprio 1
	s_waitcnt lgkmcnt(7)
	v_mfma_f32_16x16x32_bf16 v[144:147], v[120:123], v[176:179], v[144:147]
	v_mfma_f32_16x16x32_bf16 v[148:151], v[128:131], v[176:179], v[148:151]
	s_waitcnt lgkmcnt(5)
	v_mfma_f32_16x16x32_bf16 v[152:155], v[120:123], v[184:187], v[152:155]
	v_mfma_f32_16x16x32_bf16 v[156:159], v[128:131], v[184:187], v[156:159]
	s_waitcnt lgkmcnt(3)
	v_mfma_f32_16x16x32_bf16 v[160:163], v[120:123], v[192:195], v[160:163]
	v_mfma_f32_16x16x32_bf16 v[164:167], v[128:131], v[192:195], v[164:167]
	s_waitcnt lgkmcnt(1)
	v_mfma_f32_16x16x32_bf16 v[12:15], v[120:123], v[200:203], v[12:15]
	v_mfma_f32_16x16x32_bf16 v[16:19], v[128:131], v[200:203], v[16:19]
	v_mfma_f32_16x16x32_bf16 v[144:147], v[124:127], v[180:183], v[144:147]
	v_mfma_f32_16x16x32_bf16 v[148:151], v[132:135], v[180:183], v[148:151]
	v_mfma_f32_16x16x32_bf16 v[152:155], v[124:127], v[188:191], v[152:155]
	v_mfma_f32_16x16x32_bf16 v[156:159], v[132:135], v[188:191], v[156:159]
	v_mfma_f32_16x16x32_bf16 v[160:163], v[124:127], v[196:199], v[160:163]
	v_mfma_f32_16x16x32_bf16 v[164:167], v[132:135], v[196:199], v[164:167]
	s_waitcnt lgkmcnt(0)
	v_mfma_f32_16x16x32_bf16 v[12:15], v[124:127], v[204:207], v[12:15]
	v_mfma_f32_16x16x32_bf16 v[16:19], v[132:135], v[204:207], v[16:19]
	v_mfma_f32_16x16x32_bf16 v[20:23], v[136:139], v[176:179], v[20:23]
	v_mfma_f32_16x16x32_bf16 v[24:27], v[168:171], v[176:179], v[24:27]
	v_mfma_f32_16x16x32_bf16 v[36:39], v[136:139], v[184:187], v[36:39]
	v_mfma_f32_16x16x32_bf16 v[40:43], v[168:171], v[184:187], v[40:43]
	v_mfma_f32_16x16x32_bf16 v[72:75], v[136:139], v[192:195], v[72:75]
	v_mfma_f32_16x16x32_bf16 v[116:119], v[168:171], v[192:195], v[116:119]
	v_mfma_f32_16x16x32_bf16 v[28:31], v[136:139], v[200:203], v[28:31]
	v_mfma_f32_16x16x32_bf16 v[32:35], v[168:171], v[200:203], v[32:35]
	v_mfma_f32_16x16x32_bf16 v[20:23], v[140:143], v[180:183], v[20:23]
	v_mfma_f32_16x16x32_bf16 v[24:27], v[172:175], v[180:183], v[24:27]
	v_mfma_f32_16x16x32_bf16 v[36:39], v[140:143], v[188:191], v[36:39]
	v_mfma_f32_16x16x32_bf16 v[40:43], v[172:175], v[188:191], v[40:43]
	v_mfma_f32_16x16x32_bf16 v[72:75], v[140:143], v[196:199], v[72:75]
	v_mfma_f32_16x16x32_bf16 v[116:119], v[172:175], v[196:199], v[116:119]
	v_mfma_f32_16x16x32_bf16 v[28:31], v[140:143], v[204:207], v[28:31]
	v_mfma_f32_16x16x32_bf16 v[32:35], v[172:175], v[204:207], v[32:35]
	s_setprio 0
	s_barrier
	ds_read_b128 v[120:123], v7
	ds_read_b128 v[124:127], v7 offset:1024
	ds_read_b128 v[128:131], v7 offset:2048
	ds_read_b128 v[132:135], v7 offset:3072
	ds_read_b128 v[136:139], v6
	ds_read_b128 v[140:143], v6 offset:1024
	ds_read_b128 v[168:171], v6 offset:2048
	ds_read_b128 v[172:175], v6 offset:3072
	s_add_i32 s14, s13, 0x18200
	s_mov_b32 m0, s30
	ds_read_b128 v[176:179], v5 offset:32768
	ds_read_b128 v[180:183], v5 offset:33792
	ds_read_b128 v[184:187], v5 offset:34816
	ds_read_b128 v[188:191], v5 offset:35840
	ds_read_b128 v[192:195], v5 offset:36864
	ds_read_b128 v[196:199], v5 offset:37888
	ds_read_b128 v[200:203], v5 offset:38912
	ds_read_b128 v[204:207], v5 offset:39936
	buffer_load_dwordx4 v0, s[36:39], s14 offen lds
	s_mov_b32 m0, s31
	s_nop 0
	buffer_load_dwordx4 v3, s[36:39], s14 offen lds
	s_waitcnt vmcnt(8)
	s_waitcnt lgkmcnt(0)
	s_barrier
	s_setprio 1
	s_waitcnt lgkmcnt(7)
	v_mfma_f32_16x16x32_bf16 v[76:79], v[120:123], v[176:179], v[76:79]
	v_mfma_f32_16x16x32_bf16 v[80:83], v[128:131], v[176:179], v[80:83]
	s_waitcnt lgkmcnt(5)
	v_mfma_f32_16x16x32_bf16 v[84:87], v[120:123], v[184:187], v[84:87]
	v_mfma_f32_16x16x32_bf16 v[88:91], v[128:131], v[184:187], v[88:91]
	s_waitcnt lgkmcnt(3)
	v_mfma_f32_16x16x32_bf16 v[92:95], v[120:123], v[192:195], v[92:95]
	v_mfma_f32_16x16x32_bf16 v[96:99], v[128:131], v[192:195], v[96:99]
	s_waitcnt lgkmcnt(1)
	v_mfma_f32_16x16x32_bf16 v[100:103], v[120:123], v[200:203], v[100:103]
	v_mfma_f32_16x16x32_bf16 v[104:107], v[128:131], v[200:203], v[104:107]
	v_mfma_f32_16x16x32_bf16 v[76:79], v[124:127], v[180:183], v[76:79]
	v_mfma_f32_16x16x32_bf16 v[80:83], v[132:135], v[180:183], v[80:83]
	v_mfma_f32_16x16x32_bf16 v[84:87], v[124:127], v[188:191], v[84:87]
	v_mfma_f32_16x16x32_bf16 v[88:91], v[132:135], v[188:191], v[88:91]
	v_mfma_f32_16x16x32_bf16 v[92:95], v[124:127], v[196:199], v[92:95]
	v_mfma_f32_16x16x32_bf16 v[96:99], v[132:135], v[196:199], v[96:99]
	s_waitcnt lgkmcnt(0)
	v_mfma_f32_16x16x32_bf16 v[100:103], v[124:127], v[204:207], v[100:103]
	v_mfma_f32_16x16x32_bf16 v[104:107], v[132:135], v[204:207], v[104:107]
	v_mfma_f32_16x16x32_bf16 v[108:111], v[136:139], v[176:179], v[108:111]
	v_mfma_f32_16x16x32_bf16 v[44:47], v[168:171], v[176:179], v[44:47]
	v_mfma_f32_16x16x32_bf16 v[48:51], v[136:139], v[184:187], v[48:51]
	v_mfma_f32_16x16x32_bf16 v[52:55], v[168:171], v[184:187], v[52:55]
	v_mfma_f32_16x16x32_bf16 v[56:59], v[136:139], v[192:195], v[56:59]
	v_mfma_f32_16x16x32_bf16 v[60:63], v[168:171], v[192:195], v[60:63]
	v_mfma_f32_16x16x32_bf16 v[64:67], v[136:139], v[200:203], v[64:67]
	v_mfma_f32_16x16x32_bf16 v[68:71], v[168:171], v[200:203], v[68:71]
	v_mfma_f32_16x16x32_bf16 v[108:111], v[140:143], v[180:183], v[108:111]
	v_mfma_f32_16x16x32_bf16 v[44:47], v[172:175], v[180:183], v[44:47]
	v_mfma_f32_16x16x32_bf16 v[48:51], v[140:143], v[188:191], v[48:51]
	v_mfma_f32_16x16x32_bf16 v[52:55], v[172:175], v[188:191], v[52:55]
	v_mfma_f32_16x16x32_bf16 v[56:59], v[140:143], v[196:199], v[56:59]
	v_mfma_f32_16x16x32_bf16 v[60:63], v[172:175], v[196:199], v[60:63]
	v_mfma_f32_16x16x32_bf16 v[64:67], v[140:143], v[204:207], v[64:67]
	v_mfma_f32_16x16x32_bf16 v[68:71], v[172:175], v[204:207], v[68:71]
	s_setprio 0
	s_barrier
; #define PG8_STAGE(bufoff, goff, voff) do { _Pragma("unroll") for (int _i = 0; _i < 2; ++_i) \
;         __builtin_amdgcn_raw_ptr_buffer_load_lds(R_##voff, (LAS void*)(lds + (bufoff) + ldsw + _i * 8192), 16, (int)(voff)[_i], (int)(goff), 0, 0); } while (0)
; #define PG8_WAIT_V(n) asm volatile("s_waitcnt vmcnt(" #n ")" ::: "memory")
; #define PG8_WAIT_L(n) asm volatile("s_waitcnt lgkmcnt(" #n ")" ::: "memory")
; #define PG8_BAR __builtin_amdgcn_s_barrier()
; #define PG8_SCHED __builtin_amdgcn_sched_barrier(0)
; template <class Epi, class Sched, bool ALIGN_EPI, bool SP2>
; __device__ __forceinline__ void gemm_phase(LAS unsigned char* lds, const Gemm g, const Sched& S, const Epi& E, int tid_in) {
;     ...
;             PG8_LDB(B0, 0, 0); PG8_LDB(B1, 0, 1); PG8_SCHED; PG8_LDA(At, 0, 0); PG8_STAGE(PG8_SA(1, 1), a1 + hstepA, voffA);
;             PG8_WAIT_V(8); PG8_WAIT_L(0); PG8_BAR; PG8_MMA(0, 0, At, B0); PG8_MMA(0, 1, At, B1); PG8_BAR; PG8_SCHED;
;             PG8_LDA(At, 0, 1); PG8_STAGE(PG8_SB(0, 0), b2, voffB); PG8_STAGE(PG8_SB(0, 1), b2 + hstepB, voffB); PG8_STAGE(PG8_SA(0, 0), a2, voffA);
;             PG8_WAIT_V(8); PG8_WAIT_L(0); PG8_BAR; PG8_MMA(1, 0, At, B0); PG8_MMA(1, 1, At, B1); PG8_BAR; PG8_SCHED;
;             PG8_LDB(B0, 1, 0); PG8_LDB(B1, 1, 1); PG8_SCHED; PG8_LDA(At, 1, 0); PG8_STAGE(PG8_SA(0, 1), a2 + hstepA, voffA);
;             PG8_WAIT_V(8); PG8_WAIT_L(0); PG8_BAR; PG8_MMA(0, 0, At, B0); PG8_MMA(0, 1, At, B1); PG8_BAR; PG8_SCHED;
;             PG8_LDA(At, 1, 1); PG8_STAGE(PG8_SB(1, 0), b3, voffB); PG8_STAGE(PG8_SB(1, 1), b3 + hstepB, voffB); PG8_STAGE(PG8_SA(1, 0), a3, voffA);
;             PG8_WAIT_V(8); PG8_WAIT_L(0); PG8_BAR; PG8_MMA(1, 0, At, B0); PG8_MMA(1, 1, At, B1); PG8_BAR; PG8_SCHED;
	s_mov_b32 m0, s50
	s_movk_i32 s14, 0x280
	ds_read_b128 v[176:179], v5 offset:49152
	ds_read_b128 v[180:183], v5 offset:50176
	ds_read_b128 v[184:187], v5 offset:51200
	ds_read_b128 v[188:191], v5 offset:52224
	ds_read_b128 v[192:195], v5 offset:53248
	ds_read_b128 v[196:199], v5 offset:54272
	ds_read_b128 v[200:203], v5 offset:55296
	ds_read_b128 v[204:207], v5 offset:56320
	buffer_load_dwordx4 v2, s[84:87], s14 offen lds
	s_mov_b32 m0, s52
	s_nop 0
	buffer_load_dwordx4 v4, s[84:87], s14 offen lds
	s_mov_b32 m0, s57
	s_movk_i32 s14, 0x6280
	buffer_load_dwordx4 v2, s[84:87], s14 offen lds
	s_mov_b32 m0, s65
	s_nop 0
	buffer_load_dwordx4 v4, s[84:87], s14 offen lds
	s_mov_b32 m0, s17
	s_nop 0
	buffer_load_dwordx4 v0, s[36:39], s15 offen lds
	s_mov_b32 m0, s34
	s_nop 0
	buffer_load_dwordx4 v3, s[36:39], s15 offen lds
	s_waitcnt vmcnt(8)
	s_waitcnt lgkmcnt(0)
	s_barrier
	s_setprio 1
	s_waitcnt lgkmcnt(7)
	v_mfma_f32_16x16x32_bf16 v[144:147], v[120:123], v[176:179], v[144:147]
	v_mfma_f32_16x16x32_bf16 v[148:151], v[128:131], v[176:179], v[148:151]
	s_waitcnt lgkmcnt(5)
	v_mfma_f32_16x16x32_bf16 v[152:155], v[120:123], v[184:187], v[152:155]
	v_mfma_f32_16x16x32_bf16 v[156:159], v[128:131], v[184:187], v[156:159]
	s_waitcnt lgkmcnt(3)
	v_mfma_f32_16x16x32_bf16 v[160:163], v[120:123], v[192:195], v[160:163]
	v_mfma_f32_16x16x32_bf16 v[164:167], v[128:131], v[192:195], v[164:167]
	s_waitcnt lgkmcnt(1)
	v_mfma_f32_16x16x32_bf16 v[12:15], v[120:123], v[200:203], v[12:15]
	v_mfma_f32_16x16x32_bf16 v[16:19], v[128:131], v[200:203], v[16:19]
	v_mfma_f32_16x16x32_bf16 v[144:147], v[124:127], v[180:183], v[144:147]
	v_mfma_f32_16x16x32_bf16 v[148:151], v[132:135], v[180:183], v[148:151]
	v_mfma_f32_16x16x32_bf16 v[152:155], v[124:127], v[188:191], v[152:155]
	v_mfma_f32_16x16x32_bf16 v[156:159], v[132:135], v[188:191], v[156:159]
	v_mfma_f32_16x16x32_bf16 v[160:163], v[124:127], v[196:199], v[160:163]
	v_mfma_f32_16x16x32_bf16 v[164:167], v[132:135], v[196:199], v[164:167]
	s_waitcnt lgkmcnt(0)
	v_mfma_f32_16x16x32_bf16 v[12:15], v[124:127], v[204:207], v[12:15]
	v_mfma_f32_16x16x32_bf16 v[16:19], v[132:135], v[204:207], v[16:19]
	v_mfma_f32_16x16x32_bf16 v[20:23], v[136:139], v[176:179], v[20:23]
	v_mfma_f32_16x16x32_bf16 v[24:27], v[168:171], v[176:179], v[24:27]
	v_mfma_f32_16x16x32_bf16 v[36:39], v[136:139], v[184:187], v[36:39]
	v_mfma_f32_16x16x32_bf16 v[40:43], v[168:171], v[184:187], v[40:43]
	v_mfma_f32_16x16x32_bf16 v[72:75], v[136:139], v[192:195], v[72:75]
	v_mfma_f32_16x16x32_bf16 v[116:119], v[168:171], v[192:195], v[116:119]
	v_mfma_f32_16x16x32_bf16 v[28:31], v[136:139], v[200:203], v[28:31]
	v_mfma_f32_16x16x32_bf16 v[32:35], v[168:171], v[200:203], v[32:35]
	v_mfma_f32_16x16x32_bf16 v[20:23], v[140:143], v[180:183], v[20:23]
	v_mfma_f32_16x16x32_bf16 v[24:27], v[172:175], v[180:183], v[24:27]
	v_mfma_f32_16x16x32_bf16 v[36:39], v[140:143], v[188:191], v[36:39]
	v_mfma_f32_16x16x32_bf16 v[40:43], v[172:175], v[188:191], v[40:43]
	v_mfma_f32_16x16x32_bf16 v[72:75], v[140:143], v[196:199], v[72:75]
	v_mfma_f32_16x16x32_bf16 v[116:119], v[172:175], v[196:199], v[116:119]
	v_mfma_f32_16x16x32_bf16 v[28:31], v[140:143], v[204:207], v[28:31]
	v_mfma_f32_16x16x32_bf16 v[32:35], v[172:175], v[204:207], v[32:35]
	s_setprio 0
	s_barrier
	ds_read_b128 v[120:123], v9
	ds_read_b128 v[124:127], v9 offset:1024
	ds_read_b128 v[128:131], v9 offset:2048
	ds_read_b128 v[132:135], v9 offset:3072
	ds_read_b128 v[136:139], v8
	ds_read_b128 v[140:143], v8 offset:1024
	ds_read_b128 v[168:171], v8 offset:2048
	ds_read_b128 v[172:175], v8 offset:3072
	s_add_i32 s14, s13, 0x18280
	s_mov_b32 m0, s73
	ds_read_b128 v[176:179], v5
	ds_read_b128 v[180:183], v5 offset:1024
	ds_read_b128 v[184:187], v5 offset:2048
	ds_read_b128 v[188:191], v5 offset:3072
	ds_read_b128 v[192:195], v5 offset:4096
	ds_read_b128 v[196:199], v5 offset:5120
	ds_read_b128 v[200:203], v5 offset:6144
	ds_read_b128 v[204:207], v5 offset:7168
	buffer_load_dwordx4 v0, s[36:39], s14 offen lds
	s_mov_b32 m0, s25
	s_nop 0
	buffer_load_dwordx4 v3, s[36:39], s14 offen lds
	s_waitcnt vmcnt(8)
	s_waitcnt lgkmcnt(0)
	s_barrier
	s_setprio 1
	s_waitcnt lgkmcnt(7)
	v_mfma_f32_16x16x32_bf16 v[76:79], v[120:123], v[176:179], v[76:79]
	v_mfma_f32_16x16x32_bf16 v[80:83], v[128:131], v[176:179], v[80:83]
	s_waitcnt lgkmcnt(5)
	v_mfma_f32_16x16x32_bf16 v[84:87], v[120:123], v[184:187], v[84:87]
	v_mfma_f32_16x16x32_bf16 v[88:91], v[128:131], v[184:187], v[88:91]
	s_waitcnt lgkmcnt(3)
	v_mfma_f32_16x16x32_bf16 v[92:95], v[120:123], v[192:195], v[92:95]
	v_mfma_f32_16x16x32_bf16 v[96:99], v[128:131], v[192:195], v[96:99]
	s_waitcnt lgkmcnt(1)
	v_mfma_f32_16x16x32_bf16 v[100:103], v[120:123], v[200:203], v[100:103]
	v_mfma_f32_16x16x32_bf16 v[104:107], v[128:131], v[200:203], v[104:107]
	v_mfma_f32_16x16x32_bf16 v[76:79], v[124:127], v[180:183], v[76:79]
	v_mfma_f32_16x16x32_bf16 v[80:83], v[132:135], v[180:183], v[80:83]
	v_mfma_f32_16x16x32_bf16 v[84:87], v[124:127], v[188:191], v[84:87]
	v_mfma_f32_16x16x32_bf16 v[88:91], v[132:135], v[188:191], v[88:91]
	v_mfma_f32_16x16x32_bf16 v[92:95], v[124:127], v[196:199], v[92:95]
	v_mfma_f32_16x16x32_bf16 v[96:99], v[132:135], v[196:199], v[96:99]
	s_waitcnt lgkmcnt(0)
	v_mfma_f32_16x16x32_bf16 v[100:103], v[124:127], v[204:207], v[100:103]
	v_mfma_f32_16x16x32_bf16 v[104:107], v[132:135], v[204:207], v[104:107]
	v_mfma_f32_16x16x32_bf16 v[108:111], v[136:139], v[176:179], v[108:111]
	v_mfma_f32_16x16x32_bf16 v[44:47], v[168:171], v[176:179], v[44:47]
	v_mfma_f32_16x16x32_bf16 v[48:51], v[136:139], v[184:187], v[48:51]
	v_mfma_f32_16x16x32_bf16 v[52:55], v[168:171], v[184:187], v[52:55]
	v_mfma_f32_16x16x32_bf16 v[56:59], v[136:139], v[192:195], v[56:59]
	v_mfma_f32_16x16x32_bf16 v[60:63], v[168:171], v[192:195], v[60:63]
	v_mfma_f32_16x16x32_bf16 v[64:67], v[136:139], v[200:203], v[64:67]
	v_mfma_f32_16x16x32_bf16 v[68:71], v[168:171], v[200:203], v[68:71]
	v_mfma_f32_16x16x32_bf16 v[108:111], v[140:143], v[180:183], v[108:111]
	v_mfma_f32_16x16x32_bf16 v[44:47], v[172:175], v[180:183], v[44:47]
	v_mfma_f32_16x16x32_bf16 v[48:51], v[140:143], v[188:191], v[48:51]
	v_mfma_f32_16x16x32_bf16 v[52:55], v[172:175], v[188:191], v[52:55]
	v_mfma_f32_16x16x32_bf16 v[56:59], v[140:143], v[196:199], v[56:59]
	v_mfma_f32_16x16x32_bf16 v[60:63], v[172:175], v[196:199], v[60:63]
	v_mfma_f32_16x16x32_bf16 v[64:67], v[140:143], v[204:207], v[64:67]
	v_mfma_f32_16x16x32_bf16 v[68:71], v[172:175], v[204:207], v[68:71]
	s_setprio 0
	s_barrier
; #define PG8_STAGE(bufoff, goff, voff) do { _Pragma("unroll") for (int _i = 0; _i < 2; ++_i) \
;         __builtin_amdgcn_raw_ptr_buffer_load_lds(R_##voff, (LAS void*)(lds + (bufoff) + ldsw + _i * 8192), 16, (int)(voff)[_i], (int)(goff), 0, 0); } while (0)
; #define PG8_WAIT_V(n) asm volatile("s_waitcnt vmcnt(" #n ")" ::: "memory")
; #define PG8_WAIT_L(n) asm volatile("s_waitcnt lgkmcnt(" #n ")" ::: "memory")
; #define PG8_BAR __builtin_amdgcn_s_barrier()
; #define PG8_SCHED __builtin_amdgcn_sched_barrier(0)
; template <class Epi, class Sched, bool ALIGN_EPI, bool SP2>
; __device__ __forceinline__ void gemm_phase(LAS unsigned char* lds, const Gemm g, const Sched& S, const Epi& E, int tid_in) {
;     ...
;             PG8_LDA(At, 0, 1); PG8_STAGE(PG8_SB(0, 0), b2, voffB); PG8_STAGE(PG8_SB(0, 1), b2 + hstepB, voffB); PG8_STAGE(PG8_SA(0, 0), a2, voffA);
;             PG8_WAIT_V(8); PG8_WAIT_L(0); PG8_BAR; PG8_MMA(1, 0, At, B0); PG8_MMA(1, 1, At, B1); PG8_BAR; PG8_SCHED;
;             PG8_LDB(B0, 1, 0); PG8_LDB(B1, 1, 1); PG8_SCHED; PG8_LDA(At, 1, 0); PG8_STAGE(PG8_SA(0, 1), a2 + hstepA, voffA);
;             PG8_WAIT_V(8); PG8_WAIT_L(0); PG8_BAR; PG8_MMA(0, 0, At, B0); PG8_MMA(0, 1, At, B1); PG8_BAR; PG8_SCHED;
	s_mov_b32 m0, s68
	ds_read_b128 v[176:179], v5 offset:16384
	ds_read_b128 v[180:183], v5 offset:17408
	ds_read_b128 v[184:187], v5 offset:18432
	ds_read_b128 v[188:191], v5 offset:19456
	ds_read_b128 v[192:195], v5 offset:20480
	ds_read_b128 v[196:199], v5 offset:21504
	ds_read_b128 v[200:203], v5 offset:22528
	ds_read_b128 v[204:207], v5 offset:23552
	buffer_load_dwordx4 v2, s[84:87], 0 offen lds
	s_mov_b32 m0, s69
	s_movk_i32 s14, 0x6000
	buffer_load_dwordx4 v4, s[84:87], 0 offen lds
	s_mov_b32 m0, s70
	s_nop 0
	buffer_load_dwordx4 v2, s[84:87], s14 offen lds
	s_mov_b32 m0, s71
	s_nop 0
	buffer_load_dwordx4 v4, s[84:87], s14 offen lds
	s_mov_b32 m0, s56
	s_nop 0
	buffer_load_dwordx4 v0, s[36:39], s13 offen lds
	s_mov_b32 m0, s72
	s_nop 0
	buffer_load_dwordx4 v3, s[36:39], s13 offen lds
	s_waitcnt vmcnt(8)
	s_waitcnt lgkmcnt(0)
	s_barrier
	s_setprio 1
	s_waitcnt lgkmcnt(7)
	v_mfma_f32_16x16x32_bf16 v[144:147], v[120:123], v[176:179], v[144:147]
	s_waitcnt lgkmcnt(6)
	v_mfma_f32_16x16x32_bf16 v[208:211], v[124:127], v[180:183], v[144:147]
	v_mfma_f32_16x16x32_bf16 v[144:147], v[128:131], v[176:179], v[148:151]
	v_mfma_f32_16x16x32_bf16 v[148:151], v[132:135], v[180:183], v[144:147]
	s_waitcnt lgkmcnt(5)
	v_mfma_f32_16x16x32_bf16 v[144:147], v[120:123], v[184:187], v[152:155]
	s_waitcnt lgkmcnt(4)
	v_mfma_f32_16x16x32_bf16 v[220:223], v[124:127], v[188:191], v[144:147]
	v_mfma_f32_16x16x32_bf16 v[144:147], v[128:131], v[184:187], v[156:159]
	v_mfma_f32_16x16x32_bf16 v[224:227], v[132:135], v[188:191], v[144:147]
	s_waitcnt lgkmcnt(3)
	v_mfma_f32_16x16x32_bf16 v[144:147], v[120:123], v[192:195], v[160:163]
	s_waitcnt lgkmcnt(2)
	v_mfma_f32_16x16x32_bf16 v[160:163], v[124:127], v[196:199], v[144:147]
	v_mfma_f32_16x16x32_bf16 v[144:147], v[128:131], v[192:195], v[164:167]
	s_waitcnt lgkmcnt(1)
	v_mfma_f32_16x16x32_bf16 v[12:15], v[120:123], v[200:203], v[12:15]
	v_mfma_f32_16x16x32_bf16 v[16:19], v[128:131], v[200:203], v[16:19]
	v_mfma_f32_16x16x32_bf16 v[228:231], v[132:135], v[196:199], v[144:147]
	s_waitcnt lgkmcnt(0)
	v_mfma_f32_16x16x32_bf16 v[12:15], v[124:127], v[204:207], v[12:15]
	v_mfma_f32_16x16x32_bf16 v[16:19], v[132:135], v[204:207], v[16:19]
	v_mfma_f32_16x16x32_bf16 v[20:23], v[136:139], v[176:179], v[20:23]
	v_mfma_f32_16x16x32_bf16 v[124:127], v[140:143], v[180:183], v[20:23]
	v_mfma_f32_16x16x32_bf16 v[20:23], v[168:171], v[176:179], v[24:27]
	v_mfma_f32_16x16x32_bf16 v[238:241], v[172:175], v[180:183], v[20:23]
	v_mfma_f32_16x16x32_bf16 v[20:23], v[136:139], v[184:187], v[36:39]
	v_mfma_f32_16x16x32_bf16 v[36:39], v[140:143], v[188:191], v[20:23]
	v_mfma_f32_16x16x32_bf16 v[20:23], v[168:171], v[184:187], v[40:43]
	v_mfma_f32_16x16x32_bf16 v[184:187], v[172:175], v[188:191], v[20:23]
	v_mfma_f32_16x16x32_bf16 v[20:23], v[136:139], v[192:195], v[72:75]
	v_mfma_f32_16x16x32_bf16 v[188:191], v[140:143], v[196:199], v[20:23]
	v_mfma_f32_16x16x32_bf16 v[20:23], v[168:171], v[192:195], v[116:119]
	v_mfma_f32_16x16x32_bf16 v[192:195], v[172:175], v[196:199], v[20:23]
	v_mfma_f32_16x16x32_bf16 v[20:23], v[136:139], v[200:203], v[28:31]
	v_mfma_f32_16x16x32_bf16 v[26:29], v[140:143], v[204:207], v[20:23]
	v_mfma_f32_16x16x32_bf16 v[20:23], v[168:171], v[200:203], v[32:35]
	v_mfma_f32_16x16x32_bf16 v[30:33], v[172:175], v[204:207], v[20:23]
	s_setprio 0
	s_barrier
	s_nop 4
	ds_read_b128 v[20:23], v7
	ds_read_b128 v[136:139], v7 offset:1024
	ds_read_b128 v[172:175], v7 offset:2048
	ds_read_b128 v[196:199], v7 offset:3072
	ds_read_b128 v[200:203], v6
	ds_read_b128 v[204:207], v6 offset:1024
	ds_read_b128 v[242:245], v6 offset:2048
	ds_read_b128 v[246:249], v6 offset:3072
	s_mov_b32 m0, s30
	ds_read_b128 v[6:9], v5 offset:32768
	ds_read_b128 v[40:43], v5 offset:33792
	ds_read_b128 v[72:75], v5 offset:34816
	ds_read_b128 v[128:131], v5 offset:35840
	ds_read_b128 v[250:253], v5 offset:36864
	ds_read_b128 v[212:215], v5 offset:37888
	ds_read_b128 v[216:219], v5 offset:38912
	ds_read_b128 v[234:237], v5 offset:39936
	buffer_load_dwordx4 v0, s[36:39], s10 offen lds
	s_mov_b32 m0, s31
	s_nop 0
	buffer_load_dwordx4 v3, s[36:39], s10 offen lds
	s_waitcnt vmcnt(8)
	s_waitcnt lgkmcnt(0)
	s_barrier
	s_setprio 1
	s_waitcnt lgkmcnt(5)
	v_mfma_f32_16x16x32_bf16 v[84:87], v[20:23], v[72:75], v[84:87]
	s_waitcnt lgkmcnt(4)
	v_mfma_f32_16x16x32_bf16 v[168:171], v[136:139], v[128:131], v[84:87]
	v_mfma_f32_16x16x32_bf16 v[84:87], v[172:175], v[72:75], v[88:91]
	v_mfma_f32_16x16x32_bf16 v[164:167], v[196:199], v[128:131], v[84:87]
	s_waitcnt lgkmcnt(3)
	v_mfma_f32_16x16x32_bf16 v[84:87], v[20:23], v[250:253], v[92:95]
	s_waitcnt lgkmcnt(2)
	v_mfma_f32_16x16x32_bf16 v[144:147], v[136:139], v[212:215], v[84:87]
	v_mfma_f32_16x16x32_bf16 v[84:87], v[172:175], v[250:253], v[96:99]
	v_mfma_f32_16x16x32_bf16 v[140:143], v[196:199], v[212:215], v[84:87]
	s_waitcnt lgkmcnt(1)
	v_mfma_f32_16x16x32_bf16 v[84:87], v[20:23], v[216:219], v[100:103]
	v_mfma_f32_16x16x32_bf16 v[76:79], v[20:23], v[6:9], v[76:79]
	v_mfma_f32_16x16x32_bf16 v[80:83], v[172:175], v[6:9], v[80:83]
	s_waitcnt lgkmcnt(0)
	v_mfma_f32_16x16x32_bf16 v[120:123], v[136:139], v[234:237], v[84:87]
	v_mfma_f32_16x16x32_bf16 v[84:87], v[172:175], v[216:219], v[104:107]
	v_mfma_f32_16x16x32_bf16 v[76:79], v[136:139], v[40:43], v[76:79]
	v_mfma_f32_16x16x32_bf16 v[80:83], v[196:199], v[40:43], v[80:83]
	v_mfma_f32_16x16x32_bf16 v[116:119], v[196:199], v[234:237], v[84:87]
	v_mfma_f32_16x16x32_bf16 v[84:87], v[200:203], v[6:9], v[108:111]
	v_mfma_f32_16x16x32_bf16 v[6:9], v[242:245], v[6:9], v[44:47]
	v_mfma_f32_16x16x32_bf16 v[176:179], v[246:249], v[40:43], v[6:9]
	v_mfma_f32_16x16x32_bf16 v[6:9], v[200:203], v[72:75], v[48:51]
	v_mfma_f32_16x16x32_bf16 v[156:159], v[204:207], v[128:131], v[6:9]
	v_mfma_f32_16x16x32_bf16 v[6:9], v[242:245], v[72:75], v[52:55]
	v_mfma_f32_16x16x32_bf16 v[152:155], v[246:249], v[128:131], v[6:9]
	v_mfma_f32_16x16x32_bf16 v[6:9], v[200:203], v[250:253], v[56:59]
	v_mfma_f32_16x16x32_bf16 v[132:135], v[204:207], v[212:215], v[6:9]
	v_mfma_f32_16x16x32_bf16 v[6:9], v[242:245], v[250:253], v[60:63]
	v_mfma_f32_16x16x32_bf16 v[128:131], v[246:249], v[212:215], v[6:9]
	v_mfma_f32_16x16x32_bf16 v[6:9], v[200:203], v[216:219], v[64:67]
	v_mfma_f32_16x16x32_bf16 v[106:109], v[204:207], v[234:237], v[6:9]
	v_mfma_f32_16x16x32_bf16 v[6:9], v[242:245], v[216:219], v[68:71]
	v_mfma_f32_16x16x32_bf16 v[180:183], v[204:207], v[40:43], v[84:87]
	v_mfma_f32_16x16x32_bf16 v[102:105], v[246:249], v[234:237], v[6:9]
	s_setprio 0
	s_barrier
; #define PG8_STAGE(bufoff, goff, voff) do { _Pragma("unroll") for (int _i = 0; _i < 2; ++_i) \
;         __builtin_amdgcn_raw_ptr_buffer_load_lds(R_##voff, (LAS void*)(lds + (bufoff) + ldsw + _i * 8192), 16, (int)(voff)[_i], (int)(goff), 0, 0); } while (0)
; #define PG8_WAIT_V(n) asm volatile("s_waitcnt vmcnt(" #n ")" ::: "memory")
; #define PG8_BAR __builtin_amdgcn_s_barrier()
; template <class Epi, class Sched, bool ALIGN_EPI, bool SP2>
; __device__ __forceinline__ void gemm_phase(LAS unsigned char* lds, const Gemm g, const Sched& S, const Epi& E, int tid_in) {
;     ...
;             PG8_LDA(At, 1, 1); PG8_STAGE(PG8_SB(1, 0), b3, voffB); PG8_STAGE(PG8_SB(1, 1), b3 + hstepB, voffB); PG8_STAGE(PG8_SA(1, 0), a3, voffA);
;             PG8_WAIT_V(8); PG8_WAIT_L(0); PG8_BAR; PG8_MMA(1, 0, At, B0); PG8_MMA(1, 1, At, B1); PG8_BAR; PG8_SCHED;
;     __device__ __forceinline__ void operator()(const Acc& acc, const Unit& u, int wr, int wc, int fr, int fq) const {
;     ...
;         const int h0 = 8 * (fq & 1), row0 = u.pm * 256 + wr * 64 + fr, colb = wc * 64 + 8 * fq;
;         const f32x4 d0 = *(const f32x4*)(dsk + h0), d1 = *(const f32x4*)(dsk + h0 + 4);
;         u32x4 urow[8][2];
; #pragma unroll
;         for (int idx = 0; idx < 8; ++idx) { const size_t ro = (size_t)(row0 + (idx >> 2) * 128 + (idx & 3) * 16) * A2LD + colb; urow[idx][0] = *(const u32x4*)(a2g + ro); urow[idx][1] = *(const u32x4*)(a2g + ro + 32); }
;         asm volatile("" ::: "memory");
; #pragma unroll
;         for (int idx = 0; idx < 8; ++idx) { const int ai = idx >> 2, m = idx & 3, row = row0 + ai * 128 + m * 16;
; #pragma unroll
;             for (int bj = 0; bj < 2; ++bj) { const int col = bj * 32 + colb, tl = col >> 4;
;                 const u32x4 uu = urow[idx][bj];
;                 const f32x4 a = acc[ai][bj][m][0], b = acc[ai][bj][m][1];
;                 f32x2 y0 = (f32x2){a[0], a[1]} + (f32x2){d0[0], d0[1]} * (f32x2){bf2f(uu.x & 0xffffu), bf2f(uu.x >> 16)}, y1 = (f32x2){a[2], a[3]} + (f32x2){d0[2], d0[3]} * (f32x2){bf2f(uu.y & 0xffffu), bf2f(uu.y >> 16)};
;                 f32x2 y2 = (f32x2){b[0], b[1]} + (f32x2){d1[0], d1[1]} * (f32x2){bf2f(uu.z & 0xffffu), bf2f(uu.z >> 16)}, y3 = (f32x2){b[2], b[3]} + (f32x2){d1[2], d1[3]} * (f32x2){bf2f(uu.w & 0xffffu), bf2f(uu.w >> 16)};
;                 y0 = gelu_tanh2(y0); y1 = gelu_tanh2(y1); y2 = gelu_tanh2(y2); y3 = gelu_tanh2(y3);
	s_mov_b32 m0, s50
	s_nop 2
	ds_read_b128 v[6:9], v5 offset:49152
	ds_read_b128 v[50:53], v5 offset:50176
	ds_read_b128 v[54:57], v5 offset:51200
	ds_read_b128 v[58:61], v5 offset:52224
	ds_read_b128 v[98:101], v5 offset:53248
	ds_read_b128 v[110:113], v5 offset:54272
	ds_read_b128 v[212:215], v5 offset:55296
	ds_read_b128 v[216:219], v5 offset:56320
	buffer_load_dwordx4 v2, s[84:87], s74 offen lds
	s_mov_b32 m0, s52
	s_nop 0
	buffer_load_dwordx4 v4, s[84:87], s74 offen lds
	s_mov_b32 m0, s57
	s_nop 0
	buffer_load_dwordx4 v2, s[84:87], s75 offen lds
	s_mov_b32 m0, s65
	s_nop 0
	buffer_load_dwordx4 v4, s[84:87], s75 offen lds
	s_mov_b32 m0, s17
	s_nop 0
	buffer_load_dwordx4 v0, s[36:39], s12 offen lds
	s_mov_b32 m0, s34
	s_nop 0
	buffer_load_dwordx4 v3, s[36:39], s12 offen lds
	s_waitcnt vmcnt(8)
	s_waitcnt lgkmcnt(0)
	s_barrier
	s_setprio 1
	s_waitcnt lgkmcnt(7)
	v_mfma_f32_16x16x32_bf16 v[2:5], v[20:23], v[6:9], v[208:211]
	s_waitcnt lgkmcnt(6)
	v_mfma_f32_16x16x32_bf16 v[94:97], v[136:139], v[50:53], v[2:5]
	v_mfma_f32_16x16x32_bf16 v[2:5], v[172:175], v[6:9], v[148:151]
	v_mfma_f32_16x16x32_bf16 v[90:93], v[196:199], v[50:53], v[2:5]
	s_waitcnt lgkmcnt(5)
	v_mfma_f32_16x16x32_bf16 v[2:5], v[20:23], v[54:57], v[220:223]
	s_waitcnt lgkmcnt(4)
	v_mfma_f32_16x16x32_bf16 v[70:73], v[136:139], v[58:61], v[2:5]
	v_mfma_f32_16x16x32_bf16 v[2:5], v[172:175], v[54:57], v[224:227]
	v_mfma_f32_16x16x32_bf16 v[66:69], v[196:199], v[58:61], v[2:5]
	s_waitcnt lgkmcnt(3)
	v_mfma_f32_16x16x32_bf16 v[2:5], v[20:23], v[98:101], v[160:163]
	s_waitcnt lgkmcnt(2)
	v_mfma_f32_16x16x32_bf16 v[46:49], v[136:139], v[110:113], v[2:5]
	v_mfma_f32_16x16x32_bf16 v[2:5], v[172:175], v[98:101], v[228:231]
	v_mfma_f32_16x16x32_bf16 v[42:45], v[196:199], v[110:113], v[2:5]
	s_waitcnt lgkmcnt(1)
	v_mfma_f32_16x16x32_bf16 v[2:5], v[20:23], v[212:215], v[12:15]
	s_waitcnt lgkmcnt(0)
	v_mfma_f32_16x16x32_bf16 v[22:25], v[136:139], v[216:219], v[2:5]
	v_mfma_f32_16x16x32_bf16 v[2:5], v[172:175], v[212:215], v[16:19]
	v_mfma_f32_16x16x32_bf16 v[18:21], v[196:199], v[216:219], v[2:5]
	v_mfma_f32_16x16x32_bf16 v[2:5], v[200:203], v[6:9], v[124:127]
	v_mfma_f32_16x16x32_bf16 v[86:89], v[204:207], v[50:53], v[2:5]
	v_mfma_f32_16x16x32_bf16 v[2:5], v[242:245], v[6:9], v[238:241]
	v_mfma_f32_16x16x32_bf16 v[208:211], v[246:249], v[50:53], v[2:5]
	v_mfma_f32_16x16x32_bf16 v[2:5], v[200:203], v[54:57], v[36:39]
	v_mfma_f32_16x16x32_bf16 v[62:65], v[204:207], v[58:61], v[2:5]
	v_mfma_f32_16x16x32_bf16 v[2:5], v[242:245], v[54:57], v[184:187]
	v_mfma_f32_16x16x32_bf16 v[58:61], v[246:249], v[58:61], v[2:5]
	v_mfma_f32_16x16x32_bf16 v[2:5], v[200:203], v[98:101], v[188:191]
	v_mfma_f32_16x16x32_bf16 v[38:41], v[204:207], v[110:113], v[2:5]
	v_mfma_f32_16x16x32_bf16 v[2:5], v[242:245], v[98:101], v[192:195]
	v_mfma_f32_16x16x32_bf16 v[34:37], v[246:249], v[110:113], v[2:5]
	v_mfma_f32_16x16x32_bf16 v[2:5], v[200:203], v[212:215], v[26:29]
	v_mfma_f32_16x16x32_bf16 v[6:9], v[204:207], v[216:219], v[2:5]
	v_mfma_f32_16x16x32_bf16 v[2:5], v[242:245], v[212:215], v[30:33]
	v_mfma_f32_16x16x32_bf16 v[2:5], v[246:249], v[216:219], v[2:5]
	s_setprio 0
	s_barrier
	s_lshl_b32 s7, s7, 8
	v_lshlrev_b32_e32 v0, 3, v11
	v_lshl_add_u32 v192, s5, 6, v0
	s_add_i32 s11, s11, s7
	v_ashrrev_i32_e32 v193, 31, v192
	v_add_u32_e32 v30, s11, v10
	v_lshl_add_u64 v[26:27], v[192:193], 1, s[46:47]
	s_movk_i32 s5, 0x300
	v_mad_i64_i32 v[28:29], s[10:11], v30, s5, v[26:27]
	v_and_b32_e32 v0, 8, v0
	global_load_dwordx4 v[202:205], v[28:29], off
	v_lshlrev_b32_e32 v10, 2, v0
	global_load_dwordx4 v[14:17], v10, s[66:67]
	s_nop 0
	global_load_dwordx4 v[10:13], v10, s[66:67] offset:16
	s_mov_b32 s10, 0xc0135761
	v_add_u32_e32 v31, 16, v30
	v_add_u32_e32 v32, 32, v30
	v_add_u32_e32 v50, 48, v30
	v_add_u32_e32 v52, 0x80, v30
	v_add_u32_e32 v54, 0x90, v30
	v_add_u32_e32 v56, 0xa0, v30
	v_add_u32_e32 v57, 0xb0, v30
	v_mov_b64_e32 v[188:189], s[10:11]
	v_lshlrev_b32_e32 v193, 4, v30
	v_mad_i64_i32 v[30:31], s[10:11], v31, s5, v[26:27]
	v_mad_i64_i32 v[32:33], s[10:11], v32, s5, v[26:27]
	v_mad_i64_i32 v[50:51], s[10:11], v50, s5, v[26:27]
	v_mad_i64_i32 v[52:53], s[10:11], v52, s5, v[26:27]
	v_mad_i64_i32 v[54:55], s[10:11], v54, s5, v[26:27]
	v_mad_i64_i32 v[74:75], s[10:11], v56, s5, v[26:27]
	v_mad_i64_i32 v[26:27], s[10:11], v57, s5, v[26:27]
	global_load_dwordx4 v[212:215], v[28:29], off offset:64
	global_load_dwordx4 v[184:187], v[30:31], off
	global_load_dwordx4 v[172:175], v[30:31], off offset:64
	global_load_dwordx4 v[160:163], v[32:33], off
	global_load_dwordx4 v[148:151], v[32:33], off offset:64
	global_load_dwordx4 v[136:139], v[50:51], off
	global_load_dwordx4 v[124:127], v[50:51], off offset:64
	global_load_dwordx4 v[110:113], v[52:53], off
	global_load_dwordx4 v[98:101], v[52:53], off offset:64
	global_load_dwordx4 v[198:201], v[54:55], off
	global_load_dwordx4 v[194:197], v[54:55], off offset:64
	s_nop 0
	global_load_dwordx4 v[54:57], v[74:75], off
	global_load_dwordx4 v[50:53], v[74:75], off offset:64
	global_load_dwordx4 v[30:33], v[26:27], off
	s_nop 0
	global_load_dwordx4 v[26:29], v[26:27], off offset:64
	s_mov_b32 s10, 0x3dd2d3e7
	v_ashrrev_i32_e32 v115, 4, v192
	v_readlane_b32 s14, v255, 52
	v_readlane_b32 s15, v255, 53
	s_lshl_b64 s[36:37], s[2:3], 1
	s_mov_b32 s12, 0x41800000
	s_cmpk_gt_u32 s4, 0xff
	s_waitcnt vmcnt(17)
	v_lshlrev_b32_e32 v74, 16, v202
	v_and_b32_e32 v75, 0xffff0000, v202
	v_lshlrev_b32_e32 v84, 16, v203
	v_and_b32_e32 v85, 0xffff0000, v203
	v_lshlrev_b32_e32 v190, 16, v204
	v_and_b32_e32 v191, 0xffff0000, v204
	s_waitcnt vmcnt(16)
; __device__ __forceinline__ unsigned cvt_pk_bf16(float lo, float hi) { unsigned r; asm volatile("v_cvt_pk_bf16_f32 %0, %1, %2" : "=v"(r) : "v"(lo), "v"(hi)); return r; }
;     __device__ __forceinline__ void operator()(const Acc& acc, const Unit& u, int wr, int wc, int fr, int fq) const {
;     ...
;         for (int idx = 0; idx < 8; ++idx) { const int ai = idx >> 2, m = idx & 3, row = row0 + ai * 128 + m * 16;
; #pragma unroll
;             for (int bj = 0; bj < 2; ++bj) { const int col = bj * 32 + colb, tl = col >> 4;
;                 const u32x4 uu = urow[idx][bj];
;                 const f32x4 a = acc[ai][bj][m][0], b = acc[ai][bj][m][1];
;                 f32x2 y0 = (f32x2){a[0], a[1]} + (f32x2){d0[0], d0[1]} * (f32x2){bf2f(uu.x & 0xffffu), bf2f(uu.x >> 16)}, y1 = (f32x2){a[2], a[3]} + (f32x2){d0[2], d0[3]} * (f32x2){bf2f(uu.y & 0xffffu), bf2f(uu.y >> 16)};
;                 f32x2 y2 = (f32x2){b[0], b[1]} + (f32x2){d1[0], d1[1]} * (f32x2){bf2f(uu.z & 0xffffu), bf2f(uu.z >> 16)}, y3 = (f32x2){b[2], b[3]} + (f32x2){d1[2], d1[3]} * (f32x2){bf2f(uu.w & 0xffffu), bf2f(uu.w >> 16)};
;                 y0 = gelu_tanh2(y0); y1 = gelu_tanh2(y1); y2 = gelu_tanh2(y2); y3 = gelu_tanh2(y3);
;                 u32x4 w; w.x = cvt_pk_bf16(y0.x, y0.y); w.y = cvt_pk_bf16(y1.x, y1.y); w.z = cvt_pk_bf16(y2.x, y2.y); w.w = cvt_pk_bf16(y3.x, y3.y);
;                 *(u32x4*)(yg + (size_t)(row * 16 + tl) * DS + g * 16 + h0) = w;
;                 y0 = y0 * F8_SY; y1 = y1 * F8_SY; y2 = y2 * F8_SY; y3 = y3 * F8_SY;
;                 u32x2 w8; w8.x = pk4_fp8(y0.x, y0.y, y1.x, y1.y); w8.y = pk4_fp8(y2.x, y2.y, y3.x, y3.y);
;                 *(u32x2*)(yg8 + (size_t)(row * 16 + tl) * DS + g * 16 + h0) = w8; }
	v_pk_fma_f32 v[74:75], v[14:15], v[74:75], v[76:77]
	v_pk_fma_f32 v[76:77], v[16:17], v[84:85], v[78:79]
	s_waitcnt vmcnt(15)
	v_pk_fma_f32 v[78:79], v[10:11], v[190:191], v[80:81]
	v_lshlrev_b32_e32 v202, 16, v205
	v_and_b32_e32 v203, 0xffff0000, v205
	v_pk_mul_f32 v[190:191], v[78:79], v[78:79]
	v_pk_fma_f32 v[80:81], v[12:13], v[202:203], v[82:83]
	v_pk_fma_f32 v[190:191], v[190:191], s[10:11], v[188:189] op_sel_hi:[1,0,0] neg_lo:[1,0,0] neg_hi:[1,0,0]
	v_pk_mul_f32 v[202:203], v[80:81], v[80:81]
	v_pk_mul_f32 v[190:191], v[78:79], v[190:191]
	v_pk_fma_f32 v[202:203], v[202:203], s[10:11], v[188:189] op_sel_hi:[1,0,0] neg_lo:[1,0,0] neg_hi:[1,0,0]
	v_exp_f32_e32 v190, v190
	v_exp_f32_e32 v191, v191
	v_pk_mul_f32 v[202:203], v[80:81], v[202:203]
	v_pk_mul_f32 v[82:83], v[74:75], v[74:75]
	v_pk_mul_f32 v[84:85], v[76:77], v[76:77]
	v_exp_f32_e32 v202, v202
	v_exp_f32_e32 v203, v203
	v_pk_fma_f32 v[82:83], v[82:83], s[10:11], v[188:189] op_sel_hi:[1,0,0] neg_lo:[1,0,0] neg_hi:[1,0,0]
	v_pk_fma_f32 v[84:85], v[84:85], s[10:11], v[188:189] op_sel_hi:[1,0,0] neg_lo:[1,0,0] neg_hi:[1,0,0]
	v_pk_mul_f32 v[82:83], v[74:75], v[82:83]
	v_pk_mul_f32 v[84:85], v[76:77], v[84:85]
	v_pk_add_f32 v[190:191], v[190:191], 1.0 op_sel_hi:[1,0]
	v_exp_f32_e32 v82, v82
	v_exp_f32_e32 v83, v83
	v_exp_f32_e32 v84, v84
	v_exp_f32_e32 v85, v85
	v_rcp_f32_e32 v190, v190
	v_rcp_f32_e32 v191, v191
	v_pk_add_f32 v[202:203], v[202:203], 1.0 op_sel_hi:[1,0]
	v_pk_add_f32 v[82:83], v[82:83], 1.0 op_sel_hi:[1,0]
	v_rcp_f32_e32 v202, v202
	v_rcp_f32_e32 v203, v203
	v_pk_add_f32 v[84:85], v[84:85], 1.0 op_sel_hi:[1,0]
	v_pk_mul_f32 v[78:79], v[78:79], v[190:191]
	v_add_u32_e32 v190, v115, v193
	v_rcp_f32_e32 v82, v82
	v_rcp_f32_e32 v83, v83
	v_rcp_f32_e32 v84, v84
	v_rcp_f32_e32 v85, v85
	v_ashrrev_i32_e32 v191, 31, v190
	v_pk_mul_f32 v[80:81], v[80:81], v[202:203]
	v_lshlrev_b64 v[202:203], 11, v[190:191]
	v_lshlrev_b64 v[190:191], 12, v[190:191]
	v_lshl_add_u64 v[190:191], s[14:15], 0, v[190:191]
	v_lshl_add_u64 v[204:205], v[190:191], 0, s[36:37]
	v_lshlrev_b32_e32 v190, 1, v0
	v_mov_b32_e32 v191, v1
	v_pk_mul_f32 v[82:83], v[74:75], v[82:83]
	v_pk_mul_f32 v[84:85], v[76:77], v[84:85]
	v_cvt_pk_bf16_f32 v74, v82, v83
	v_lshl_add_u64 v[204:205], v[204:205], 0, v[190:191]
	v_cvt_pk_bf16_f32 v75, v84, v85
	v_cvt_pk_bf16_f32 v76, v78, v79
	v_cvt_pk_bf16_f32 v77, v80, v81
	global_store_dwordx4 v[204:205], v[74:77], off
	s_nop 1
	v_pk_mul_f32 v[74:75], v[82:83], s[12:13] op_sel_hi:[1,0]
	v_pk_mul_f32 v[76:77], v[78:79], s[12:13] op_sel_hi:[1,0]
	v_mov_b32_e32 v78, v1
	v_mov_b32_e32 v79, v1
	v_cvt_pk_fp8_f32 v78, v74, v75
	v_cvt_pk_fp8_f32 v79, v76, v77
	v_pk_mul_f32 v[74:75], v[84:85], s[12:13] op_sel_hi:[1,0]
	v_pk_mul_f32 v[76:77], v[80:81], s[12:13] op_sel_hi:[1,0]
	v_cvt_pk_fp8_f32 v78, v74, v75 op_sel:[0,0,1]
	v_cvt_pk_fp8_f32 v79, v76, v77 op_sel:[0,0,1]
	v_lshl_add_u64 v[74:75], s[60:61], 0, v[202:203]
	v_lshl_add_u64 v[74:75], v[74:75], 0, s[2:3]
	v_lshl_add_u64 v[74:75], v[74:75], 0, v[0:1]
	global_store_dwordx2 v[74:75], v[78:79], off
	s_waitcnt vmcnt(16)
	v_lshlrev_b32_e32 v78, 16, v214
	v_and_b32_e32 v79, 0xffff0000, v214
	v_pk_fma_f32 v[78:79], v[10:11], v[78:79], v[176:177]
	v_lshlrev_b32_e32 v80, 16, v215
	v_and_b32_e32 v81, 0xffff0000, v215
	v_pk_mul_f32 v[176:177], v[78:79], v[78:79]
	v_pk_fma_f32 v[80:81], v[12:13], v[80:81], v[178:179]
	v_pk_fma_f32 v[176:177], v[176:177], s[10:11], v[188:189] op_sel_hi:[1,0,0] neg_lo:[1,0,0] neg_hi:[1,0,0]
	v_add_u32_e32 v74, 32, v192
	v_pk_mul_f32 v[176:177], v[78:79], v[176:177]
	v_pk_mul_f32 v[178:179], v[80:81], v[80:81]
	v_ashrrev_i32_e32 v192, 4, v74
	v_lshlrev_b32_e32 v74, 16, v212
	v_and_b32_e32 v75, 0xffff0000, v212
	v_lshlrev_b32_e32 v76, 16, v213
	v_and_b32_e32 v77, 0xffff0000, v213
	v_exp_f32_e32 v176, v176
	v_exp_f32_e32 v177, v177
	v_pk_fma_f32 v[178:179], v[178:179], s[10:11], v[188:189] op_sel_hi:[1,0,0] neg_lo:[1,0,0] neg_hi:[1,0,0]
	v_pk_fma_f32 v[74:75], v[14:15], v[74:75], v[180:181]
	v_pk_fma_f32 v[76:77], v[16:17], v[76:77], v[182:183]
	v_pk_mul_f32 v[178:179], v[80:81], v[178:179]
	v_pk_mul_f32 v[82:83], v[74:75], v[74:75]
	v_pk_mul_f32 v[84:85], v[76:77], v[76:77]
	v_exp_f32_e32 v178, v178
	v_exp_f32_e32 v179, v179
	v_pk_fma_f32 v[82:83], v[82:83], s[10:11], v[188:189] op_sel_hi:[1,0,0] neg_lo:[1,0,0] neg_hi:[1,0,0]
	v_pk_fma_f32 v[84:85], v[84:85], s[10:11], v[188:189] op_sel_hi:[1,0,0] neg_lo:[1,0,0] neg_hi:[1,0,0]
	v_pk_mul_f32 v[82:83], v[74:75], v[82:83]
	v_pk_mul_f32 v[84:85], v[76:77], v[84:85]
	v_pk_add_f32 v[176:177], v[176:177], 1.0 op_sel_hi:[1,0]
	v_exp_f32_e32 v82, v82
	v_exp_f32_e32 v83, v83
	v_exp_f32_e32 v84, v84
	v_exp_f32_e32 v85, v85
	v_rcp_f32_e32 v176, v176
	v_rcp_f32_e32 v177, v177
	v_pk_add_f32 v[178:179], v[178:179], 1.0 op_sel_hi:[1,0]
	v_pk_add_f32 v[82:83], v[82:83], 1.0 op_sel_hi:[1,0]
	v_rcp_f32_e32 v178, v178
	v_rcp_f32_e32 v179, v179
	v_pk_add_f32 v[84:85], v[84:85], 1.0 op_sel_hi:[1,0]
	v_pk_mul_f32 v[78:79], v[78:79], v[176:177]
	v_add_u32_e32 v176, v192, v193
	v_rcp_f32_e32 v82, v82
	v_rcp_f32_e32 v83, v83
	v_rcp_f32_e32 v84, v84
	v_rcp_f32_e32 v85, v85
	v_ashrrev_i32_e32 v177, 31, v176
	v_pk_mul_f32 v[80:81], v[80:81], v[178:179]
	v_lshlrev_b64 v[178:179], 11, v[176:177]
	v_lshlrev_b64 v[176:177], 12, v[176:177]
	v_lshl_add_u64 v[176:177], s[14:15], 0, v[176:177]
	v_lshl_add_u64 v[176:177], v[176:177], 0, s[36:37]
	v_pk_mul_f32 v[82:83], v[74:75], v[82:83]
	v_pk_mul_f32 v[84:85], v[76:77], v[84:85]
	v_cvt_pk_bf16_f32 v74, v82, v83
	v_lshl_add_u64 v[176:177], v[176:177], 0, v[190:191]
	v_cvt_pk_bf16_f32 v75, v84, v85
	v_cvt_pk_bf16_f32 v76, v78, v79
	v_cvt_pk_bf16_f32 v77, v80, v81
	global_store_dwordx4 v[176:177], v[74:77], off
	v_add_u32_e32 v176, 0x100, v193
	s_nop 0
	v_pk_mul_f32 v[74:75], v[82:83], s[12:13] op_sel_hi:[1,0]
	v_pk_mul_f32 v[76:77], v[78:79], s[12:13] op_sel_hi:[1,0]
	v_mov_b32_e32 v78, v1
	v_mov_b32_e32 v79, v1
	v_cvt_pk_fp8_f32 v78, v74, v75
	v_cvt_pk_fp8_f32 v79, v76, v77
	v_pk_mul_f32 v[74:75], v[84:85], s[12:13] op_sel_hi:[1,0]
	v_pk_mul_f32 v[76:77], v[80:81], s[12:13] op_sel_hi:[1,0]
	v_cvt_pk_fp8_f32 v78, v74, v75 op_sel:[0,0,1]
	v_cvt_pk_fp8_f32 v79, v76, v77 op_sel:[0,0,1]
	v_lshl_add_u64 v[74:75], s[60:61], 0, v[178:179]
	v_lshl_add_u64 v[74:75], v[74:75], 0, s[2:3]
	v_lshl_add_u64 v[74:75], v[74:75], 0, v[0:1]
	global_store_dwordx2 v[74:75], v[78:79], off
	s_waitcnt vmcnt(17)
; __device__ __forceinline__ unsigned cvt_pk_bf16(float lo, float hi) { unsigned r; asm volatile("v_cvt_pk_bf16_f32 %0, %1, %2" : "=v"(r) : "v"(lo), "v"(hi)); return r; }
;     __device__ __forceinline__ void operator()(const Acc& acc, const Unit& u, int wr, int wc, int fr, int fq) const {
;     ...
;         for (int idx = 0; idx < 8; ++idx) { const int ai = idx >> 2, m = idx & 3, row = row0 + ai * 128 + m * 16;
; #pragma unroll
;             for (int bj = 0; bj < 2; ++bj) { const int col = bj * 32 + colb, tl = col >> 4;
;                 const u32x4 uu = urow[idx][bj];
;                 const f32x4 a = acc[ai][bj][m][0], b = acc[ai][bj][m][1];
;                 f32x2 y0 = (f32x2){a[0], a[1]} + (f32x2){d0[0], d0[1]} * (f32x2){bf2f(uu.x & 0xffffu), bf2f(uu.x >> 16)}, y1 = (f32x2){a[2], a[3]} + (f32x2){d0[2], d0[3]} * (f32x2){bf2f(uu.y & 0xffffu), bf2f(uu.y >> 16)};
;                 f32x2 y2 = (f32x2){b[0], b[1]} + (f32x2){d1[0], d1[1]} * (f32x2){bf2f(uu.z & 0xffffu), bf2f(uu.z >> 16)}, y3 = (f32x2){b[2], b[3]} + (f32x2){d1[2], d1[3]} * (f32x2){bf2f(uu.w & 0xffffu), bf2f(uu.w >> 16)};
;                 y0 = gelu_tanh2(y0); y1 = gelu_tanh2(y1); y2 = gelu_tanh2(y2); y3 = gelu_tanh2(y3);
;                 u32x4 w; w.x = cvt_pk_bf16(y0.x, y0.y); w.y = cvt_pk_bf16(y1.x, y1.y); w.z = cvt_pk_bf16(y2.x, y2.y); w.w = cvt_pk_bf16(y3.x, y3.y);
;                 *(u32x4*)(yg + (size_t)(row * 16 + tl) * DS + g * 16 + h0) = w;
;                 y0 = y0 * F8_SY; y1 = y1 * F8_SY; y2 = y2 * F8_SY; y3 = y3 * F8_SY;
;                 u32x2 w8; w8.x = pk4_fp8(y0.x, y0.y, y1.x, y1.y); w8.y = pk4_fp8(y2.x, y2.y, y3.x, y3.y);
;                 *(u32x2*)(yg8 + (size_t)(row * 16 + tl) * DS + g * 16 + h0) = w8; }
	v_lshlrev_b32_e32 v78, 16, v186
	v_and_b32_e32 v79, 0xffff0000, v186
	v_pk_fma_f32 v[78:79], v[10:11], v[78:79], v[164:165]
	v_lshlrev_b32_e32 v80, 16, v187
	v_and_b32_e32 v81, 0xffff0000, v187
	v_pk_mul_f32 v[164:165], v[78:79], v[78:79]
	v_pk_fma_f32 v[80:81], v[12:13], v[80:81], v[166:167]
	v_pk_fma_f32 v[164:165], v[164:165], s[10:11], v[188:189] op_sel_hi:[1,0,0] neg_lo:[1,0,0] neg_hi:[1,0,0]
	v_pk_mul_f32 v[166:167], v[80:81], v[80:81]
	v_pk_mul_f32 v[164:165], v[78:79], v[164:165]
	v_lshlrev_b32_e32 v74, 16, v184
	v_and_b32_e32 v75, 0xffff0000, v184
	v_lshlrev_b32_e32 v76, 16, v185
	v_and_b32_e32 v77, 0xffff0000, v185
	v_exp_f32_e32 v164, v164
	v_exp_f32_e32 v165, v165
	v_pk_fma_f32 v[166:167], v[166:167], s[10:11], v[188:189] op_sel_hi:[1,0,0] neg_lo:[1,0,0] neg_hi:[1,0,0]
	v_pk_fma_f32 v[74:75], v[14:15], v[74:75], v[168:169]
	v_pk_fma_f32 v[76:77], v[16:17], v[76:77], v[170:171]
	v_pk_mul_f32 v[166:167], v[80:81], v[166:167]
	v_pk_mul_f32 v[82:83], v[74:75], v[74:75]
	v_pk_mul_f32 v[84:85], v[76:77], v[76:77]
	v_exp_f32_e32 v166, v166
	v_exp_f32_e32 v167, v167
	v_pk_fma_f32 v[82:83], v[82:83], s[10:11], v[188:189] op_sel_hi:[1,0,0] neg_lo:[1,0,0] neg_hi:[1,0,0]
	v_pk_fma_f32 v[84:85], v[84:85], s[10:11], v[188:189] op_sel_hi:[1,0,0] neg_lo:[1,0,0] neg_hi:[1,0,0]
	v_pk_mul_f32 v[82:83], v[74:75], v[82:83]
	v_pk_mul_f32 v[84:85], v[76:77], v[84:85]
	v_pk_add_f32 v[164:165], v[164:165], 1.0 op_sel_hi:[1,0]
	v_exp_f32_e32 v82, v82
	v_exp_f32_e32 v83, v83
	v_exp_f32_e32 v84, v84
	v_exp_f32_e32 v85, v85
	v_rcp_f32_e32 v164, v164
	v_rcp_f32_e32 v165, v165
	v_pk_add_f32 v[166:167], v[166:167], 1.0 op_sel_hi:[1,0]
	v_pk_add_f32 v[82:83], v[82:83], 1.0 op_sel_hi:[1,0]
	v_rcp_f32_e32 v166, v166
	v_rcp_f32_e32 v167, v167
	v_pk_add_f32 v[84:85], v[84:85], 1.0 op_sel_hi:[1,0]
	v_pk_mul_f32 v[78:79], v[78:79], v[164:165]
	v_add_u32_e32 v164, v176, v115
	v_rcp_f32_e32 v82, v82
	v_rcp_f32_e32 v83, v83
	v_rcp_f32_e32 v84, v84
	v_rcp_f32_e32 v85, v85
	v_ashrrev_i32_e32 v165, 31, v164
	v_pk_mul_f32 v[80:81], v[80:81], v[166:167]
	v_lshlrev_b64 v[166:167], 11, v[164:165]
	v_lshlrev_b64 v[164:165], 12, v[164:165]
	v_lshl_add_u64 v[164:165], s[14:15], 0, v[164:165]
	v_lshl_add_u64 v[164:165], v[164:165], 0, s[36:37]
	v_pk_mul_f32 v[82:83], v[74:75], v[82:83]
	v_pk_mul_f32 v[84:85], v[76:77], v[84:85]
	v_cvt_pk_bf16_f32 v74, v82, v83
	v_lshl_add_u64 v[164:165], v[164:165], 0, v[190:191]
	v_cvt_pk_bf16_f32 v75, v84, v85
	v_cvt_pk_bf16_f32 v76, v78, v79
	v_cvt_pk_bf16_f32 v77, v80, v81
	global_store_dwordx4 v[164:165], v[74:77], off
	s_nop 1
	v_pk_mul_f32 v[74:75], v[82:83], s[12:13] op_sel_hi:[1,0]
	v_pk_mul_f32 v[76:77], v[78:79], s[12:13] op_sel_hi:[1,0]
	v_mov_b32_e32 v78, v1
	v_mov_b32_e32 v79, v1
	v_cvt_pk_fp8_f32 v78, v74, v75
	v_cvt_pk_fp8_f32 v79, v76, v77
	v_pk_mul_f32 v[74:75], v[84:85], s[12:13] op_sel_hi:[1,0]
	v_pk_mul_f32 v[76:77], v[80:81], s[12:13] op_sel_hi:[1,0]
	v_cvt_pk_fp8_f32 v78, v74, v75 op_sel:[0,0,1]
	v_cvt_pk_fp8_f32 v79, v76, v77 op_sel:[0,0,1]
	v_lshl_add_u64 v[74:75], s[60:61], 0, v[166:167]
	v_lshl_add_u64 v[74:75], v[74:75], 0, s[2:3]
	v_lshl_add_u64 v[74:75], v[74:75], 0, v[0:1]
	global_store_dwordx2 v[74:75], v[78:79], off
	s_waitcnt vmcnt(18)
	v_lshlrev_b32_e32 v78, 16, v174
	v_and_b32_e32 v79, 0xffff0000, v174
	v_pk_fma_f32 v[78:79], v[10:11], v[78:79], v[152:153]
	v_lshlrev_b32_e32 v80, 16, v175
	v_and_b32_e32 v81, 0xffff0000, v175
	v_pk_mul_f32 v[152:153], v[78:79], v[78:79]
	v_pk_fma_f32 v[80:81], v[12:13], v[80:81], v[154:155]
	v_pk_fma_f32 v[152:153], v[152:153], s[10:11], v[188:189] op_sel_hi:[1,0,0] neg_lo:[1,0,0] neg_hi:[1,0,0]
	v_pk_mul_f32 v[154:155], v[80:81], v[80:81]
	v_pk_mul_f32 v[152:153], v[78:79], v[152:153]
	v_lshlrev_b32_e32 v74, 16, v172
	v_and_b32_e32 v75, 0xffff0000, v172
	v_lshlrev_b32_e32 v76, 16, v173
	v_and_b32_e32 v77, 0xffff0000, v173
	v_exp_f32_e32 v152, v152
	v_exp_f32_e32 v153, v153
	v_pk_fma_f32 v[154:155], v[154:155], s[10:11], v[188:189] op_sel_hi:[1,0,0] neg_lo:[1,0,0] neg_hi:[1,0,0]
	v_pk_fma_f32 v[74:75], v[14:15], v[74:75], v[156:157]
	v_pk_fma_f32 v[76:77], v[16:17], v[76:77], v[158:159]
	v_pk_mul_f32 v[154:155], v[80:81], v[154:155]
	v_pk_mul_f32 v[82:83], v[74:75], v[74:75]
	v_pk_mul_f32 v[84:85], v[76:77], v[76:77]
	v_exp_f32_e32 v154, v154
	v_exp_f32_e32 v155, v155
	v_pk_fma_f32 v[82:83], v[82:83], s[10:11], v[188:189] op_sel_hi:[1,0,0] neg_lo:[1,0,0] neg_hi:[1,0,0]
	v_pk_fma_f32 v[84:85], v[84:85], s[10:11], v[188:189] op_sel_hi:[1,0,0] neg_lo:[1,0,0] neg_hi:[1,0,0]
	v_pk_mul_f32 v[82:83], v[74:75], v[82:83]
	v_pk_mul_f32 v[84:85], v[76:77], v[84:85]
	v_pk_add_f32 v[152:153], v[152:153], 1.0 op_sel_hi:[1,0]
	v_exp_f32_e32 v82, v82
	v_exp_f32_e32 v83, v83
	v_exp_f32_e32 v84, v84
	v_exp_f32_e32 v85, v85
	v_rcp_f32_e32 v152, v152
	v_rcp_f32_e32 v153, v153
	v_pk_add_f32 v[154:155], v[154:155], 1.0 op_sel_hi:[1,0]
	v_pk_add_f32 v[82:83], v[82:83], 1.0 op_sel_hi:[1,0]
	v_rcp_f32_e32 v154, v154
	v_rcp_f32_e32 v155, v155
	v_pk_add_f32 v[84:85], v[84:85], 1.0 op_sel_hi:[1,0]
	v_pk_mul_f32 v[78:79], v[78:79], v[152:153]
	v_add_u32_e32 v152, v192, v176
	v_rcp_f32_e32 v82, v82
	v_rcp_f32_e32 v83, v83
	v_rcp_f32_e32 v84, v84
	v_rcp_f32_e32 v85, v85
	v_ashrrev_i32_e32 v153, 31, v152
	v_pk_mul_f32 v[80:81], v[80:81], v[154:155]
	v_lshlrev_b64 v[154:155], 11, v[152:153]
	v_lshlrev_b64 v[152:153], 12, v[152:153]
	v_lshl_add_u64 v[152:153], s[14:15], 0, v[152:153]
	v_lshl_add_u64 v[152:153], v[152:153], 0, s[36:37]
	v_pk_mul_f32 v[82:83], v[74:75], v[82:83]
	v_pk_mul_f32 v[84:85], v[76:77], v[84:85]
	v_cvt_pk_bf16_f32 v74, v82, v83
	v_lshl_add_u64 v[152:153], v[152:153], 0, v[190:191]
	v_cvt_pk_bf16_f32 v75, v84, v85
	v_cvt_pk_bf16_f32 v76, v78, v79
	v_cvt_pk_bf16_f32 v77, v80, v81
	global_store_dwordx4 v[152:153], v[74:77], off
	v_add_u32_e32 v152, 0x200, v193
	s_nop 0
	v_pk_mul_f32 v[74:75], v[82:83], s[12:13] op_sel_hi:[1,0]
	v_pk_mul_f32 v[76:77], v[78:79], s[12:13] op_sel_hi:[1,0]
	v_mov_b32_e32 v78, v1
	v_mov_b32_e32 v79, v1
	v_cvt_pk_fp8_f32 v78, v74, v75
	v_cvt_pk_fp8_f32 v79, v76, v77
	v_pk_mul_f32 v[74:75], v[84:85], s[12:13] op_sel_hi:[1,0]
	v_pk_mul_f32 v[76:77], v[80:81], s[12:13] op_sel_hi:[1,0]
	v_cvt_pk_fp8_f32 v78, v74, v75 op_sel:[0,0,1]
	v_cvt_pk_fp8_f32 v79, v76, v77 op_sel:[0,0,1]
	v_lshl_add_u64 v[74:75], s[60:61], 0, v[154:155]
	v_lshl_add_u64 v[74:75], v[74:75], 0, s[2:3]
	v_lshl_add_u64 v[74:75], v[74:75], 0, v[0:1]
	global_store_dwordx2 v[74:75], v[78:79], off
	s_waitcnt vmcnt(19)
; __device__ __forceinline__ unsigned cvt_pk_bf16(float lo, float hi) { unsigned r; asm volatile("v_cvt_pk_bf16_f32 %0, %1, %2" : "=v"(r) : "v"(lo), "v"(hi)); return r; }
;     __device__ __forceinline__ void operator()(const Acc& acc, const Unit& u, int wr, int wc, int fr, int fq) const {
;     ...
;         for (int idx = 0; idx < 8; ++idx) { const int ai = idx >> 2, m = idx & 3, row = row0 + ai * 128 + m * 16;
; #pragma unroll
;             for (int bj = 0; bj < 2; ++bj) { const int col = bj * 32 + colb, tl = col >> 4;
;                 const u32x4 uu = urow[idx][bj];
;                 const f32x4 a = acc[ai][bj][m][0], b = acc[ai][bj][m][1];
;                 f32x2 y0 = (f32x2){a[0], a[1]} + (f32x2){d0[0], d0[1]} * (f32x2){bf2f(uu.x & 0xffffu), bf2f(uu.x >> 16)}, y1 = (f32x2){a[2], a[3]} + (f32x2){d0[2], d0[3]} * (f32x2){bf2f(uu.y & 0xffffu), bf2f(uu.y >> 16)};
;                 f32x2 y2 = (f32x2){b[0], b[1]} + (f32x2){d1[0], d1[1]} * (f32x2){bf2f(uu.z & 0xffffu), bf2f(uu.z >> 16)}, y3 = (f32x2){b[2], b[3]} + (f32x2){d1[2], d1[3]} * (f32x2){bf2f(uu.w & 0xffffu), bf2f(uu.w >> 16)};
;                 y0 = gelu_tanh2(y0); y1 = gelu_tanh2(y1); y2 = gelu_tanh2(y2); y3 = gelu_tanh2(y3);
;                 u32x4 w; w.x = cvt_pk_bf16(y0.x, y0.y); w.y = cvt_pk_bf16(y1.x, y1.y); w.z = cvt_pk_bf16(y2.x, y2.y); w.w = cvt_pk_bf16(y3.x, y3.y);
;                 *(u32x4*)(yg + (size_t)(row * 16 + tl) * DS + g * 16 + h0) = w;
;                 y0 = y0 * F8_SY; y1 = y1 * F8_SY; y2 = y2 * F8_SY; y3 = y3 * F8_SY;
;                 u32x2 w8; w8.x = pk4_fp8(y0.x, y0.y, y1.x, y1.y); w8.y = pk4_fp8(y2.x, y2.y, y3.x, y3.y);
;                 *(u32x2*)(yg8 + (size_t)(row * 16 + tl) * DS + g * 16 + h0) = w8; }
	v_lshlrev_b32_e32 v78, 16, v162
	v_and_b32_e32 v79, 0xffff0000, v162
	v_pk_fma_f32 v[78:79], v[10:11], v[78:79], v[140:141]
	v_lshlrev_b32_e32 v80, 16, v163
	v_and_b32_e32 v81, 0xffff0000, v163
	v_pk_mul_f32 v[140:141], v[78:79], v[78:79]
	v_pk_fma_f32 v[80:81], v[12:13], v[80:81], v[142:143]
	v_pk_fma_f32 v[140:141], v[140:141], s[10:11], v[188:189] op_sel_hi:[1,0,0] neg_lo:[1,0,0] neg_hi:[1,0,0]
	v_pk_mul_f32 v[142:143], v[80:81], v[80:81]
	v_pk_mul_f32 v[140:141], v[78:79], v[140:141]
	v_lshlrev_b32_e32 v74, 16, v160
	v_and_b32_e32 v75, 0xffff0000, v160
	v_lshlrev_b32_e32 v76, 16, v161
	v_and_b32_e32 v77, 0xffff0000, v161
	v_exp_f32_e32 v140, v140
	v_exp_f32_e32 v141, v141
	v_pk_fma_f32 v[142:143], v[142:143], s[10:11], v[188:189] op_sel_hi:[1,0,0] neg_lo:[1,0,0] neg_hi:[1,0,0]
	v_pk_fma_f32 v[74:75], v[14:15], v[74:75], v[144:145]
	v_pk_fma_f32 v[76:77], v[16:17], v[76:77], v[146:147]
	v_pk_mul_f32 v[142:143], v[80:81], v[142:143]
	v_pk_mul_f32 v[82:83], v[74:75], v[74:75]
	v_pk_mul_f32 v[84:85], v[76:77], v[76:77]
	v_exp_f32_e32 v142, v142
	v_exp_f32_e32 v143, v143
	v_pk_fma_f32 v[82:83], v[82:83], s[10:11], v[188:189] op_sel_hi:[1,0,0] neg_lo:[1,0,0] neg_hi:[1,0,0]
	v_pk_fma_f32 v[84:85], v[84:85], s[10:11], v[188:189] op_sel_hi:[1,0,0] neg_lo:[1,0,0] neg_hi:[1,0,0]
	v_pk_mul_f32 v[82:83], v[74:75], v[82:83]
	v_pk_mul_f32 v[84:85], v[76:77], v[84:85]
	v_pk_add_f32 v[140:141], v[140:141], 1.0 op_sel_hi:[1,0]
	v_exp_f32_e32 v82, v82
	v_exp_f32_e32 v83, v83
	v_exp_f32_e32 v84, v84
	v_exp_f32_e32 v85, v85
	v_rcp_f32_e32 v140, v140
	v_rcp_f32_e32 v141, v141
	v_pk_add_f32 v[142:143], v[142:143], 1.0 op_sel_hi:[1,0]
	v_pk_add_f32 v[82:83], v[82:83], 1.0 op_sel_hi:[1,0]
	v_rcp_f32_e32 v142, v142
	v_rcp_f32_e32 v143, v143
	v_pk_add_f32 v[84:85], v[84:85], 1.0 op_sel_hi:[1,0]
	v_pk_mul_f32 v[78:79], v[78:79], v[140:141]
	v_add_u32_e32 v140, v152, v115
	v_rcp_f32_e32 v82, v82
	v_rcp_f32_e32 v83, v83
	v_rcp_f32_e32 v84, v84
	v_rcp_f32_e32 v85, v85
	v_ashrrev_i32_e32 v141, 31, v140
	v_pk_mul_f32 v[80:81], v[80:81], v[142:143]
	v_lshlrev_b64 v[142:143], 11, v[140:141]
	v_lshlrev_b64 v[140:141], 12, v[140:141]
	v_lshl_add_u64 v[140:141], s[14:15], 0, v[140:141]
	v_lshl_add_u64 v[140:141], v[140:141], 0, s[36:37]
	v_pk_mul_f32 v[82:83], v[74:75], v[82:83]
	v_pk_mul_f32 v[84:85], v[76:77], v[84:85]
	v_cvt_pk_bf16_f32 v74, v82, v83
	v_lshl_add_u64 v[140:141], v[140:141], 0, v[190:191]
	v_cvt_pk_bf16_f32 v75, v84, v85
	v_cvt_pk_bf16_f32 v76, v78, v79
	v_cvt_pk_bf16_f32 v77, v80, v81
	global_store_dwordx4 v[140:141], v[74:77], off
	s_nop 1
	v_pk_mul_f32 v[74:75], v[82:83], s[12:13] op_sel_hi:[1,0]
	v_pk_mul_f32 v[76:77], v[78:79], s[12:13] op_sel_hi:[1,0]
	v_mov_b32_e32 v78, v1
	v_mov_b32_e32 v79, v1
	v_cvt_pk_fp8_f32 v78, v74, v75
	v_cvt_pk_fp8_f32 v79, v76, v77
	v_pk_mul_f32 v[74:75], v[84:85], s[12:13] op_sel_hi:[1,0]
	v_pk_mul_f32 v[76:77], v[80:81], s[12:13] op_sel_hi:[1,0]
	v_cvt_pk_fp8_f32 v78, v74, v75 op_sel:[0,0,1]
	v_cvt_pk_fp8_f32 v79, v76, v77 op_sel:[0,0,1]
	v_lshl_add_u64 v[74:75], s[60:61], 0, v[142:143]
	v_lshl_add_u64 v[74:75], v[74:75], 0, s[2:3]
	v_lshl_add_u64 v[74:75], v[74:75], 0, v[0:1]
	global_store_dwordx2 v[74:75], v[78:79], off
	s_waitcnt vmcnt(20)
	v_lshlrev_b32_e32 v78, 16, v150
	v_and_b32_e32 v79, 0xffff0000, v150
	v_pk_fma_f32 v[78:79], v[10:11], v[78:79], v[128:129]
	v_lshlrev_b32_e32 v80, 16, v151
	v_and_b32_e32 v81, 0xffff0000, v151
	v_pk_mul_f32 v[128:129], v[78:79], v[78:79]
	v_pk_fma_f32 v[80:81], v[12:13], v[80:81], v[130:131]
	v_pk_fma_f32 v[128:129], v[128:129], s[10:11], v[188:189] op_sel_hi:[1,0,0] neg_lo:[1,0,0] neg_hi:[1,0,0]
	v_pk_mul_f32 v[130:131], v[80:81], v[80:81]
	v_pk_mul_f32 v[128:129], v[78:79], v[128:129]
	v_lshlrev_b32_e32 v74, 16, v148
	v_and_b32_e32 v75, 0xffff0000, v148
	v_lshlrev_b32_e32 v76, 16, v149
	v_and_b32_e32 v77, 0xffff0000, v149
	v_exp_f32_e32 v128, v128
	v_exp_f32_e32 v129, v129
	v_pk_fma_f32 v[130:131], v[130:131], s[10:11], v[188:189] op_sel_hi:[1,0,0] neg_lo:[1,0,0] neg_hi:[1,0,0]
	v_pk_fma_f32 v[74:75], v[14:15], v[74:75], v[132:133]
	v_pk_fma_f32 v[76:77], v[16:17], v[76:77], v[134:135]
	v_pk_mul_f32 v[130:131], v[80:81], v[130:131]
	v_pk_mul_f32 v[82:83], v[74:75], v[74:75]
	v_pk_mul_f32 v[84:85], v[76:77], v[76:77]
	v_exp_f32_e32 v130, v130
	v_exp_f32_e32 v131, v131
	v_pk_fma_f32 v[82:83], v[82:83], s[10:11], v[188:189] op_sel_hi:[1,0,0] neg_lo:[1,0,0] neg_hi:[1,0,0]
	v_pk_fma_f32 v[84:85], v[84:85], s[10:11], v[188:189] op_sel_hi:[1,0,0] neg_lo:[1,0,0] neg_hi:[1,0,0]
	v_pk_mul_f32 v[82:83], v[74:75], v[82:83]
	v_pk_mul_f32 v[84:85], v[76:77], v[84:85]
	v_pk_add_f32 v[128:129], v[128:129], 1.0 op_sel_hi:[1,0]
	v_exp_f32_e32 v82, v82
	v_exp_f32_e32 v83, v83
	v_exp_f32_e32 v84, v84
	v_exp_f32_e32 v85, v85
	v_rcp_f32_e32 v128, v128
	v_rcp_f32_e32 v129, v129
	v_pk_add_f32 v[130:131], v[130:131], 1.0 op_sel_hi:[1,0]
	v_pk_add_f32 v[82:83], v[82:83], 1.0 op_sel_hi:[1,0]
	v_rcp_f32_e32 v130, v130
	v_rcp_f32_e32 v131, v131
	v_pk_add_f32 v[84:85], v[84:85], 1.0 op_sel_hi:[1,0]
	v_pk_mul_f32 v[78:79], v[78:79], v[128:129]
	v_add_u32_e32 v128, v192, v152
	v_rcp_f32_e32 v82, v82
	v_rcp_f32_e32 v83, v83
	v_rcp_f32_e32 v84, v84
	v_rcp_f32_e32 v85, v85
	v_ashrrev_i32_e32 v129, 31, v128
	v_pk_mul_f32 v[80:81], v[80:81], v[130:131]
	v_lshlrev_b64 v[130:131], 11, v[128:129]
	v_lshlrev_b64 v[128:129], 12, v[128:129]
	v_lshl_add_u64 v[128:129], s[14:15], 0, v[128:129]
	v_lshl_add_u64 v[128:129], v[128:129], 0, s[36:37]
	v_pk_mul_f32 v[82:83], v[74:75], v[82:83]
	v_pk_mul_f32 v[84:85], v[76:77], v[84:85]
	v_cvt_pk_bf16_f32 v74, v82, v83
	v_lshl_add_u64 v[128:129], v[128:129], 0, v[190:191]
	v_cvt_pk_bf16_f32 v75, v84, v85
	v_cvt_pk_bf16_f32 v76, v78, v79
	v_cvt_pk_bf16_f32 v77, v80, v81
	global_store_dwordx4 v[128:129], v[74:77], off
	v_add_u32_e32 v128, 0x300, v193
	s_nop 0
	v_pk_mul_f32 v[74:75], v[82:83], s[12:13] op_sel_hi:[1,0]
	v_pk_mul_f32 v[76:77], v[78:79], s[12:13] op_sel_hi:[1,0]
	v_mov_b32_e32 v78, v1
	v_mov_b32_e32 v79, v1
	v_cvt_pk_fp8_f32 v78, v74, v75
	v_cvt_pk_fp8_f32 v79, v76, v77
	v_pk_mul_f32 v[74:75], v[84:85], s[12:13] op_sel_hi:[1,0]
	v_pk_mul_f32 v[76:77], v[80:81], s[12:13] op_sel_hi:[1,0]
	v_cvt_pk_fp8_f32 v78, v74, v75 op_sel:[0,0,1]
	v_cvt_pk_fp8_f32 v79, v76, v77 op_sel:[0,0,1]
	v_lshl_add_u64 v[74:75], s[60:61], 0, v[130:131]
	v_lshl_add_u64 v[74:75], v[74:75], 0, s[2:3]
	v_lshl_add_u64 v[74:75], v[74:75], 0, v[0:1]
	global_store_dwordx2 v[74:75], v[78:79], off
	s_waitcnt vmcnt(21)
; __device__ __forceinline__ unsigned cvt_pk_bf16(float lo, float hi) { unsigned r; asm volatile("v_cvt_pk_bf16_f32 %0, %1, %2" : "=v"(r) : "v"(lo), "v"(hi)); return r; }
;     __device__ __forceinline__ void operator()(const Acc& acc, const Unit& u, int wr, int wc, int fr, int fq) const {
;     ...
;         for (int idx = 0; idx < 8; ++idx) { const int ai = idx >> 2, m = idx & 3, row = row0 + ai * 128 + m * 16;
; #pragma unroll
;             for (int bj = 0; bj < 2; ++bj) { const int col = bj * 32 + colb, tl = col >> 4;
;                 const u32x4 uu = urow[idx][bj];
;                 const f32x4 a = acc[ai][bj][m][0], b = acc[ai][bj][m][1];
;                 f32x2 y0 = (f32x2){a[0], a[1]} + (f32x2){d0[0], d0[1]} * (f32x2){bf2f(uu.x & 0xffffu), bf2f(uu.x >> 16)}, y1 = (f32x2){a[2], a[3]} + (f32x2){d0[2], d0[3]} * (f32x2){bf2f(uu.y & 0xffffu), bf2f(uu.y >> 16)};
;                 f32x2 y2 = (f32x2){b[0], b[1]} + (f32x2){d1[0], d1[1]} * (f32x2){bf2f(uu.z & 0xffffu), bf2f(uu.z >> 16)}, y3 = (f32x2){b[2], b[3]} + (f32x2){d1[2], d1[3]} * (f32x2){bf2f(uu.w & 0xffffu), bf2f(uu.w >> 16)};
;                 y0 = gelu_tanh2(y0); y1 = gelu_tanh2(y1); y2 = gelu_tanh2(y2); y3 = gelu_tanh2(y3);
;                 u32x4 w; w.x = cvt_pk_bf16(y0.x, y0.y); w.y = cvt_pk_bf16(y1.x, y1.y); w.z = cvt_pk_bf16(y2.x, y2.y); w.w = cvt_pk_bf16(y3.x, y3.y);
;                 *(u32x4*)(yg + (size_t)(row * 16 + tl) * DS + g * 16 + h0) = w;
;                 y0 = y0 * F8_SY; y1 = y1 * F8_SY; y2 = y2 * F8_SY; y3 = y3 * F8_SY;
;                 u32x2 w8; w8.x = pk4_fp8(y0.x, y0.y, y1.x, y1.y); w8.y = pk4_fp8(y2.x, y2.y, y3.x, y3.y);
;                 *(u32x2*)(yg8 + (size_t)(row * 16 + tl) * DS + g * 16 + h0) = w8; }
	v_lshlrev_b32_e32 v78, 16, v138
	v_and_b32_e32 v79, 0xffff0000, v138
	v_pk_fma_f32 v[78:79], v[10:11], v[78:79], v[116:117]
	v_lshlrev_b32_e32 v80, 16, v139
	v_and_b32_e32 v81, 0xffff0000, v139
	v_pk_mul_f32 v[116:117], v[78:79], v[78:79]
	v_pk_fma_f32 v[80:81], v[12:13], v[80:81], v[118:119]
	v_pk_fma_f32 v[116:117], v[116:117], s[10:11], v[188:189] op_sel_hi:[1,0,0] neg_lo:[1,0,0] neg_hi:[1,0,0]
	v_pk_mul_f32 v[118:119], v[80:81], v[80:81]
	v_pk_mul_f32 v[116:117], v[78:79], v[116:117]
	v_lshlrev_b32_e32 v74, 16, v136
	v_and_b32_e32 v75, 0xffff0000, v136
	v_lshlrev_b32_e32 v76, 16, v137
	v_and_b32_e32 v77, 0xffff0000, v137
	v_exp_f32_e32 v116, v116
	v_exp_f32_e32 v117, v117
	v_pk_fma_f32 v[118:119], v[118:119], s[10:11], v[188:189] op_sel_hi:[1,0,0] neg_lo:[1,0,0] neg_hi:[1,0,0]
	v_pk_fma_f32 v[74:75], v[14:15], v[74:75], v[120:121]
	v_pk_fma_f32 v[76:77], v[16:17], v[76:77], v[122:123]
	v_pk_mul_f32 v[118:119], v[80:81], v[118:119]
	v_pk_mul_f32 v[82:83], v[74:75], v[74:75]
	v_pk_mul_f32 v[84:85], v[76:77], v[76:77]
	v_exp_f32_e32 v118, v118
	v_exp_f32_e32 v119, v119
	v_pk_fma_f32 v[82:83], v[82:83], s[10:11], v[188:189] op_sel_hi:[1,0,0] neg_lo:[1,0,0] neg_hi:[1,0,0]
	v_pk_fma_f32 v[84:85], v[84:85], s[10:11], v[188:189] op_sel_hi:[1,0,0] neg_lo:[1,0,0] neg_hi:[1,0,0]
	v_pk_mul_f32 v[82:83], v[74:75], v[82:83]
	v_pk_mul_f32 v[84:85], v[76:77], v[84:85]
	v_pk_add_f32 v[116:117], v[116:117], 1.0 op_sel_hi:[1,0]
	v_exp_f32_e32 v82, v82
	v_exp_f32_e32 v83, v83
	v_exp_f32_e32 v84, v84
	v_exp_f32_e32 v85, v85
	v_rcp_f32_e32 v116, v116
	v_rcp_f32_e32 v117, v117
	v_pk_add_f32 v[118:119], v[118:119], 1.0 op_sel_hi:[1,0]
	v_pk_add_f32 v[82:83], v[82:83], 1.0 op_sel_hi:[1,0]
	v_rcp_f32_e32 v118, v118
	v_rcp_f32_e32 v119, v119
	v_pk_add_f32 v[84:85], v[84:85], 1.0 op_sel_hi:[1,0]
	v_pk_mul_f32 v[78:79], v[78:79], v[116:117]
	v_add_u32_e32 v116, v128, v115
	v_rcp_f32_e32 v82, v82
	v_rcp_f32_e32 v83, v83
	v_rcp_f32_e32 v84, v84
	v_rcp_f32_e32 v85, v85
	v_ashrrev_i32_e32 v117, 31, v116
	v_pk_mul_f32 v[80:81], v[80:81], v[118:119]
	v_lshlrev_b64 v[118:119], 11, v[116:117]
	v_lshlrev_b64 v[116:117], 12, v[116:117]
	v_lshl_add_u64 v[116:117], s[14:15], 0, v[116:117]
	v_lshl_add_u64 v[116:117], v[116:117], 0, s[36:37]
	v_pk_mul_f32 v[82:83], v[74:75], v[82:83]
	v_pk_mul_f32 v[84:85], v[76:77], v[84:85]
	v_cvt_pk_bf16_f32 v74, v82, v83
	v_lshl_add_u64 v[116:117], v[116:117], 0, v[190:191]
	v_cvt_pk_bf16_f32 v75, v84, v85
	v_cvt_pk_bf16_f32 v76, v78, v79
	v_cvt_pk_bf16_f32 v77, v80, v81
	global_store_dwordx4 v[116:117], v[74:77], off
	s_nop 1
	v_pk_mul_f32 v[74:75], v[82:83], s[12:13] op_sel_hi:[1,0]
	v_pk_mul_f32 v[76:77], v[78:79], s[12:13] op_sel_hi:[1,0]
	v_mov_b32_e32 v78, v1
	v_mov_b32_e32 v79, v1
	v_cvt_pk_fp8_f32 v78, v74, v75
	v_cvt_pk_fp8_f32 v79, v76, v77
	v_pk_mul_f32 v[74:75], v[84:85], s[12:13] op_sel_hi:[1,0]
	v_pk_mul_f32 v[76:77], v[80:81], s[12:13] op_sel_hi:[1,0]
	v_cvt_pk_fp8_f32 v78, v74, v75 op_sel:[0,0,1]
	v_cvt_pk_fp8_f32 v79, v76, v77 op_sel:[0,0,1]
	v_lshl_add_u64 v[74:75], s[60:61], 0, v[118:119]
	v_lshl_add_u64 v[74:75], v[74:75], 0, s[2:3]
	v_lshl_add_u64 v[74:75], v[74:75], 0, v[0:1]
	global_store_dwordx2 v[74:75], v[78:79], off
	s_waitcnt vmcnt(22)
	v_lshlrev_b32_e32 v78, 16, v126
	v_and_b32_e32 v79, 0xffff0000, v126
	v_pk_fma_f32 v[78:79], v[10:11], v[78:79], v[102:103]
	v_lshlrev_b32_e32 v80, 16, v127
	v_and_b32_e32 v81, 0xffff0000, v127
	v_pk_mul_f32 v[102:103], v[78:79], v[78:79]
	v_pk_fma_f32 v[80:81], v[12:13], v[80:81], v[104:105]
	v_pk_fma_f32 v[102:103], v[102:103], s[10:11], v[188:189] op_sel_hi:[1,0,0] neg_lo:[1,0,0] neg_hi:[1,0,0]
	v_pk_mul_f32 v[104:105], v[80:81], v[80:81]
	v_pk_mul_f32 v[102:103], v[78:79], v[102:103]
	v_lshlrev_b32_e32 v74, 16, v124
	v_and_b32_e32 v75, 0xffff0000, v124
	v_lshlrev_b32_e32 v76, 16, v125
	v_and_b32_e32 v77, 0xffff0000, v125
	v_exp_f32_e32 v102, v102
	v_exp_f32_e32 v103, v103
	v_pk_fma_f32 v[104:105], v[104:105], s[10:11], v[188:189] op_sel_hi:[1,0,0] neg_lo:[1,0,0] neg_hi:[1,0,0]
	v_pk_fma_f32 v[74:75], v[14:15], v[74:75], v[106:107]
	v_pk_fma_f32 v[76:77], v[16:17], v[76:77], v[108:109]
	v_pk_mul_f32 v[104:105], v[80:81], v[104:105]
	v_pk_mul_f32 v[82:83], v[74:75], v[74:75]
	v_pk_mul_f32 v[84:85], v[76:77], v[76:77]
	v_exp_f32_e32 v104, v104
	v_exp_f32_e32 v105, v105
	v_pk_fma_f32 v[82:83], v[82:83], s[10:11], v[188:189] op_sel_hi:[1,0,0] neg_lo:[1,0,0] neg_hi:[1,0,0]
	v_pk_fma_f32 v[84:85], v[84:85], s[10:11], v[188:189] op_sel_hi:[1,0,0] neg_lo:[1,0,0] neg_hi:[1,0,0]
	v_pk_mul_f32 v[82:83], v[74:75], v[82:83]
	v_pk_mul_f32 v[84:85], v[76:77], v[84:85]
	v_pk_add_f32 v[102:103], v[102:103], 1.0 op_sel_hi:[1,0]
	v_exp_f32_e32 v82, v82
	v_exp_f32_e32 v83, v83
	v_exp_f32_e32 v84, v84
	v_exp_f32_e32 v85, v85
	v_rcp_f32_e32 v102, v102
	v_rcp_f32_e32 v103, v103
	v_pk_add_f32 v[104:105], v[104:105], 1.0 op_sel_hi:[1,0]
	v_pk_add_f32 v[82:83], v[82:83], 1.0 op_sel_hi:[1,0]
	v_rcp_f32_e32 v104, v104
	v_rcp_f32_e32 v105, v105
	v_pk_add_f32 v[84:85], v[84:85], 1.0 op_sel_hi:[1,0]
	v_pk_mul_f32 v[78:79], v[78:79], v[102:103]
	v_add_u32_e32 v102, v192, v128
	v_rcp_f32_e32 v82, v82
	v_rcp_f32_e32 v83, v83
	v_rcp_f32_e32 v84, v84
	v_rcp_f32_e32 v85, v85
	v_ashrrev_i32_e32 v103, 31, v102
	v_pk_mul_f32 v[80:81], v[80:81], v[104:105]
	v_lshlrev_b64 v[104:105], 11, v[102:103]
	v_lshlrev_b64 v[102:103], 12, v[102:103]
	v_lshl_add_u64 v[102:103], s[14:15], 0, v[102:103]
	v_lshl_add_u64 v[102:103], v[102:103], 0, s[36:37]
	v_pk_mul_f32 v[82:83], v[74:75], v[82:83]
	v_pk_mul_f32 v[84:85], v[76:77], v[84:85]
	v_cvt_pk_bf16_f32 v74, v82, v83
	v_lshl_add_u64 v[102:103], v[102:103], 0, v[190:191]
	v_cvt_pk_bf16_f32 v75, v84, v85
	v_cvt_pk_bf16_f32 v76, v78, v79
	v_cvt_pk_bf16_f32 v77, v80, v81
	global_store_dwordx4 v[102:103], v[74:77], off
	v_add_u32_e32 v102, 0x800, v193
	s_nop 0
	v_pk_mul_f32 v[74:75], v[82:83], s[12:13] op_sel_hi:[1,0]
	v_pk_mul_f32 v[76:77], v[78:79], s[12:13] op_sel_hi:[1,0]
	v_mov_b32_e32 v78, v1
	v_mov_b32_e32 v79, v1
	v_cvt_pk_fp8_f32 v78, v74, v75
	v_cvt_pk_fp8_f32 v79, v76, v77
	v_pk_mul_f32 v[74:75], v[84:85], s[12:13] op_sel_hi:[1,0]
	v_pk_mul_f32 v[76:77], v[80:81], s[12:13] op_sel_hi:[1,0]
	v_cvt_pk_fp8_f32 v78, v74, v75 op_sel:[0,0,1]
	v_cvt_pk_fp8_f32 v79, v76, v77 op_sel:[0,0,1]
	v_lshl_add_u64 v[74:75], s[60:61], 0, v[104:105]
	v_lshl_add_u64 v[74:75], v[74:75], 0, s[2:3]
	v_lshl_add_u64 v[74:75], v[74:75], 0, v[0:1]
	global_store_dwordx2 v[74:75], v[78:79], off
	s_waitcnt vmcnt(23)
; __device__ __forceinline__ unsigned cvt_pk_bf16(float lo, float hi) { unsigned r; asm volatile("v_cvt_pk_bf16_f32 %0, %1, %2" : "=v"(r) : "v"(lo), "v"(hi)); return r; }
;     __device__ __forceinline__ void operator()(const Acc& acc, const Unit& u, int wr, int wc, int fr, int fq) const {
;     ...
;         for (int idx = 0; idx < 8; ++idx) { const int ai = idx >> 2, m = idx & 3, row = row0 + ai * 128 + m * 16;
; #pragma unroll
;             for (int bj = 0; bj < 2; ++bj) { const int col = bj * 32 + colb, tl = col >> 4;
;                 const u32x4 uu = urow[idx][bj];
;                 const f32x4 a = acc[ai][bj][m][0], b = acc[ai][bj][m][1];
;                 f32x2 y0 = (f32x2){a[0], a[1]} + (f32x2){d0[0], d0[1]} * (f32x2){bf2f(uu.x & 0xffffu), bf2f(uu.x >> 16)}, y1 = (f32x2){a[2], a[3]} + (f32x2){d0[2], d0[3]} * (f32x2){bf2f(uu.y & 0xffffu), bf2f(uu.y >> 16)};
;                 f32x2 y2 = (f32x2){b[0], b[1]} + (f32x2){d1[0], d1[1]} * (f32x2){bf2f(uu.z & 0xffffu), bf2f(uu.z >> 16)}, y3 = (f32x2){b[2], b[3]} + (f32x2){d1[2], d1[3]} * (f32x2){bf2f(uu.w & 0xffffu), bf2f(uu.w >> 16)};
;                 y0 = gelu_tanh2(y0); y1 = gelu_tanh2(y1); y2 = gelu_tanh2(y2); y3 = gelu_tanh2(y3);
;                 u32x4 w; w.x = cvt_pk_bf16(y0.x, y0.y); w.y = cvt_pk_bf16(y1.x, y1.y); w.z = cvt_pk_bf16(y2.x, y2.y); w.w = cvt_pk_bf16(y3.x, y3.y);
;                 *(u32x4*)(yg + (size_t)(row * 16 + tl) * DS + g * 16 + h0) = w;
;                 y0 = y0 * F8_SY; y1 = y1 * F8_SY; y2 = y2 * F8_SY; y3 = y3 * F8_SY;
;                 u32x2 w8; w8.x = pk4_fp8(y0.x, y0.y, y1.x, y1.y); w8.y = pk4_fp8(y2.x, y2.y, y3.x, y3.y);
;                 *(u32x2*)(yg8 + (size_t)(row * 16 + tl) * DS + g * 16 + h0) = w8; }
	v_lshlrev_b32_e32 v78, 16, v112
	v_and_b32_e32 v79, 0xffff0000, v112
	v_pk_fma_f32 v[78:79], v[10:11], v[78:79], v[90:91]
	v_lshlrev_b32_e32 v80, 16, v113
	v_and_b32_e32 v81, 0xffff0000, v113
	v_pk_mul_f32 v[90:91], v[78:79], v[78:79]
	v_pk_fma_f32 v[80:81], v[12:13], v[80:81], v[92:93]
	v_pk_fma_f32 v[90:91], v[90:91], s[10:11], v[188:189] op_sel_hi:[1,0,0] neg_lo:[1,0,0] neg_hi:[1,0,0]
	v_pk_mul_f32 v[92:93], v[80:81], v[80:81]
	v_pk_mul_f32 v[90:91], v[78:79], v[90:91]
	v_lshlrev_b32_e32 v74, 16, v110
	v_and_b32_e32 v75, 0xffff0000, v110
	v_lshlrev_b32_e32 v76, 16, v111
	v_and_b32_e32 v77, 0xffff0000, v111
	v_exp_f32_e32 v90, v90
	v_exp_f32_e32 v91, v91
	v_pk_fma_f32 v[92:93], v[92:93], s[10:11], v[188:189] op_sel_hi:[1,0,0] neg_lo:[1,0,0] neg_hi:[1,0,0]
	v_pk_fma_f32 v[74:75], v[14:15], v[74:75], v[94:95]
	v_pk_fma_f32 v[76:77], v[16:17], v[76:77], v[96:97]
	v_pk_mul_f32 v[92:93], v[80:81], v[92:93]
	v_pk_mul_f32 v[82:83], v[74:75], v[74:75]
	v_pk_mul_f32 v[84:85], v[76:77], v[76:77]
	v_exp_f32_e32 v92, v92
	v_exp_f32_e32 v93, v93
	v_pk_fma_f32 v[82:83], v[82:83], s[10:11], v[188:189] op_sel_hi:[1,0,0] neg_lo:[1,0,0] neg_hi:[1,0,0]
	v_pk_fma_f32 v[84:85], v[84:85], s[10:11], v[188:189] op_sel_hi:[1,0,0] neg_lo:[1,0,0] neg_hi:[1,0,0]
	v_pk_mul_f32 v[82:83], v[74:75], v[82:83]
	v_pk_mul_f32 v[84:85], v[76:77], v[84:85]
	v_pk_add_f32 v[90:91], v[90:91], 1.0 op_sel_hi:[1,0]
	v_exp_f32_e32 v82, v82
	v_exp_f32_e32 v83, v83
	v_exp_f32_e32 v84, v84
	v_exp_f32_e32 v85, v85
	v_rcp_f32_e32 v90, v90
	v_rcp_f32_e32 v91, v91
	v_pk_add_f32 v[92:93], v[92:93], 1.0 op_sel_hi:[1,0]
	v_pk_add_f32 v[82:83], v[82:83], 1.0 op_sel_hi:[1,0]
	v_rcp_f32_e32 v92, v92
	v_rcp_f32_e32 v93, v93
	v_pk_add_f32 v[84:85], v[84:85], 1.0 op_sel_hi:[1,0]
	v_pk_mul_f32 v[78:79], v[78:79], v[90:91]
	v_add_u32_e32 v90, v102, v115
	v_rcp_f32_e32 v82, v82
	v_rcp_f32_e32 v83, v83
	v_rcp_f32_e32 v84, v84
	v_rcp_f32_e32 v85, v85
	v_ashrrev_i32_e32 v91, 31, v90
	v_pk_mul_f32 v[80:81], v[80:81], v[92:93]
	v_lshlrev_b64 v[92:93], 11, v[90:91]
	v_lshlrev_b64 v[90:91], 12, v[90:91]
	v_lshl_add_u64 v[90:91], s[14:15], 0, v[90:91]
	v_lshl_add_u64 v[90:91], v[90:91], 0, s[36:37]
	v_pk_mul_f32 v[82:83], v[74:75], v[82:83]
	v_pk_mul_f32 v[84:85], v[76:77], v[84:85]
	v_cvt_pk_bf16_f32 v74, v82, v83
	v_lshl_add_u64 v[90:91], v[90:91], 0, v[190:191]
	v_cvt_pk_bf16_f32 v75, v84, v85
	v_cvt_pk_bf16_f32 v76, v78, v79
	v_cvt_pk_bf16_f32 v77, v80, v81
	global_store_dwordx4 v[90:91], v[74:77], off
	s_nop 1
	v_pk_mul_f32 v[74:75], v[82:83], s[12:13] op_sel_hi:[1,0]
	v_pk_mul_f32 v[76:77], v[78:79], s[12:13] op_sel_hi:[1,0]
	v_mov_b32_e32 v78, v1
	v_mov_b32_e32 v79, v1
	v_cvt_pk_fp8_f32 v78, v74, v75
	v_cvt_pk_fp8_f32 v79, v76, v77
	v_pk_mul_f32 v[74:75], v[84:85], s[12:13] op_sel_hi:[1,0]
	v_pk_mul_f32 v[76:77], v[80:81], s[12:13] op_sel_hi:[1,0]
	v_cvt_pk_fp8_f32 v78, v74, v75 op_sel:[0,0,1]
	v_cvt_pk_fp8_f32 v79, v76, v77 op_sel:[0,0,1]
	v_lshl_add_u64 v[74:75], s[60:61], 0, v[92:93]
	v_lshl_add_u64 v[74:75], v[74:75], 0, s[2:3]
	v_lshl_add_u64 v[74:75], v[74:75], 0, v[0:1]
	global_store_dwordx2 v[74:75], v[78:79], off
	s_waitcnt vmcnt(24)
	v_lshlrev_b32_e32 v78, 16, v100
	v_and_b32_e32 v79, 0xffff0000, v100
	v_lshlrev_b32_e32 v74, 16, v98
	v_and_b32_e32 v75, 0xffff0000, v98
	v_pk_fma_f32 v[78:79], v[10:11], v[78:79], v[208:209]
	v_pk_fma_f32 v[74:75], v[14:15], v[74:75], v[86:87]
	v_lshlrev_b32_e32 v80, 16, v101
	v_and_b32_e32 v81, 0xffff0000, v101
	v_pk_mul_f32 v[86:87], v[78:79], v[78:79]
	v_lshlrev_b32_e32 v76, 16, v99
	v_and_b32_e32 v77, 0xffff0000, v99
	v_pk_fma_f32 v[80:81], v[12:13], v[80:81], v[210:211]
	v_pk_fma_f32 v[86:87], v[86:87], s[10:11], v[188:189] op_sel_hi:[1,0,0] neg_lo:[1,0,0] neg_hi:[1,0,0]
	v_pk_fma_f32 v[76:77], v[16:17], v[76:77], v[88:89]
	v_pk_mul_f32 v[86:87], v[78:79], v[86:87]
	v_pk_mul_f32 v[88:89], v[80:81], v[80:81]
	v_exp_f32_e32 v86, v86
	v_exp_f32_e32 v87, v87
	v_pk_fma_f32 v[88:89], v[88:89], s[10:11], v[188:189] op_sel_hi:[1,0,0] neg_lo:[1,0,0] neg_hi:[1,0,0]
	v_pk_mul_f32 v[82:83], v[74:75], v[74:75]
	v_pk_mul_f32 v[88:89], v[80:81], v[88:89]
	v_pk_mul_f32 v[84:85], v[76:77], v[76:77]
	v_exp_f32_e32 v88, v88
	v_exp_f32_e32 v89, v89
	v_pk_fma_f32 v[82:83], v[82:83], s[10:11], v[188:189] op_sel_hi:[1,0,0] neg_lo:[1,0,0] neg_hi:[1,0,0]
	v_pk_fma_f32 v[84:85], v[84:85], s[10:11], v[188:189] op_sel_hi:[1,0,0] neg_lo:[1,0,0] neg_hi:[1,0,0]
	v_pk_mul_f32 v[82:83], v[74:75], v[82:83]
	v_pk_mul_f32 v[84:85], v[76:77], v[84:85]
	v_pk_add_f32 v[86:87], v[86:87], 1.0 op_sel_hi:[1,0]
	v_exp_f32_e32 v82, v82
	v_exp_f32_e32 v83, v83
	v_exp_f32_e32 v84, v84
	v_exp_f32_e32 v85, v85
	v_rcp_f32_e32 v86, v86
	v_rcp_f32_e32 v87, v87
	v_pk_add_f32 v[88:89], v[88:89], 1.0 op_sel_hi:[1,0]
	v_pk_add_f32 v[82:83], v[82:83], 1.0 op_sel_hi:[1,0]
	v_rcp_f32_e32 v88, v88
	v_rcp_f32_e32 v89, v89
	v_pk_add_f32 v[84:85], v[84:85], 1.0 op_sel_hi:[1,0]
	v_pk_mul_f32 v[78:79], v[78:79], v[86:87]
	v_add_u32_e32 v86, v192, v102
	v_rcp_f32_e32 v82, v82
	v_rcp_f32_e32 v83, v83
	v_rcp_f32_e32 v84, v84
	v_rcp_f32_e32 v85, v85
	v_ashrrev_i32_e32 v87, 31, v86
	v_pk_mul_f32 v[80:81], v[80:81], v[88:89]
	v_lshlrev_b64 v[88:89], 11, v[86:87]
	v_lshlrev_b64 v[86:87], 12, v[86:87]
	v_lshl_add_u64 v[86:87], s[14:15], 0, v[86:87]
	v_lshl_add_u64 v[86:87], v[86:87], 0, s[36:37]
	v_pk_mul_f32 v[82:83], v[74:75], v[82:83]
	v_pk_mul_f32 v[84:85], v[76:77], v[84:85]
	v_cvt_pk_bf16_f32 v74, v82, v83
	v_lshl_add_u64 v[86:87], v[86:87], 0, v[190:191]
	v_cvt_pk_bf16_f32 v75, v84, v85
	v_cvt_pk_bf16_f32 v76, v78, v79
	v_cvt_pk_bf16_f32 v77, v80, v81
	global_store_dwordx4 v[86:87], v[74:77], off
	s_nop 1
	v_pk_mul_f32 v[74:75], v[82:83], s[12:13] op_sel_hi:[1,0]
	v_pk_mul_f32 v[76:77], v[78:79], s[12:13] op_sel_hi:[1,0]
	v_mov_b32_e32 v78, v1
	v_mov_b32_e32 v79, v1
	v_cvt_pk_fp8_f32 v78, v74, v75
	v_cvt_pk_fp8_f32 v79, v76, v77
	v_pk_mul_f32 v[74:75], v[84:85], s[12:13] op_sel_hi:[1,0]
	v_pk_mul_f32 v[76:77], v[80:81], s[12:13] op_sel_hi:[1,0]
	v_cvt_pk_fp8_f32 v78, v74, v75 op_sel:[0,0,1]
	v_cvt_pk_fp8_f32 v79, v76, v77 op_sel:[0,0,1]
	v_lshl_add_u64 v[74:75], s[60:61], 0, v[88:89]
	v_lshl_add_u64 v[74:75], v[74:75], 0, s[2:3]
	v_lshl_add_u64 v[74:75], v[74:75], 0, v[0:1]
	global_store_dwordx2 v[74:75], v[78:79], off
	s_waitcnt vmcnt(25)
; __device__ __forceinline__ unsigned cvt_pk_bf16(float lo, float hi) { unsigned r; asm volatile("v_cvt_pk_bf16_f32 %0, %1, %2" : "=v"(r) : "v"(lo), "v"(hi)); return r; }
;     __device__ __forceinline__ void operator()(const Acc& acc, const Unit& u, int wr, int wc, int fr, int fq) const {
;     ...
;         for (int idx = 0; idx < 8; ++idx) { const int ai = idx >> 2, m = idx & 3, row = row0 + ai * 128 + m * 16;
; #pragma unroll
;             for (int bj = 0; bj < 2; ++bj) { const int col = bj * 32 + colb, tl = col >> 4;
;                 const u32x4 uu = urow[idx][bj];
;                 const f32x4 a = acc[ai][bj][m][0], b = acc[ai][bj][m][1];
;                 f32x2 y0 = (f32x2){a[0], a[1]} + (f32x2){d0[0], d0[1]} * (f32x2){bf2f(uu.x & 0xffffu), bf2f(uu.x >> 16)}, y1 = (f32x2){a[2], a[3]} + (f32x2){d0[2], d0[3]} * (f32x2){bf2f(uu.y & 0xffffu), bf2f(uu.y >> 16)};
;                 f32x2 y2 = (f32x2){b[0], b[1]} + (f32x2){d1[0], d1[1]} * (f32x2){bf2f(uu.z & 0xffffu), bf2f(uu.z >> 16)}, y3 = (f32x2){b[2], b[3]} + (f32x2){d1[2], d1[3]} * (f32x2){bf2f(uu.w & 0xffffu), bf2f(uu.w >> 16)};
;                 y0 = gelu_tanh2(y0); y1 = gelu_tanh2(y1); y2 = gelu_tanh2(y2); y3 = gelu_tanh2(y3);
;                 u32x4 w; w.x = cvt_pk_bf16(y0.x, y0.y); w.y = cvt_pk_bf16(y1.x, y1.y); w.z = cvt_pk_bf16(y2.x, y2.y); w.w = cvt_pk_bf16(y3.x, y3.y);
;                 *(u32x4*)(yg + (size_t)(row * 16 + tl) * DS + g * 16 + h0) = w;
;                 y0 = y0 * F8_SY; y1 = y1 * F8_SY; y2 = y2 * F8_SY; y3 = y3 * F8_SY;
;                 u32x2 w8; w8.x = pk4_fp8(y0.x, y0.y, y1.x, y1.y); w8.y = pk4_fp8(y2.x, y2.y, y3.x, y3.y);
;                 *(u32x2*)(yg8 + (size_t)(row * 16 + tl) * DS + g * 16 + h0) = w8; }
	v_lshlrev_b32_e32 v74, 16, v198
	v_and_b32_e32 v75, 0xffff0000, v198
	v_pk_fma_f32 v[70:71], v[14:15], v[74:75], v[70:71]
	v_lshlrev_b32_e32 v74, 16, v199
	v_and_b32_e32 v75, 0xffff0000, v199
	v_pk_fma_f32 v[72:73], v[16:17], v[74:75], v[72:73]
	v_lshlrev_b32_e32 v74, 16, v200
	v_and_b32_e32 v75, 0xffff0000, v200
	v_pk_fma_f32 v[66:67], v[10:11], v[74:75], v[66:67]
	v_lshlrev_b32_e32 v74, 16, v201
	v_and_b32_e32 v75, 0xffff0000, v201
	v_pk_fma_f32 v[68:69], v[12:13], v[74:75], v[68:69]
	v_pk_mul_f32 v[74:75], v[70:71], v[70:71]
	v_pk_mul_f32 v[78:79], v[66:67], v[66:67]
	v_pk_fma_f32 v[74:75], v[74:75], s[10:11], v[188:189] op_sel_hi:[1,0,0] neg_lo:[1,0,0] neg_hi:[1,0,0]
	v_pk_fma_f32 v[78:79], v[78:79], s[10:11], v[188:189] op_sel_hi:[1,0,0] neg_lo:[1,0,0] neg_hi:[1,0,0]
	v_pk_mul_f32 v[74:75], v[70:71], v[74:75]
	v_pk_mul_f32 v[76:77], v[72:73], v[72:73]
	v_pk_mul_f32 v[78:79], v[66:67], v[78:79]
	v_pk_mul_f32 v[80:81], v[68:69], v[68:69]
	v_exp_f32_e32 v74, v74
	v_exp_f32_e32 v75, v75
	v_pk_fma_f32 v[76:77], v[76:77], s[10:11], v[188:189] op_sel_hi:[1,0,0] neg_lo:[1,0,0] neg_hi:[1,0,0]
	v_exp_f32_e32 v78, v78
	v_exp_f32_e32 v79, v79
	v_pk_fma_f32 v[80:81], v[80:81], s[10:11], v[188:189] op_sel_hi:[1,0,0] neg_lo:[1,0,0] neg_hi:[1,0,0]
	v_pk_mul_f32 v[76:77], v[72:73], v[76:77]
	v_pk_mul_f32 v[80:81], v[68:69], v[80:81]
	v_exp_f32_e32 v76, v76
	v_exp_f32_e32 v77, v77
	v_exp_f32_e32 v80, v80
	v_exp_f32_e32 v81, v81
	v_pk_add_f32 v[74:75], v[74:75], 1.0 op_sel_hi:[1,0]
	v_pk_add_f32 v[78:79], v[78:79], 1.0 op_sel_hi:[1,0]
	v_rcp_f32_e32 v74, v74
	v_rcp_f32_e32 v75, v75
	v_rcp_f32_e32 v78, v78
	v_rcp_f32_e32 v79, v79
	v_pk_add_f32 v[76:77], v[76:77], 1.0 op_sel_hi:[1,0]
	v_pk_add_f32 v[80:81], v[80:81], 1.0 op_sel_hi:[1,0]
	v_rcp_f32_e32 v76, v76
	v_rcp_f32_e32 v77, v77
	v_rcp_f32_e32 v80, v80
	v_rcp_f32_e32 v81, v81
	v_add_u32_e32 v82, 0x900, v193
	v_pk_mul_f32 v[70:71], v[70:71], v[74:75]
	v_pk_mul_f32 v[74:75], v[66:67], v[78:79]
	v_add_u32_e32 v78, v82, v115
	v_ashrrev_i32_e32 v79, 31, v78
	v_pk_mul_f32 v[72:73], v[72:73], v[76:77]
	v_pk_mul_f32 v[76:77], v[68:69], v[80:81]
	v_lshlrev_b64 v[80:81], 11, v[78:79]
	v_lshlrev_b64 v[78:79], 12, v[78:79]
	v_lshl_add_u64 v[78:79], s[14:15], 0, v[78:79]
	v_lshl_add_u64 v[78:79], v[78:79], 0, s[36:37]
	v_cvt_pk_bf16_f32 v66, v70, v71
	v_cvt_pk_bf16_f32 v67, v72, v73
	v_cvt_pk_bf16_f32 v68, v74, v75
	v_cvt_pk_bf16_f32 v69, v76, v77
	v_lshl_add_u64 v[78:79], v[78:79], 0, v[190:191]
	global_store_dwordx4 v[78:79], v[66:69], off
	s_nop 1
	v_pk_mul_f32 v[66:67], v[70:71], s[12:13] op_sel_hi:[1,0]
	v_pk_mul_f32 v[68:69], v[74:75], s[12:13] op_sel_hi:[1,0]
	v_mov_b32_e32 v70, v1
	v_mov_b32_e32 v71, v1
	v_cvt_pk_fp8_f32 v70, v66, v67
	v_cvt_pk_fp8_f32 v71, v68, v69
	v_pk_mul_f32 v[66:67], v[72:73], s[12:13] op_sel_hi:[1,0]
	v_pk_mul_f32 v[68:69], v[76:77], s[12:13] op_sel_hi:[1,0]
	v_cvt_pk_fp8_f32 v70, v66, v67 op_sel:[0,0,1]
	v_cvt_pk_fp8_f32 v71, v68, v69 op_sel:[0,0,1]
	v_lshl_add_u64 v[66:67], s[60:61], 0, v[80:81]
	v_lshl_add_u64 v[66:67], v[66:67], 0, s[2:3]
	v_lshl_add_u64 v[66:67], v[66:67], 0, v[0:1]
	global_store_dwordx2 v[66:67], v[70:71], off
	s_waitcnt vmcnt(26)
	v_lshlrev_b32_e32 v66, 16, v194
	v_and_b32_e32 v67, 0xffff0000, v194
	v_pk_fma_f32 v[62:63], v[14:15], v[66:67], v[62:63]
	v_lshlrev_b32_e32 v66, 16, v195
	v_and_b32_e32 v67, 0xffff0000, v195
	v_pk_fma_f32 v[64:65], v[16:17], v[66:67], v[64:65]
	v_lshlrev_b32_e32 v66, 16, v196
	v_and_b32_e32 v67, 0xffff0000, v196
	v_pk_fma_f32 v[58:59], v[10:11], v[66:67], v[58:59]
	v_lshlrev_b32_e32 v66, 16, v197
	v_and_b32_e32 v67, 0xffff0000, v197
	v_pk_fma_f32 v[60:61], v[12:13], v[66:67], v[60:61]
	v_pk_mul_f32 v[66:67], v[62:63], v[62:63]
	v_pk_mul_f32 v[70:71], v[58:59], v[58:59]
	v_pk_fma_f32 v[66:67], v[66:67], s[10:11], v[188:189] op_sel_hi:[1,0,0] neg_lo:[1,0,0] neg_hi:[1,0,0]
	v_pk_fma_f32 v[70:71], v[70:71], s[10:11], v[188:189] op_sel_hi:[1,0,0] neg_lo:[1,0,0] neg_hi:[1,0,0]
	v_pk_mul_f32 v[66:67], v[62:63], v[66:67]
	v_pk_mul_f32 v[68:69], v[64:65], v[64:65]
	v_pk_mul_f32 v[70:71], v[58:59], v[70:71]
	v_pk_mul_f32 v[72:73], v[60:61], v[60:61]
	v_exp_f32_e32 v66, v66
	v_exp_f32_e32 v67, v67
	v_pk_fma_f32 v[68:69], v[68:69], s[10:11], v[188:189] op_sel_hi:[1,0,0] neg_lo:[1,0,0] neg_hi:[1,0,0]
	v_exp_f32_e32 v70, v70
	v_exp_f32_e32 v71, v71
	v_pk_fma_f32 v[72:73], v[72:73], s[10:11], v[188:189] op_sel_hi:[1,0,0] neg_lo:[1,0,0] neg_hi:[1,0,0]
	v_pk_mul_f32 v[68:69], v[64:65], v[68:69]
	v_pk_mul_f32 v[72:73], v[60:61], v[72:73]
	v_exp_f32_e32 v68, v68
	v_exp_f32_e32 v69, v69
	v_exp_f32_e32 v72, v72
	v_exp_f32_e32 v73, v73
	v_pk_add_f32 v[66:67], v[66:67], 1.0 op_sel_hi:[1,0]
	v_pk_add_f32 v[70:71], v[70:71], 1.0 op_sel_hi:[1,0]
	v_rcp_f32_e32 v66, v66
	v_rcp_f32_e32 v67, v67
	v_rcp_f32_e32 v70, v70
	v_rcp_f32_e32 v71, v71
	v_pk_add_f32 v[68:69], v[68:69], 1.0 op_sel_hi:[1,0]
	v_pk_add_f32 v[72:73], v[72:73], 1.0 op_sel_hi:[1,0]
	v_rcp_f32_e32 v68, v68
	v_rcp_f32_e32 v69, v69
	v_rcp_f32_e32 v72, v72
	v_rcp_f32_e32 v73, v73
	v_pk_mul_f32 v[62:63], v[62:63], v[66:67]
	v_pk_mul_f32 v[66:67], v[58:59], v[70:71]
	v_add_u32_e32 v70, v192, v82
	v_ashrrev_i32_e32 v71, 31, v70
	v_pk_mul_f32 v[64:65], v[64:65], v[68:69]
	v_pk_mul_f32 v[68:69], v[60:61], v[72:73]
	v_lshlrev_b64 v[72:73], 11, v[70:71]
	v_lshlrev_b64 v[70:71], 12, v[70:71]
	v_lshl_add_u64 v[70:71], s[14:15], 0, v[70:71]
	v_lshl_add_u64 v[70:71], v[70:71], 0, s[36:37]
	v_cvt_pk_bf16_f32 v58, v62, v63
	v_cvt_pk_bf16_f32 v59, v64, v65
	v_cvt_pk_bf16_f32 v60, v66, v67
	v_cvt_pk_bf16_f32 v61, v68, v69
	v_lshl_add_u64 v[70:71], v[70:71], 0, v[190:191]
	global_store_dwordx4 v[70:71], v[58:61], off
	s_nop 1
	v_pk_mul_f32 v[58:59], v[62:63], s[12:13] op_sel_hi:[1,0]
	v_pk_mul_f32 v[60:61], v[66:67], s[12:13] op_sel_hi:[1,0]
	v_mov_b32_e32 v62, v1
	v_mov_b32_e32 v63, v1
	v_cvt_pk_fp8_f32 v62, v58, v59
	v_cvt_pk_fp8_f32 v63, v60, v61
	v_pk_mul_f32 v[58:59], v[64:65], s[12:13] op_sel_hi:[1,0]
	v_pk_mul_f32 v[60:61], v[68:69], s[12:13] op_sel_hi:[1,0]
	v_cvt_pk_fp8_f32 v62, v58, v59 op_sel:[0,0,1]
	v_cvt_pk_fp8_f32 v63, v60, v61 op_sel:[0,0,1]
	v_lshl_add_u64 v[58:59], s[60:61], 0, v[72:73]
	v_lshl_add_u64 v[58:59], v[58:59], 0, s[2:3]
	v_lshl_add_u64 v[58:59], v[58:59], 0, v[0:1]
	global_store_dwordx2 v[58:59], v[62:63], off
	s_waitcnt vmcnt(27)
; __device__ __forceinline__ unsigned cvt_pk_bf16(float lo, float hi) { unsigned r; asm volatile("v_cvt_pk_bf16_f32 %0, %1, %2" : "=v"(r) : "v"(lo), "v"(hi)); return r; }
;     __device__ __forceinline__ void operator()(const Acc& acc, const Unit& u, int wr, int wc, int fr, int fq) const {
;     ...
;         for (int idx = 0; idx < 8; ++idx) { const int ai = idx >> 2, m = idx & 3, row = row0 + ai * 128 + m * 16;
; #pragma unroll
;             for (int bj = 0; bj < 2; ++bj) { const int col = bj * 32 + colb, tl = col >> 4;
;                 const u32x4 uu = urow[idx][bj];
;                 const f32x4 a = acc[ai][bj][m][0], b = acc[ai][bj][m][1];
;                 f32x2 y0 = (f32x2){a[0], a[1]} + (f32x2){d0[0], d0[1]} * (f32x2){bf2f(uu.x & 0xffffu), bf2f(uu.x >> 16)}, y1 = (f32x2){a[2], a[3]} + (f32x2){d0[2], d0[3]} * (f32x2){bf2f(uu.y & 0xffffu), bf2f(uu.y >> 16)};
;                 f32x2 y2 = (f32x2){b[0], b[1]} + (f32x2){d1[0], d1[1]} * (f32x2){bf2f(uu.z & 0xffffu), bf2f(uu.z >> 16)}, y3 = (f32x2){b[2], b[3]} + (f32x2){d1[2], d1[3]} * (f32x2){bf2f(uu.w & 0xffffu), bf2f(uu.w >> 16)};
;                 y0 = gelu_tanh2(y0); y1 = gelu_tanh2(y1); y2 = gelu_tanh2(y2); y3 = gelu_tanh2(y3);
;                 u32x4 w; w.x = cvt_pk_bf16(y0.x, y0.y); w.y = cvt_pk_bf16(y1.x, y1.y); w.z = cvt_pk_bf16(y2.x, y2.y); w.w = cvt_pk_bf16(y3.x, y3.y);
;                 *(u32x4*)(yg + (size_t)(row * 16 + tl) * DS + g * 16 + h0) = w;
;                 y0 = y0 * F8_SY; y1 = y1 * F8_SY; y2 = y2 * F8_SY; y3 = y3 * F8_SY;
;                 u32x2 w8; w8.x = pk4_fp8(y0.x, y0.y, y1.x, y1.y); w8.y = pk4_fp8(y2.x, y2.y, y3.x, y3.y);
;                 *(u32x2*)(yg8 + (size_t)(row * 16 + tl) * DS + g * 16 + h0) = w8; }
	v_lshlrev_b32_e32 v58, 16, v54
	v_and_b32_e32 v59, 0xffff0000, v54
	v_lshlrev_b32_e32 v54, 16, v55
	v_and_b32_e32 v55, 0xffff0000, v55
	v_pk_fma_f32 v[48:49], v[16:17], v[54:55], v[48:49]
	v_lshlrev_b32_e32 v54, 16, v56
	v_and_b32_e32 v55, 0xffff0000, v56
	v_pk_fma_f32 v[46:47], v[14:15], v[58:59], v[46:47]
	v_pk_fma_f32 v[42:43], v[10:11], v[54:55], v[42:43]
	v_lshlrev_b32_e32 v54, 16, v57
	v_and_b32_e32 v55, 0xffff0000, v57
	v_pk_fma_f32 v[44:45], v[12:13], v[54:55], v[44:45]
	v_pk_mul_f32 v[54:55], v[46:47], v[46:47]
	v_pk_mul_f32 v[58:59], v[42:43], v[42:43]
	v_pk_fma_f32 v[54:55], v[54:55], s[10:11], v[188:189] op_sel_hi:[1,0,0] neg_lo:[1,0,0] neg_hi:[1,0,0]
	v_pk_fma_f32 v[58:59], v[58:59], s[10:11], v[188:189] op_sel_hi:[1,0,0] neg_lo:[1,0,0] neg_hi:[1,0,0]
	v_pk_mul_f32 v[54:55], v[46:47], v[54:55]
	v_pk_mul_f32 v[56:57], v[48:49], v[48:49]
	v_pk_mul_f32 v[58:59], v[42:43], v[58:59]
	v_pk_mul_f32 v[60:61], v[44:45], v[44:45]
	v_exp_f32_e32 v54, v54
	v_exp_f32_e32 v55, v55
	v_pk_fma_f32 v[56:57], v[56:57], s[10:11], v[188:189] op_sel_hi:[1,0,0] neg_lo:[1,0,0] neg_hi:[1,0,0]
	v_exp_f32_e32 v58, v58
	v_exp_f32_e32 v59, v59
	v_pk_fma_f32 v[60:61], v[60:61], s[10:11], v[188:189] op_sel_hi:[1,0,0] neg_lo:[1,0,0] neg_hi:[1,0,0]
	v_pk_mul_f32 v[56:57], v[48:49], v[56:57]
	v_pk_mul_f32 v[60:61], v[44:45], v[60:61]
	v_exp_f32_e32 v56, v56
	v_exp_f32_e32 v57, v57
	v_exp_f32_e32 v60, v60
	v_exp_f32_e32 v61, v61
	v_pk_add_f32 v[54:55], v[54:55], 1.0 op_sel_hi:[1,0]
	v_pk_add_f32 v[58:59], v[58:59], 1.0 op_sel_hi:[1,0]
	v_rcp_f32_e32 v54, v54
	v_rcp_f32_e32 v55, v55
	v_rcp_f32_e32 v58, v58
	v_rcp_f32_e32 v59, v59
	v_pk_add_f32 v[56:57], v[56:57], 1.0 op_sel_hi:[1,0]
	v_pk_add_f32 v[60:61], v[60:61], 1.0 op_sel_hi:[1,0]
	v_rcp_f32_e32 v56, v56
	v_rcp_f32_e32 v57, v57
	v_rcp_f32_e32 v60, v60
	v_rcp_f32_e32 v61, v61
	v_add_u32_e32 v62, 0xa00, v193
	v_pk_mul_f32 v[46:47], v[46:47], v[54:55]
	v_pk_mul_f32 v[54:55], v[42:43], v[58:59]
	v_add_u32_e32 v58, v62, v115
	v_ashrrev_i32_e32 v59, 31, v58
	v_pk_mul_f32 v[48:49], v[48:49], v[56:57]
	v_pk_mul_f32 v[56:57], v[44:45], v[60:61]
	v_lshlrev_b64 v[60:61], 11, v[58:59]
	v_lshlrev_b64 v[58:59], 12, v[58:59]
	v_lshl_add_u64 v[58:59], s[14:15], 0, v[58:59]
	v_lshl_add_u64 v[58:59], v[58:59], 0, s[36:37]
	v_cvt_pk_bf16_f32 v42, v46, v47
	v_cvt_pk_bf16_f32 v43, v48, v49
	v_cvt_pk_bf16_f32 v44, v54, v55
	v_cvt_pk_bf16_f32 v45, v56, v57
	v_lshl_add_u64 v[58:59], v[58:59], 0, v[190:191]
	global_store_dwordx4 v[58:59], v[42:45], off
	s_nop 1
	v_pk_mul_f32 v[42:43], v[46:47], s[12:13] op_sel_hi:[1,0]
	v_pk_mul_f32 v[44:45], v[54:55], s[12:13] op_sel_hi:[1,0]
	v_mov_b32_e32 v46, v1
	v_mov_b32_e32 v47, v1
	v_cvt_pk_fp8_f32 v46, v42, v43
	v_cvt_pk_fp8_f32 v47, v44, v45
	v_pk_mul_f32 v[42:43], v[48:49], s[12:13] op_sel_hi:[1,0]
	v_pk_mul_f32 v[44:45], v[56:57], s[12:13] op_sel_hi:[1,0]
	v_cvt_pk_fp8_f32 v46, v42, v43 op_sel:[0,0,1]
	v_cvt_pk_fp8_f32 v47, v44, v45 op_sel:[0,0,1]
	v_lshl_add_u64 v[42:43], s[60:61], 0, v[60:61]
	v_lshl_add_u64 v[42:43], v[42:43], 0, s[2:3]
	v_lshl_add_u64 v[42:43], v[42:43], 0, v[0:1]
	global_store_dwordx2 v[42:43], v[46:47], off
	s_waitcnt vmcnt(28)
	v_lshlrev_b32_e32 v42, 16, v50
	v_and_b32_e32 v43, 0xffff0000, v50
	v_pk_fma_f32 v[38:39], v[14:15], v[42:43], v[38:39]
	v_lshlrev_b32_e32 v42, 16, v51
	v_and_b32_e32 v43, 0xffff0000, v51
	v_pk_fma_f32 v[40:41], v[16:17], v[42:43], v[40:41]
	v_lshlrev_b32_e32 v42, 16, v52
	v_and_b32_e32 v43, 0xffff0000, v52
	v_pk_fma_f32 v[34:35], v[10:11], v[42:43], v[34:35]
	v_lshlrev_b32_e32 v42, 16, v53
	v_and_b32_e32 v43, 0xffff0000, v53
	v_pk_fma_f32 v[36:37], v[12:13], v[42:43], v[36:37]
	v_pk_mul_f32 v[42:43], v[38:39], v[38:39]
	v_pk_mul_f32 v[46:47], v[34:35], v[34:35]
	v_pk_fma_f32 v[42:43], v[42:43], s[10:11], v[188:189] op_sel_hi:[1,0,0] neg_lo:[1,0,0] neg_hi:[1,0,0]
	v_pk_fma_f32 v[46:47], v[46:47], s[10:11], v[188:189] op_sel_hi:[1,0,0] neg_lo:[1,0,0] neg_hi:[1,0,0]
	v_pk_mul_f32 v[42:43], v[38:39], v[42:43]
	v_pk_mul_f32 v[44:45], v[40:41], v[40:41]
	v_pk_mul_f32 v[46:47], v[34:35], v[46:47]
	v_pk_mul_f32 v[48:49], v[36:37], v[36:37]
	v_exp_f32_e32 v42, v42
	v_exp_f32_e32 v43, v43
	v_pk_fma_f32 v[44:45], v[44:45], s[10:11], v[188:189] op_sel_hi:[1,0,0] neg_lo:[1,0,0] neg_hi:[1,0,0]
	v_exp_f32_e32 v46, v46
	v_exp_f32_e32 v47, v47
	v_pk_fma_f32 v[48:49], v[48:49], s[10:11], v[188:189] op_sel_hi:[1,0,0] neg_lo:[1,0,0] neg_hi:[1,0,0]
	v_pk_mul_f32 v[44:45], v[40:41], v[44:45]
	v_pk_mul_f32 v[48:49], v[36:37], v[48:49]
	v_exp_f32_e32 v44, v44
	v_exp_f32_e32 v45, v45
	v_exp_f32_e32 v48, v48
	v_exp_f32_e32 v49, v49
	v_pk_add_f32 v[42:43], v[42:43], 1.0 op_sel_hi:[1,0]
	v_pk_add_f32 v[46:47], v[46:47], 1.0 op_sel_hi:[1,0]
	v_rcp_f32_e32 v42, v42
	v_rcp_f32_e32 v43, v43
	v_rcp_f32_e32 v46, v46
	v_rcp_f32_e32 v47, v47
	v_pk_add_f32 v[44:45], v[44:45], 1.0 op_sel_hi:[1,0]
	v_pk_add_f32 v[48:49], v[48:49], 1.0 op_sel_hi:[1,0]
	v_rcp_f32_e32 v44, v44
	v_rcp_f32_e32 v45, v45
	v_rcp_f32_e32 v48, v48
	v_rcp_f32_e32 v49, v49
	v_pk_mul_f32 v[38:39], v[38:39], v[42:43]
	v_pk_mul_f32 v[42:43], v[34:35], v[46:47]
	v_add_u32_e32 v46, v192, v62
	v_ashrrev_i32_e32 v47, 31, v46
	v_pk_mul_f32 v[40:41], v[40:41], v[44:45]
	v_pk_mul_f32 v[44:45], v[36:37], v[48:49]
	v_lshlrev_b64 v[48:49], 11, v[46:47]
	v_lshlrev_b64 v[46:47], 12, v[46:47]
	v_lshl_add_u64 v[46:47], s[14:15], 0, v[46:47]
	v_lshl_add_u64 v[46:47], v[46:47], 0, s[36:37]
	v_cvt_pk_bf16_f32 v34, v38, v39
	v_cvt_pk_bf16_f32 v35, v40, v41
	v_cvt_pk_bf16_f32 v36, v42, v43
	v_cvt_pk_bf16_f32 v37, v44, v45
	v_lshl_add_u64 v[46:47], v[46:47], 0, v[190:191]
	global_store_dwordx4 v[46:47], v[34:37], off
	s_nop 1
	v_pk_mul_f32 v[34:35], v[38:39], s[12:13] op_sel_hi:[1,0]
	v_pk_mul_f32 v[36:37], v[42:43], s[12:13] op_sel_hi:[1,0]
	v_mov_b32_e32 v38, v1
	v_mov_b32_e32 v39, v1
	v_cvt_pk_fp8_f32 v38, v34, v35
	v_cvt_pk_fp8_f32 v39, v36, v37
	v_pk_mul_f32 v[34:35], v[40:41], s[12:13] op_sel_hi:[1,0]
	v_pk_mul_f32 v[36:37], v[44:45], s[12:13] op_sel_hi:[1,0]
	v_cvt_pk_fp8_f32 v38, v34, v35 op_sel:[0,0,1]
	v_cvt_pk_fp8_f32 v39, v36, v37 op_sel:[0,0,1]
	v_lshl_add_u64 v[34:35], s[60:61], 0, v[48:49]
	v_lshl_add_u64 v[34:35], v[34:35], 0, s[2:3]
	v_lshl_add_u64 v[34:35], v[34:35], 0, v[0:1]
	global_store_dwordx2 v[34:35], v[38:39], off
	s_waitcnt vmcnt(29)
; __device__ __forceinline__ unsigned cvt_pk_bf16(float lo, float hi) { unsigned r; asm volatile("v_cvt_pk_bf16_f32 %0, %1, %2" : "=v"(r) : "v"(lo), "v"(hi)); return r; }
; #define PG8_WAIT_V(n) asm volatile("s_waitcnt vmcnt(" #n ")" ::: "memory")
; #define PG8_BAR __builtin_amdgcn_s_barrier()
; template <class Epi, class Sched, bool ALIGN_EPI, bool SP2>
; __device__ __forceinline__ void gemm_phase(LAS unsigned char* lds, const Gemm g, const Sched& S, const Epi& E, int tid_in) {
;     ...
;     PG8_WAIT_V(0);
;     if constexpr (!ALIGN_EPI) { if (wr == 0) PG8_BAR; }
;     PG8_BAR;
;     __device__ __forceinline__ void operator()(const Acc& acc, const Unit& u, int wr, int wc, int fr, int fq) const {
;     ...
;         for (int idx = 0; idx < 8; ++idx) { const int ai = idx >> 2, m = idx & 3, row = row0 + ai * 128 + m * 16;
; #pragma unroll
;             for (int bj = 0; bj < 2; ++bj) { const int col = bj * 32 + colb, tl = col >> 4;
;                 const u32x4 uu = urow[idx][bj];
;                 const f32x4 a = acc[ai][bj][m][0], b = acc[ai][bj][m][1];
;                 f32x2 y0 = (f32x2){a[0], a[1]} + (f32x2){d0[0], d0[1]} * (f32x2){bf2f(uu.x & 0xffffu), bf2f(uu.x >> 16)}, y1 = (f32x2){a[2], a[3]} + (f32x2){d0[2], d0[3]} * (f32x2){bf2f(uu.y & 0xffffu), bf2f(uu.y >> 16)};
;                 f32x2 y2 = (f32x2){b[0], b[1]} + (f32x2){d1[0], d1[1]} * (f32x2){bf2f(uu.z & 0xffffu), bf2f(uu.z >> 16)}, y3 = (f32x2){b[2], b[3]} + (f32x2){d1[2], d1[3]} * (f32x2){bf2f(uu.w & 0xffffu), bf2f(uu.w >> 16)};
;                 y0 = gelu_tanh2(y0); y1 = gelu_tanh2(y1); y2 = gelu_tanh2(y2); y3 = gelu_tanh2(y3);
;                 u32x4 w; w.x = cvt_pk_bf16(y0.x, y0.y); w.y = cvt_pk_bf16(y1.x, y1.y); w.z = cvt_pk_bf16(y2.x, y2.y); w.w = cvt_pk_bf16(y3.x, y3.y);
;                 *(u32x4*)(yg + (size_t)(row * 16 + tl) * DS + g * 16 + h0) = w;
;                 y0 = y0 * F8_SY; y1 = y1 * F8_SY; y2 = y2 * F8_SY; y3 = y3 * F8_SY;
;                 u32x2 w8; w8.x = pk4_fp8(y0.x, y0.y, y1.x, y1.y); w8.y = pk4_fp8(y2.x, y2.y, y3.x, y3.y);
;                 *(u32x2*)(yg8 + (size_t)(row * 16 + tl) * DS + g * 16 + h0) = w8; }
	v_lshlrev_b32_e32 v34, 16, v30
	v_and_b32_e32 v35, 0xffff0000, v30
	v_lshlrev_b32_e32 v30, 16, v31
	v_and_b32_e32 v31, 0xffff0000, v31
	v_pk_fma_f32 v[24:25], v[16:17], v[30:31], v[24:25]
	v_lshlrev_b32_e32 v30, 16, v32
	v_and_b32_e32 v31, 0xffff0000, v32
	v_pk_fma_f32 v[22:23], v[14:15], v[34:35], v[22:23]
	v_pk_fma_f32 v[18:19], v[10:11], v[30:31], v[18:19]
	v_lshlrev_b32_e32 v30, 16, v33
	v_and_b32_e32 v31, 0xffff0000, v33
	v_pk_fma_f32 v[20:21], v[12:13], v[30:31], v[20:21]
	v_pk_mul_f32 v[30:31], v[22:23], v[22:23]
	v_pk_mul_f32 v[34:35], v[18:19], v[18:19]
	v_pk_fma_f32 v[30:31], v[30:31], s[10:11], v[188:189] op_sel_hi:[1,0,0] neg_lo:[1,0,0] neg_hi:[1,0,0]
	v_pk_fma_f32 v[34:35], v[34:35], s[10:11], v[188:189] op_sel_hi:[1,0,0] neg_lo:[1,0,0] neg_hi:[1,0,0]
	v_pk_mul_f32 v[30:31], v[22:23], v[30:31]
	v_pk_mul_f32 v[32:33], v[24:25], v[24:25]
	v_pk_mul_f32 v[34:35], v[18:19], v[34:35]
	v_pk_mul_f32 v[36:37], v[20:21], v[20:21]
	v_exp_f32_e32 v30, v30
	v_exp_f32_e32 v31, v31
	v_pk_fma_f32 v[32:33], v[32:33], s[10:11], v[188:189] op_sel_hi:[1,0,0] neg_lo:[1,0,0] neg_hi:[1,0,0]
	v_exp_f32_e32 v34, v34
	v_exp_f32_e32 v35, v35
	v_pk_fma_f32 v[36:37], v[36:37], s[10:11], v[188:189] op_sel_hi:[1,0,0] neg_lo:[1,0,0] neg_hi:[1,0,0]
	v_pk_mul_f32 v[32:33], v[24:25], v[32:33]
	v_pk_mul_f32 v[36:37], v[20:21], v[36:37]
	v_exp_f32_e32 v32, v32
	v_exp_f32_e32 v33, v33
	v_exp_f32_e32 v36, v36
	v_exp_f32_e32 v37, v37
	v_pk_add_f32 v[30:31], v[30:31], 1.0 op_sel_hi:[1,0]
	v_pk_add_f32 v[34:35], v[34:35], 1.0 op_sel_hi:[1,0]
	v_rcp_f32_e32 v30, v30
	v_rcp_f32_e32 v31, v31
	v_rcp_f32_e32 v34, v34
	v_rcp_f32_e32 v35, v35
	v_pk_add_f32 v[32:33], v[32:33], 1.0 op_sel_hi:[1,0]
	v_pk_add_f32 v[36:37], v[36:37], 1.0 op_sel_hi:[1,0]
	v_rcp_f32_e32 v32, v32
	v_rcp_f32_e32 v33, v33
	v_rcp_f32_e32 v36, v36
	v_rcp_f32_e32 v37, v37
	v_add_u32_e32 v38, 0xb00, v193
	v_pk_mul_f32 v[22:23], v[22:23], v[30:31]
	v_pk_mul_f32 v[30:31], v[18:19], v[34:35]
	v_add_u32_e32 v34, v38, v115
	v_ashrrev_i32_e32 v35, 31, v34
	v_pk_mul_f32 v[24:25], v[24:25], v[32:33]
	v_pk_mul_f32 v[32:33], v[20:21], v[36:37]
	v_lshlrev_b64 v[36:37], 11, v[34:35]
	v_lshlrev_b64 v[34:35], 12, v[34:35]
	v_lshl_add_u64 v[34:35], s[14:15], 0, v[34:35]
	v_lshl_add_u64 v[34:35], v[34:35], 0, s[36:37]
	v_cvt_pk_bf16_f32 v18, v22, v23
	v_cvt_pk_bf16_f32 v19, v24, v25
	v_cvt_pk_bf16_f32 v20, v30, v31
	v_cvt_pk_bf16_f32 v21, v32, v33
	v_lshl_add_u64 v[34:35], v[34:35], 0, v[190:191]
	global_store_dwordx4 v[34:35], v[18:21], off
	s_nop 1
	v_pk_mul_f32 v[18:19], v[22:23], s[12:13] op_sel_hi:[1,0]
	v_pk_mul_f32 v[20:21], v[30:31], s[12:13] op_sel_hi:[1,0]
	v_mov_b32_e32 v22, v1
	v_mov_b32_e32 v23, v1
	v_cvt_pk_fp8_f32 v22, v18, v19
	v_cvt_pk_fp8_f32 v23, v20, v21
	v_pk_mul_f32 v[18:19], v[24:25], s[12:13] op_sel_hi:[1,0]
	v_pk_mul_f32 v[20:21], v[32:33], s[12:13] op_sel_hi:[1,0]
	v_cvt_pk_fp8_f32 v22, v18, v19 op_sel:[0,0,1]
	v_cvt_pk_fp8_f32 v23, v20, v21 op_sel:[0,0,1]
	v_lshl_add_u64 v[18:19], s[60:61], 0, v[36:37]
	v_lshl_add_u64 v[18:19], v[18:19], 0, s[2:3]
	v_lshl_add_u64 v[18:19], v[18:19], 0, v[0:1]
	global_store_dwordx2 v[18:19], v[22:23], off
	s_waitcnt vmcnt(30)
	v_lshlrev_b32_e32 v18, 16, v26
	v_and_b32_e32 v19, 0xffff0000, v26
	v_pk_fma_f32 v[6:7], v[14:15], v[18:19], v[6:7]
	v_lshlrev_b32_e32 v14, 16, v27
	v_and_b32_e32 v15, 0xffff0000, v27
	v_pk_fma_f32 v[8:9], v[16:17], v[14:15], v[8:9]
	v_lshlrev_b32_e32 v14, 16, v28
	v_and_b32_e32 v15, 0xffff0000, v28
	v_pk_fma_f32 v[2:3], v[10:11], v[14:15], v[2:3]
	v_lshlrev_b32_e32 v10, 16, v29
	v_and_b32_e32 v11, 0xffff0000, v29
	v_pk_fma_f32 v[4:5], v[12:13], v[10:11], v[4:5]
	v_pk_mul_f32 v[10:11], v[6:7], v[6:7]
	v_pk_mul_f32 v[14:15], v[2:3], v[2:3]
	v_pk_fma_f32 v[10:11], v[10:11], s[10:11], v[188:189] op_sel_hi:[1,0,0] neg_lo:[1,0,0] neg_hi:[1,0,0]
	v_pk_fma_f32 v[14:15], v[14:15], s[10:11], v[188:189] op_sel_hi:[1,0,0] neg_lo:[1,0,0] neg_hi:[1,0,0]
	v_pk_mul_f32 v[10:11], v[6:7], v[10:11]
	v_pk_mul_f32 v[12:13], v[8:9], v[8:9]
	v_pk_mul_f32 v[14:15], v[2:3], v[14:15]
	v_pk_mul_f32 v[16:17], v[4:5], v[4:5]
	v_exp_f32_e32 v10, v10
	v_exp_f32_e32 v11, v11
	v_pk_fma_f32 v[12:13], v[12:13], s[10:11], v[188:189] op_sel_hi:[1,0,0] neg_lo:[1,0,0] neg_hi:[1,0,0]
	v_exp_f32_e32 v14, v14
	v_exp_f32_e32 v15, v15
	v_pk_fma_f32 v[16:17], v[16:17], s[10:11], v[188:189] op_sel_hi:[1,0,0] neg_lo:[1,0,0] neg_hi:[1,0,0]
	v_pk_mul_f32 v[12:13], v[8:9], v[12:13]
	v_pk_mul_f32 v[16:17], v[4:5], v[16:17]
	v_exp_f32_e32 v12, v12
	v_exp_f32_e32 v13, v13
	v_exp_f32_e32 v16, v16
	v_exp_f32_e32 v17, v17
	v_pk_add_f32 v[10:11], v[10:11], 1.0 op_sel_hi:[1,0]
	v_pk_add_f32 v[14:15], v[14:15], 1.0 op_sel_hi:[1,0]
	v_rcp_f32_e32 v10, v10
	v_rcp_f32_e32 v11, v11
	v_rcp_f32_e32 v14, v14
	v_rcp_f32_e32 v15, v15
	v_pk_add_f32 v[12:13], v[12:13], 1.0 op_sel_hi:[1,0]
	v_pk_add_f32 v[16:17], v[16:17], 1.0 op_sel_hi:[1,0]
	v_rcp_f32_e32 v12, v12
	v_rcp_f32_e32 v13, v13
	v_rcp_f32_e32 v16, v16
	v_rcp_f32_e32 v17, v17
	v_pk_mul_f32 v[6:7], v[6:7], v[10:11]
	v_pk_mul_f32 v[10:11], v[2:3], v[14:15]
	v_add_u32_e32 v14, v192, v38
	v_ashrrev_i32_e32 v15, 31, v14
	v_pk_mul_f32 v[8:9], v[8:9], v[12:13]
	v_pk_mul_f32 v[12:13], v[4:5], v[16:17]
	v_lshlrev_b64 v[16:17], 11, v[14:15]
	v_lshlrev_b64 v[14:15], 12, v[14:15]
	v_lshl_add_u64 v[14:15], s[14:15], 0, v[14:15]
	v_lshl_add_u64 v[14:15], v[14:15], 0, s[36:37]
	v_cvt_pk_bf16_f32 v2, v6, v7
	v_cvt_pk_bf16_f32 v3, v8, v9
	v_cvt_pk_bf16_f32 v4, v10, v11
	v_cvt_pk_bf16_f32 v5, v12, v13
	v_lshl_add_u64 v[14:15], v[14:15], 0, v[190:191]
	global_store_dwordx4 v[14:15], v[2:5], off
	s_nop 1
	v_pk_mul_f32 v[2:3], v[6:7], s[12:13] op_sel_hi:[1,0]
	v_pk_mul_f32 v[4:5], v[10:11], s[12:13] op_sel_hi:[1,0]
	v_mov_b32_e32 v6, v1
	v_mov_b32_e32 v7, v1
	v_cvt_pk_fp8_f32 v6, v2, v3
	v_cvt_pk_fp8_f32 v7, v4, v5
	v_pk_mul_f32 v[2:3], v[8:9], s[12:13] op_sel_hi:[1,0]
	v_pk_mul_f32 v[4:5], v[12:13], s[12:13] op_sel_hi:[1,0]
	v_cvt_pk_fp8_f32 v6, v2, v3 op_sel:[0,0,1]
	v_cvt_pk_fp8_f32 v7, v4, v5 op_sel:[0,0,1]
	v_lshl_add_u64 v[2:3], s[60:61], 0, v[16:17]
	v_lshl_add_u64 v[2:3], v[2:3], 0, s[2:3]
	v_lshl_add_u64 v[2:3], v[2:3], 0, v[0:1]
	global_store_dwordx2 v[2:3], v[6:7], off
	s_waitcnt vmcnt(0)
	s_cbranch_scc1 .LBB0_500
	s_barrier
	s_branch .LBB0_500
